# all-gemm-loops-prio-before-barrier-redundant-waits-removed
# baseline (speedup 1.0000x reference)
; #define PG8_STAGEA(bufoff, goff, voff) PG8_STAGEX(rsA, bufoff, goff, voff)
; #define PG8_STAGEB(bufoff, goff, voff) PG8_STAGEX(rsB, bufoff, goff, voff)
; #define PG8_LDA(dst, b, h) do { _Pragma("unroll") for (int m = 0; m < 4; ++m) _Pragma("unroll") for (int k = 0; k < 2; ++k) dst[m][k] = *(const PG8_LAS bf16x8*)(lds + PG8_SA(b, h) + aoff + m * 2048 + k * 1024); } while (0)
; #define PG8_MMA(ai, bj, At, Bt) do { __builtin_amdgcn_s_setprio(1); _Pragma("unroll") for (int m = 0; m < 4; ++m) _Pragma("unroll") for (int n = 0; n < 2; ++n) _Pragma("unroll") for (int k = 0; k < 2; ++k) \
;         acc[ai][bj][m][n] = __builtin_amdgcn_mfma_f32_16x16x32_bf16(Bt[n][k], At[m][k], acc[ai][bj][m][n], 0, 0, 0); __builtin_amdgcn_s_setprio(0); } while (0)
; #define PG8_WAIT_V(n) asm volatile("s_waitcnt vmcnt(" #n ")" ::: "memory")
; #define PG8_WAIT_L(n) asm volatile("s_waitcnt lgkmcnt(" #n ")" ::: "memory")
; #define PG8_BAR __builtin_amdgcn_s_barrier()
; #define PG8_SCHED __builtin_amdgcn_sched_barrier(0)
; template <class Epi, class Sched, bool ALIGN_EPI = false, bool SP2 = false>
; __device__ __forceinline__ void gemm_phase(PG8_LAS unsigned char* lds, const Gemm g, const Sched& S, const Epi& E) {
;     ...
;         const size_t nA = has_next ? (size_t)nxt.pm * tstep : cA; const size_t nB = has_next ? (size_t)nxt.pn * tstep : cB;
;         for (int t = 0; t < nt; t += 2) {
;             const bool last = (t == nt - 2);
;             if constexpr (Epi::MIDK) { if (t == (nt >> 1)) E.midk(acc, wr, fr, lds); }
;             const size_t a1 = cA + (size_t)(t + 1) * kstep;
;             const size_t a2 = last ? nA : cA + (size_t)(t + 2) * kstep; const size_t b2 = last ? nB : cB + (size_t)(t + 2) * kstep;
;     ...
;             PG8_WAIT_V(8); PG8_WAIT_L(0); PG8_BAR; PG8_MMA(0, 0, At, B0); PG8_MMA(0, 1, At, B1); PG8_BAR; PG8_SCHED;
;             PG8_LDA(At, 0, 1); PG8_STAGEB(PG8_SB(0, 0), b2, voffB); PG8_STAGEB(PG8_SB(0, 1), b2 + hstep, voffB); PG8_STAGEA(PG8_SA(0, 0), a2, voffA);
;             PG8_WAIT_V(8); PG8_WAIT_L(0); PG8_BAR; PG8_MMA(1, 0, At, B0); PG8_MMA(1, 1, At, B1); PG8_BAR; PG8_SCHED;
.LBB0_182:
	s_ashr_i32 s95, s94, 31
	s_lshl_b64 s[92:93], s[94:95], 20
	s_and_b64 s[66:67], s[76:77], exec
	s_cselect_b32 s7, s92, s46
	s_ashr_i32 s83, s82, 31
	s_waitcnt vmcnt(8)
	s_lshl_b64 s[66:67], s[82:83], 20
	s_waitcnt lgkmcnt(0)
	s_and_b64 s[74:75], s[76:77], exec
	s_cselect_b32 s47, s66, s8
	s_setprio 1
	s_barrier
	v_mfma_f32_16x16x32_bf16 v[126:129], v[146:149], v[186:189], v[126:129]
	v_mfma_f32_16x16x32_bf16 v[122:125], v[154:157], v[186:189], v[122:125]
	v_mfma_f32_16x16x32_bf16 v[118:121], v[146:149], v[178:181], v[118:121]
	v_mfma_f32_16x16x32_bf16 v[114:117], v[154:157], v[178:181], v[114:117]
	v_mfma_f32_16x16x32_bf16 v[110:113], v[146:149], v[170:173], v[110:113]
	v_mfma_f32_16x16x32_bf16 v[106:109], v[154:157], v[170:173], v[106:109]
	v_mfma_f32_16x16x32_bf16 v[102:105], v[146:149], v[162:165], v[102:105]
	v_mfma_f32_16x16x32_bf16 v[98:101], v[154:157], v[162:165], v[98:101]
	v_mfma_f32_16x16x32_bf16 v[126:129], v[150:153], v[190:193], v[126:129]
	v_mfma_f32_16x16x32_bf16 v[122:125], v[158:161], v[190:193], v[122:125]
	v_mfma_f32_16x16x32_bf16 v[118:121], v[150:153], v[182:185], v[118:121]
	v_mfma_f32_16x16x32_bf16 v[114:117], v[158:161], v[182:185], v[114:117]
	v_mfma_f32_16x16x32_bf16 v[110:113], v[150:153], v[174:177], v[110:113]
	v_mfma_f32_16x16x32_bf16 v[106:109], v[158:161], v[174:177], v[106:109]
	v_mfma_f32_16x16x32_bf16 v[102:105], v[150:153], v[166:169], v[102:105]
	v_mfma_f32_16x16x32_bf16 v[98:101], v[158:161], v[166:169], v[98:101]
	v_mfma_f32_16x16x32_bf16 v[94:97], v[130:133], v[186:189], v[94:97]
	v_mfma_f32_16x16x32_bf16 v[90:93], v[138:141], v[186:189], v[90:93]
	v_mfma_f32_16x16x32_bf16 v[86:89], v[130:133], v[178:181], v[86:89]
	v_mfma_f32_16x16x32_bf16 v[82:85], v[138:141], v[178:181], v[82:85]
	v_mfma_f32_16x16x32_bf16 v[78:81], v[130:133], v[170:173], v[78:81]
	v_mfma_f32_16x16x32_bf16 v[74:77], v[138:141], v[170:173], v[74:77]
	v_mfma_f32_16x16x32_bf16 v[70:73], v[130:133], v[162:165], v[70:73]
	v_mfma_f32_16x16x32_bf16 v[66:69], v[138:141], v[162:165], v[66:69]
	v_mfma_f32_16x16x32_bf16 v[94:97], v[134:137], v[190:193], v[94:97]
	v_mfma_f32_16x16x32_bf16 v[90:93], v[142:145], v[190:193], v[90:93]
	v_mfma_f32_16x16x32_bf16 v[86:89], v[134:137], v[182:185], v[86:89]
	v_mfma_f32_16x16x32_bf16 v[82:85], v[142:145], v[182:185], v[82:85]
	v_mfma_f32_16x16x32_bf16 v[78:81], v[134:137], v[174:177], v[78:81]
	v_mfma_f32_16x16x32_bf16 v[74:77], v[142:145], v[174:177], v[74:77]
	v_mfma_f32_16x16x32_bf16 v[70:73], v[134:137], v[166:169], v[70:73]
	v_mfma_f32_16x16x32_bf16 v[66:69], v[142:145], v[166:169], v[66:69]
	s_setprio 0
	s_barrier
	s_mov_b32 m0, s35
	s_or_b32 s9, s8, 0x100
	s_mov_b32 s74, s62
	s_mov_b32 s75, s63
	ds_read_b128 v[162:165], v207 offset:16384
	ds_read_b128 v[166:169], v207 offset:17408
	ds_read_b128 v[170:173], v207 offset:18432
	ds_read_b128 v[174:177], v207 offset:19456
	ds_read_b128 v[178:181], v207 offset:20480
	ds_read_b128 v[182:185], v207 offset:21504
	ds_read_b128 v[186:189], v207 offset:22528
	ds_read_b128 v[190:193], v207 offset:23552
	buffer_load_dwordx4 v195, s[72:75], s9 offen lds
	s_mov_b32 m0, s39
	s_nop 0
	buffer_load_dwordx4 v203, s[72:75], s9 offen lds
	s_or_b32 s9, s8, 0x80100
	s_mov_b32 m0, s79
	s_nop 0
	buffer_load_dwordx4 v195, s[72:75], s9 offen lds
	s_mov_b32 m0, s85
	s_nop 0
	buffer_load_dwordx4 v203, s[72:75], s9 offen lds
	s_or_b32 s9, s46, 0x100
	s_mov_b32 m0, s96
	s_nop 0
	buffer_load_dwordx4 v1, s[60:63], s9 offen lds
	s_mov_b32 m0, s91
	s_nop 0
	buffer_load_dwordx4 v202, s[60:63], s9 offen lds
	s_waitcnt vmcnt(8)
	s_waitcnt lgkmcnt(0)
	s_setprio 1
	s_barrier
	v_mfma_f32_16x16x32_bf16 v[62:65], v[146:149], v[162:165], v[62:65]
	v_mfma_f32_16x16x32_bf16 v[58:61], v[154:157], v[162:165], v[58:61]
	v_mfma_f32_16x16x32_bf16 v[54:57], v[146:149], v[170:173], v[54:57]
	v_mfma_f32_16x16x32_bf16 v[50:53], v[154:157], v[170:173], v[50:53]
	v_mfma_f32_16x16x32_bf16 v[46:49], v[146:149], v[178:181], v[46:49]
	v_mfma_f32_16x16x32_bf16 v[42:45], v[154:157], v[178:181], v[42:45]
	v_mfma_f32_16x16x32_bf16 v[38:41], v[146:149], v[186:189], v[38:41]
	v_mfma_f32_16x16x32_bf16 v[34:37], v[154:157], v[186:189], v[34:37]
	v_mfma_f32_16x16x32_bf16 v[62:65], v[150:153], v[166:169], v[62:65]
	v_mfma_f32_16x16x32_bf16 v[58:61], v[158:161], v[166:169], v[58:61]
	v_mfma_f32_16x16x32_bf16 v[54:57], v[150:153], v[174:177], v[54:57]
	v_mfma_f32_16x16x32_bf16 v[50:53], v[158:161], v[174:177], v[50:53]
	v_mfma_f32_16x16x32_bf16 v[46:49], v[150:153], v[182:185], v[46:49]
	v_mfma_f32_16x16x32_bf16 v[42:45], v[158:161], v[182:185], v[42:45]
	v_mfma_f32_16x16x32_bf16 v[38:41], v[150:153], v[190:193], v[38:41]
	v_mfma_f32_16x16x32_bf16 v[34:37], v[158:161], v[190:193], v[34:37]
	v_mfma_f32_16x16x32_bf16 v[30:33], v[130:133], v[162:165], v[30:33]
	v_mfma_f32_16x16x32_bf16 v[26:29], v[138:141], v[162:165], v[26:29]
	v_mfma_f32_16x16x32_bf16 v[22:25], v[130:133], v[170:173], v[22:25]
	v_mfma_f32_16x16x32_bf16 v[18:21], v[138:141], v[170:173], v[18:21]
	v_mfma_f32_16x16x32_bf16 v[14:17], v[130:133], v[178:181], v[14:17]
	v_mfma_f32_16x16x32_bf16 v[10:13], v[138:141], v[178:181], v[10:13]
	v_mfma_f32_16x16x32_bf16 v[6:9], v[130:133], v[186:189], v[6:9]
	v_mfma_f32_16x16x32_bf16 v[2:5], v[138:141], v[186:189], v[2:5]
	v_mfma_f32_16x16x32_bf16 v[30:33], v[134:137], v[166:169], v[30:33]
	v_mfma_f32_16x16x32_bf16 v[26:29], v[142:145], v[166:169], v[26:29]
	v_mfma_f32_16x16x32_bf16 v[22:25], v[134:137], v[174:177], v[22:25]
	v_mfma_f32_16x16x32_bf16 v[18:21], v[142:145], v[174:177], v[18:21]
	v_mfma_f32_16x16x32_bf16 v[14:17], v[134:137], v[182:185], v[14:17]
	v_mfma_f32_16x16x32_bf16 v[10:13], v[142:145], v[182:185], v[10:13]
	v_mfma_f32_16x16x32_bf16 v[6:9], v[134:137], v[190:193], v[6:9]
	v_mfma_f32_16x16x32_bf16 v[2:5], v[142:145], v[190:193], v[2:5]
	s_setprio 0
	s_barrier
; #define PG8_STAGEA(bufoff, goff, voff) PG8_STAGEX(rsA, bufoff, goff, voff)
; #define PG8_STAGEB(bufoff, goff, voff) PG8_STAGEX(rsB, bufoff, goff, voff)
; #define PG8_LDA(dst, b, h) do { _Pragma("unroll") for (int m = 0; m < 4; ++m) _Pragma("unroll") for (int k = 0; k < 2; ++k) dst[m][k] = *(const PG8_LAS bf16x8*)(lds + PG8_SA(b, h) + aoff + m * 2048 + k * 1024); } while (0)
; #define PG8_LDB(dst, b, h) do { _Pragma("unroll") for (int n = 0; n < 2; ++n) _Pragma("unroll") for (int k = 0; k < 2; ++k) dst[n][k] = *(const PG8_LAS bf16x8*)(lds + PG8_SB(b, h) + boff + n * 2048 + k * 1024); } while (0)
; #define PG8_MMA(ai, bj, At, Bt) do { __builtin_amdgcn_s_setprio(1); _Pragma("unroll") for (int m = 0; m < 4; ++m) _Pragma("unroll") for (int n = 0; n < 2; ++n) _Pragma("unroll") for (int k = 0; k < 2; ++k) \
;         acc[ai][bj][m][n] = __builtin_amdgcn_mfma_f32_16x16x32_bf16(Bt[n][k], At[m][k], acc[ai][bj][m][n], 0, 0, 0); __builtin_amdgcn_s_setprio(0); } while (0)
; #define PG8_WAIT_V(n) asm volatile("s_waitcnt vmcnt(" #n ")" ::: "memory")
; #define PG8_WAIT_L(n) asm volatile("s_waitcnt lgkmcnt(" #n ")" ::: "memory")
; #define PG8_BAR __builtin_amdgcn_s_barrier()
; #define PG8_SCHED __builtin_amdgcn_sched_barrier(0)
; template <class Epi, class Sched, bool ALIGN_EPI = false, bool SP2 = false>
; __device__ __forceinline__ void gemm_phase(PG8_LAS unsigned char* lds, const Gemm g, const Sched& S, const Epi& E) {
;     ...
;             PG8_LDB(B0, 1, 0); PG8_LDB(B1, 1, 1); PG8_SCHED; PG8_LDA(At, 1, 0); PG8_STAGEA(PG8_SA(0, 1), a2 + hstep, voffA);
;             PG8_WAIT_V(8); PG8_WAIT_L(0); PG8_BAR; PG8_MMA(0, 0, At, B0); PG8_MMA(0, 1, At, B1); PG8_BAR; PG8_SCHED;
;             PG8_LDA(At, 1, 1); PG8_STAGEB(PG8_SB(1, 0), b3, voffB); PG8_STAGEB(PG8_SB(1, 1), b3 + hstep, voffB); PG8_STAGEA(PG8_SA(1, 0), a3, voffA);
;             PG8_WAIT_V(8); PG8_WAIT_L(0); PG8_BAR; PG8_MMA(1, 0, At, B0); PG8_MMA(1, 1, At, B1); PG8_BAR; PG8_SCHED;
	v_add_u32_e32 v130, 0x18000, v206
	v_add_u32_e32 v131, 0x1c000, v206
	ds_read_b128 v[132:135], v130
	ds_read_b128 v[136:139], v130 offset:1024
	ds_read_b128 v[140:143], v130 offset:2048
	ds_read_b128 v[144:147], v130 offset:3072
	ds_read_b128 v[148:151], v131
	ds_read_b128 v[152:155], v131 offset:1024
	ds_read_b128 v[156:159], v131 offset:2048
	ds_read_b128 v[160:163], v131 offset:3072
	s_or_b32 s9, s46, 0x80100
	s_mov_b32 m0, s89
	ds_read_b128 v[164:167], v207 offset:32768
	ds_read_b128 v[168:171], v207 offset:33792
	ds_read_b128 v[172:175], v207 offset:34816
	ds_read_b128 v[176:179], v207 offset:35840
	ds_read_b128 v[180:183], v207 offset:36864
	ds_read_b128 v[184:187], v207 offset:37888
	ds_read_b128 v[188:191], v207 offset:38912
	ds_read_b128 v[210:213], v207 offset:39936
	buffer_load_dwordx4 v1, s[60:63], s9 offen lds
	s_mov_b32 m0, s59
	s_nop 0
	buffer_load_dwordx4 v202, s[60:63], s9 offen lds
	s_waitcnt vmcnt(8)
	s_waitcnt lgkmcnt(0)
	s_setprio 1
	s_barrier
	v_mfma_f32_16x16x32_bf16 v[126:129], v[132:135], v[164:167], v[126:129]
	v_mfma_f32_16x16x32_bf16 v[122:125], v[140:143], v[164:167], v[122:125]
	v_mfma_f32_16x16x32_bf16 v[118:121], v[132:135], v[172:175], v[118:121]
	v_mfma_f32_16x16x32_bf16 v[114:117], v[140:143], v[172:175], v[114:117]
	v_mfma_f32_16x16x32_bf16 v[110:113], v[132:135], v[180:183], v[110:113]
	v_mfma_f32_16x16x32_bf16 v[106:109], v[140:143], v[180:183], v[106:109]
	v_mfma_f32_16x16x32_bf16 v[102:105], v[132:135], v[188:191], v[102:105]
	v_mfma_f32_16x16x32_bf16 v[98:101], v[140:143], v[188:191], v[98:101]
	v_mfma_f32_16x16x32_bf16 v[126:129], v[136:139], v[168:171], v[126:129]
	v_mfma_f32_16x16x32_bf16 v[122:125], v[144:147], v[168:171], v[122:125]
	v_mfma_f32_16x16x32_bf16 v[118:121], v[136:139], v[176:179], v[118:121]
	v_mfma_f32_16x16x32_bf16 v[114:117], v[144:147], v[176:179], v[114:117]
	v_mfma_f32_16x16x32_bf16 v[110:113], v[136:139], v[184:187], v[110:113]
	v_mfma_f32_16x16x32_bf16 v[106:109], v[144:147], v[184:187], v[106:109]
	v_mfma_f32_16x16x32_bf16 v[102:105], v[136:139], v[210:213], v[102:105]
	v_mfma_f32_16x16x32_bf16 v[98:101], v[144:147], v[210:213], v[98:101]
	v_mfma_f32_16x16x32_bf16 v[94:97], v[148:151], v[164:167], v[94:97]
	v_mfma_f32_16x16x32_bf16 v[90:93], v[156:159], v[164:167], v[90:93]
	v_mfma_f32_16x16x32_bf16 v[86:89], v[148:151], v[172:175], v[86:89]
	v_mfma_f32_16x16x32_bf16 v[82:85], v[156:159], v[172:175], v[82:85]
	v_mfma_f32_16x16x32_bf16 v[78:81], v[148:151], v[180:183], v[78:81]
	v_mfma_f32_16x16x32_bf16 v[74:77], v[156:159], v[180:183], v[74:77]
	v_mfma_f32_16x16x32_bf16 v[70:73], v[148:151], v[188:191], v[70:73]
	v_mfma_f32_16x16x32_bf16 v[66:69], v[156:159], v[188:191], v[66:69]
	v_mfma_f32_16x16x32_bf16 v[94:97], v[152:155], v[168:171], v[94:97]
	v_mfma_f32_16x16x32_bf16 v[90:93], v[160:163], v[168:171], v[90:93]
	v_mfma_f32_16x16x32_bf16 v[86:89], v[152:155], v[176:179], v[86:89]
	v_mfma_f32_16x16x32_bf16 v[82:85], v[160:163], v[176:179], v[82:85]
	v_mfma_f32_16x16x32_bf16 v[78:81], v[152:155], v[184:187], v[78:81]
	v_mfma_f32_16x16x32_bf16 v[74:77], v[160:163], v[184:187], v[74:77]
	v_mfma_f32_16x16x32_bf16 v[70:73], v[152:155], v[210:213], v[70:73]
	v_mfma_f32_16x16x32_bf16 v[66:69], v[160:163], v[210:213], v[66:69]
	s_setprio 0
	s_barrier
	s_mov_b32 m0, s58
	s_or_b32 s9, s8, 0x180
	ds_read_b128 v[164:167], v207 offset:49152
	ds_read_b128 v[168:171], v207 offset:50176
	ds_read_b128 v[172:175], v207 offset:51200
	ds_read_b128 v[176:179], v207 offset:52224
	ds_read_b128 v[180:183], v207 offset:53248
	ds_read_b128 v[184:187], v207 offset:54272
	ds_read_b128 v[188:191], v207 offset:55296
	ds_read_b128 v[210:213], v207 offset:56320
	buffer_load_dwordx4 v195, s[72:75], s9 offen lds
	s_mov_b32 m0, s2
	s_nop 0
	buffer_load_dwordx4 v203, s[72:75], s9 offen lds
	s_or_b32 s9, s8, 0x80180
	s_mov_b32 m0, s70
	s_nop 0
	buffer_load_dwordx4 v195, s[72:75], s9 offen lds
	s_mov_b32 m0, s71
	s_nop 0
	buffer_load_dwordx4 v203, s[72:75], s9 offen lds
	s_or_b32 s9, s46, 0x180
	s_mov_b32 m0, s3
	s_nop 0
	buffer_load_dwordx4 v1, s[60:63], s9 offen lds
	s_mov_b32 m0, s57
	s_nop 0
	buffer_load_dwordx4 v202, s[60:63], s9 offen lds
	s_waitcnt vmcnt(8)
	s_waitcnt lgkmcnt(0)
	s_setprio 1
	s_barrier
	v_mfma_f32_16x16x32_bf16 v[62:65], v[132:135], v[164:167], v[62:65]
	v_mfma_f32_16x16x32_bf16 v[58:61], v[140:143], v[164:167], v[58:61]
	v_mfma_f32_16x16x32_bf16 v[54:57], v[132:135], v[172:175], v[54:57]
	v_mfma_f32_16x16x32_bf16 v[50:53], v[140:143], v[172:175], v[50:53]
	v_mfma_f32_16x16x32_bf16 v[46:49], v[132:135], v[180:183], v[46:49]
	v_mfma_f32_16x16x32_bf16 v[42:45], v[140:143], v[180:183], v[42:45]
	v_mfma_f32_16x16x32_bf16 v[38:41], v[132:135], v[188:191], v[38:41]
	v_mfma_f32_16x16x32_bf16 v[34:37], v[140:143], v[188:191], v[34:37]
	v_mfma_f32_16x16x32_bf16 v[62:65], v[136:139], v[168:171], v[62:65]
	v_mfma_f32_16x16x32_bf16 v[58:61], v[144:147], v[168:171], v[58:61]
	v_mfma_f32_16x16x32_bf16 v[54:57], v[136:139], v[176:179], v[54:57]
	v_mfma_f32_16x16x32_bf16 v[50:53], v[144:147], v[176:179], v[50:53]
	v_mfma_f32_16x16x32_bf16 v[46:49], v[136:139], v[184:187], v[46:49]
	v_mfma_f32_16x16x32_bf16 v[42:45], v[144:147], v[184:187], v[42:45]
	v_mfma_f32_16x16x32_bf16 v[38:41], v[136:139], v[210:213], v[38:41]
	v_mfma_f32_16x16x32_bf16 v[34:37], v[144:147], v[210:213], v[34:37]
	v_mfma_f32_16x16x32_bf16 v[30:33], v[148:151], v[164:167], v[30:33]
	v_mfma_f32_16x16x32_bf16 v[26:29], v[156:159], v[164:167], v[26:29]
	v_mfma_f32_16x16x32_bf16 v[22:25], v[148:151], v[172:175], v[22:25]
	v_mfma_f32_16x16x32_bf16 v[18:21], v[156:159], v[172:175], v[18:21]
	v_mfma_f32_16x16x32_bf16 v[14:17], v[148:151], v[180:183], v[14:17]
	v_mfma_f32_16x16x32_bf16 v[10:13], v[156:159], v[180:183], v[10:13]
	v_mfma_f32_16x16x32_bf16 v[6:9], v[148:151], v[188:191], v[6:9]
	v_mfma_f32_16x16x32_bf16 v[2:5], v[156:159], v[188:191], v[2:5]
	v_mfma_f32_16x16x32_bf16 v[30:33], v[152:155], v[168:171], v[30:33]
	v_mfma_f32_16x16x32_bf16 v[26:29], v[160:163], v[168:171], v[26:29]
	v_mfma_f32_16x16x32_bf16 v[22:25], v[152:155], v[176:179], v[22:25]
	v_mfma_f32_16x16x32_bf16 v[18:21], v[160:163], v[176:179], v[18:21]
	v_mfma_f32_16x16x32_bf16 v[14:17], v[152:155], v[184:187], v[14:17]
	v_mfma_f32_16x16x32_bf16 v[10:13], v[160:163], v[184:187], v[10:13]
	v_mfma_f32_16x16x32_bf16 v[6:9], v[152:155], v[210:213], v[6:9]
	v_mfma_f32_16x16x32_bf16 v[2:5], v[160:163], v[210:213], v[2:5]
	s_setprio 0
	s_barrier
	s_add_u32 s46, s46, 0x200
	s_add_u32 s83, s8, 0x200
	s_mov_b32 s87, 0
	s_mov_b64 s[8:9], 0
; #define PG8_STAGEA(bufoff, goff, voff) PG8_STAGEX(rsA, bufoff, goff, voff)
; #define PG8_STAGEB(bufoff, goff, voff) PG8_STAGEX(rsB, bufoff, goff, voff)
; #define PG8_LDA(dst, b, h) do { _Pragma("unroll") for (int m = 0; m < 4; ++m) _Pragma("unroll") for (int k = 0; k < 2; ++k) dst[m][k] = *(const PG8_LAS bf16x8*)(lds + PG8_SA(b, h) + aoff + m * 2048 + k * 1024); } while (0)
; #define PG8_LDB(dst, b, h) do { _Pragma("unroll") for (int n = 0; n < 2; ++n) _Pragma("unroll") for (int k = 0; k < 2; ++k) dst[n][k] = *(const PG8_LAS bf16x8*)(lds + PG8_SB(b, h) + boff + n * 2048 + k * 1024); } while (0)
; #define PG8_MMA(ai, bj, At, Bt) do { __builtin_amdgcn_s_setprio(1); _Pragma("unroll") for (int m = 0; m < 4; ++m) _Pragma("unroll") for (int n = 0; n < 2; ++n) _Pragma("unroll") for (int k = 0; k < 2; ++k) \
;         acc[ai][bj][m][n] = __builtin_amdgcn_mfma_f32_16x16x32_bf16(Bt[n][k], At[m][k], acc[ai][bj][m][n], 0, 0, 0); __builtin_amdgcn_s_setprio(0); } while (0)
; #define PG8_WAIT_V(n) asm volatile("s_waitcnt vmcnt(" #n ")" ::: "memory")
; #define PG8_WAIT_L(n) asm volatile("s_waitcnt lgkmcnt(" #n ")" ::: "memory")
; #define PG8_BAR __builtin_amdgcn_s_barrier()
; #define PG8_SCHED __builtin_amdgcn_sched_barrier(0)
; template <class Epi, class Sched, bool ALIGN_EPI = false, bool SP2 = false>
; __device__ __forceinline__ void gemm_phase(PG8_LAS unsigned char* lds, const Gemm g, const Sched& S, const Epi& E) {
;     ...
;             PG8_LDB(B0, 0, 0); PG8_LDB(B1, 0, 1); PG8_SCHED; PG8_LDA(At, 0, 0); PG8_STAGEA(PG8_SA(1, 1), a1 + hstep, voffA);
;             if (t == 0 && ui > 0) {
; #pragma unroll
;                 for (int a = 0; a < 2; ++a)
; #pragma unroll
;                     for (int b = 0; b < 2; ++b)
; #pragma unroll
;                         for (int m = 0; m < 4; ++m)
; #pragma unroll
;                             for (int n = 0; n < 2; ++n) acc[a][b][m][n] = (f32x4){0.f, 0.f, 0.f, 0.f}; }
;             PG8_WAIT_V(8); PG8_WAIT_L(0); PG8_BAR; PG8_MMA(0, 0, At, B0); PG8_MMA(0, 1, At, B1); PG8_BAR; PG8_SCHED;
;             PG8_LDA(At, 0, 1); PG8_STAGEB(PG8_SB(0, 0), b2, voffB); PG8_STAGEB(PG8_SB(0, 1), b2 + hstep, voffB); PG8_STAGEA(PG8_SA(0, 0), a2, voffA);
;             PG8_WAIT_V(8); PG8_WAIT_L(0); PG8_BAR; PG8_MMA(1, 0, At, B0); PG8_MMA(1, 1, At, B1); PG8_BAR; PG8_SCHED;
.LBB0_183:
	ds_read_b128 v[132:135], v196
	ds_read_b128 v[136:139], v196 offset:1024
	ds_read_b128 v[140:143], v196 offset:2048
	ds_read_b128 v[144:147], v196 offset:3072
	ds_read_b128 v[148:151], v208
	ds_read_b128 v[152:155], v208 offset:1024
	ds_read_b128 v[156:159], v208 offset:2048
	ds_read_b128 v[160:163], v208 offset:3072
	s_add_i32 s95, s46, s8
	s_mov_b32 m0, s56
	s_add_i32 vcc_lo, s95, 0x7ff80
	ds_read_b128 v[164:167], v207
	ds_read_b128 v[168:171], v207 offset:1024
	ds_read_b128 v[172:175], v207 offset:2048
	ds_read_b128 v[176:179], v207 offset:3072
	ds_read_b128 v[180:183], v207 offset:4096
	ds_read_b128 v[184:187], v207 offset:5120
	ds_read_b128 v[188:191], v207 offset:6144
	ds_read_b128 v[210:213], v207 offset:7168
	buffer_load_dwordx4 v1, s[60:63], vcc_lo offen lds
	s_mov_b32 m0, s1
	s_nop 0
	buffer_load_dwordx4 v202, s[60:63], vcc_lo offen lds
	s_waitcnt vmcnt(8)
	s_waitcnt lgkmcnt(0)
	s_add_i32 vcc_lo, s83, s8
	s_cmp_eq_u32 s87, 28
	s_setprio 1
	s_barrier
	v_mfma_f32_16x16x32_bf16 v[126:129], v[132:135], v[164:167], v[126:129]
	v_mfma_f32_16x16x32_bf16 v[122:125], v[140:143], v[164:167], v[122:125]
	v_mfma_f32_16x16x32_bf16 v[118:121], v[132:135], v[172:175], v[118:121]
	v_mfma_f32_16x16x32_bf16 v[114:117], v[140:143], v[172:175], v[114:117]
	v_mfma_f32_16x16x32_bf16 v[110:113], v[132:135], v[180:183], v[110:113]
	v_mfma_f32_16x16x32_bf16 v[106:109], v[140:143], v[180:183], v[106:109]
	v_mfma_f32_16x16x32_bf16 v[102:105], v[132:135], v[188:191], v[102:105]
	v_mfma_f32_16x16x32_bf16 v[98:101], v[140:143], v[188:191], v[98:101]
	v_mfma_f32_16x16x32_bf16 v[126:129], v[136:139], v[168:171], v[126:129]
	v_mfma_f32_16x16x32_bf16 v[122:125], v[144:147], v[168:171], v[122:125]
	v_mfma_f32_16x16x32_bf16 v[118:121], v[136:139], v[176:179], v[118:121]
	v_mfma_f32_16x16x32_bf16 v[114:117], v[144:147], v[176:179], v[114:117]
	v_mfma_f32_16x16x32_bf16 v[110:113], v[136:139], v[184:187], v[110:113]
	v_mfma_f32_16x16x32_bf16 v[106:109], v[144:147], v[184:187], v[106:109]
	v_mfma_f32_16x16x32_bf16 v[102:105], v[136:139], v[210:213], v[102:105]
	v_mfma_f32_16x16x32_bf16 v[98:101], v[144:147], v[210:213], v[98:101]
	v_mfma_f32_16x16x32_bf16 v[94:97], v[148:151], v[164:167], v[94:97]
	v_mfma_f32_16x16x32_bf16 v[90:93], v[156:159], v[164:167], v[90:93]
	v_mfma_f32_16x16x32_bf16 v[86:89], v[148:151], v[172:175], v[86:89]
	v_mfma_f32_16x16x32_bf16 v[82:85], v[156:159], v[172:175], v[82:85]
	v_mfma_f32_16x16x32_bf16 v[78:81], v[148:151], v[180:183], v[78:81]
	v_mfma_f32_16x16x32_bf16 v[74:77], v[156:159], v[180:183], v[74:77]
	v_mfma_f32_16x16x32_bf16 v[70:73], v[148:151], v[188:191], v[70:73]
	v_mfma_f32_16x16x32_bf16 v[66:69], v[156:159], v[188:191], v[66:69]
	v_mfma_f32_16x16x32_bf16 v[94:97], v[152:155], v[168:171], v[94:97]
	v_mfma_f32_16x16x32_bf16 v[90:93], v[160:163], v[168:171], v[90:93]
	v_mfma_f32_16x16x32_bf16 v[86:89], v[152:155], v[176:179], v[86:89]
	v_mfma_f32_16x16x32_bf16 v[82:85], v[160:163], v[176:179], v[82:85]
	v_mfma_f32_16x16x32_bf16 v[78:81], v[152:155], v[184:187], v[78:81]
	v_mfma_f32_16x16x32_bf16 v[74:77], v[160:163], v[184:187], v[74:77]
	v_mfma_f32_16x16x32_bf16 v[70:73], v[152:155], v[210:213], v[70:73]
	v_mfma_f32_16x16x32_bf16 v[66:69], v[160:163], v[210:213], v[66:69]
	s_setprio 0
	s_barrier
	s_mov_b32 m0, s35
	s_cselect_b32 vcc_lo, s47, vcc_lo
	ds_read_b128 v[164:167], v207 offset:16384
	ds_read_b128 v[168:171], v207 offset:17408
	ds_read_b128 v[172:175], v207 offset:18432
	ds_read_b128 v[176:179], v207 offset:19456
	ds_read_b128 v[180:183], v207 offset:20480
	ds_read_b128 v[184:187], v207 offset:21504
	ds_read_b128 v[188:191], v207 offset:22528
	ds_read_b128 v[210:213], v207 offset:23552
	buffer_load_dwordx4 v195, s[72:75], vcc_lo offen lds
	s_mov_b32 m0, s39
	s_cselect_b32 s95, s7, s95
	buffer_load_dwordx4 v203, s[72:75], vcc_lo offen lds
	s_add_i32 vcc_hi, vcc_lo, 0x80000
	s_mov_b32 m0, s79
	s_nop 0
	buffer_load_dwordx4 v195, s[72:75], vcc_hi offen lds
	s_mov_b32 m0, s85
	s_nop 0
	buffer_load_dwordx4 v203, s[72:75], vcc_hi offen lds
	s_mov_b32 m0, s96
	s_nop 0
	buffer_load_dwordx4 v1, s[60:63], s95 offen lds
	s_mov_b32 m0, s91
	s_nop 0
	buffer_load_dwordx4 v202, s[60:63], s95 offen lds
	s_waitcnt vmcnt(8)
	s_waitcnt lgkmcnt(0)
	s_setprio 1
	s_barrier
	v_mfma_f32_16x16x32_bf16 v[62:65], v[132:135], v[164:167], v[62:65]
	v_mfma_f32_16x16x32_bf16 v[58:61], v[140:143], v[164:167], v[58:61]
	v_mfma_f32_16x16x32_bf16 v[54:57], v[132:135], v[172:175], v[54:57]
	v_mfma_f32_16x16x32_bf16 v[50:53], v[140:143], v[172:175], v[50:53]
	v_mfma_f32_16x16x32_bf16 v[46:49], v[132:135], v[180:183], v[46:49]
	v_mfma_f32_16x16x32_bf16 v[42:45], v[140:143], v[180:183], v[42:45]
	v_mfma_f32_16x16x32_bf16 v[38:41], v[132:135], v[188:191], v[38:41]
	v_mfma_f32_16x16x32_bf16 v[34:37], v[140:143], v[188:191], v[34:37]
	v_mfma_f32_16x16x32_bf16 v[62:65], v[136:139], v[168:171], v[62:65]
	v_mfma_f32_16x16x32_bf16 v[58:61], v[144:147], v[168:171], v[58:61]
	v_mfma_f32_16x16x32_bf16 v[54:57], v[136:139], v[176:179], v[54:57]
	v_mfma_f32_16x16x32_bf16 v[50:53], v[144:147], v[176:179], v[50:53]
	v_mfma_f32_16x16x32_bf16 v[46:49], v[136:139], v[184:187], v[46:49]
	v_mfma_f32_16x16x32_bf16 v[42:45], v[144:147], v[184:187], v[42:45]
	v_mfma_f32_16x16x32_bf16 v[38:41], v[136:139], v[210:213], v[38:41]
	v_mfma_f32_16x16x32_bf16 v[34:37], v[144:147], v[210:213], v[34:37]
	v_mfma_f32_16x16x32_bf16 v[30:33], v[148:151], v[164:167], v[30:33]
	v_mfma_f32_16x16x32_bf16 v[26:29], v[156:159], v[164:167], v[26:29]
	v_mfma_f32_16x16x32_bf16 v[22:25], v[148:151], v[172:175], v[22:25]
	v_mfma_f32_16x16x32_bf16 v[18:21], v[156:159], v[172:175], v[18:21]
	v_mfma_f32_16x16x32_bf16 v[14:17], v[148:151], v[180:183], v[14:17]
	v_mfma_f32_16x16x32_bf16 v[10:13], v[156:159], v[180:183], v[10:13]
	v_mfma_f32_16x16x32_bf16 v[6:9], v[148:151], v[188:191], v[6:9]
	v_mfma_f32_16x16x32_bf16 v[2:5], v[156:159], v[188:191], v[2:5]
	v_mfma_f32_16x16x32_bf16 v[30:33], v[152:155], v[168:171], v[30:33]
	v_mfma_f32_16x16x32_bf16 v[26:29], v[160:163], v[168:171], v[26:29]
	v_mfma_f32_16x16x32_bf16 v[22:25], v[152:155], v[176:179], v[22:25]
	v_mfma_f32_16x16x32_bf16 v[18:21], v[160:163], v[176:179], v[18:21]
	v_mfma_f32_16x16x32_bf16 v[14:17], v[152:155], v[184:187], v[14:17]
	v_mfma_f32_16x16x32_bf16 v[10:13], v[160:163], v[184:187], v[10:13]
	v_mfma_f32_16x16x32_bf16 v[6:9], v[152:155], v[210:213], v[6:9]
	v_mfma_f32_16x16x32_bf16 v[2:5], v[160:163], v[210:213], v[2:5]
	s_setprio 0
	s_barrier
;     __device__ bool next(int i, Unit& u) const { const int L = i * G + c; if (L >= 128) return false; u.pm = L; u.pn = L >> 1; return true; }
; #define PG8_STAGEA(bufoff, goff, voff) PG8_STAGEX(rsA, bufoff, goff, voff)
; #define PG8_STAGEB(bufoff, goff, voff) PG8_STAGEX(rsB, bufoff, goff, voff)
; #define PG8_LDA(dst, b, h) do { _Pragma("unroll") for (int m = 0; m < 4; ++m) _Pragma("unroll") for (int k = 0; k < 2; ++k) dst[m][k] = *(const PG8_LAS bf16x8*)(lds + PG8_SA(b, h) + aoff + m * 2048 + k * 1024); } while (0)
; #define PG8_LDB(dst, b, h) do { _Pragma("unroll") for (int n = 0; n < 2; ++n) _Pragma("unroll") for (int k = 0; k < 2; ++k) dst[n][k] = *(const PG8_LAS bf16x8*)(lds + PG8_SB(b, h) + boff + n * 2048 + k * 1024); } while (0)
; #define PG8_MMA(ai, bj, At, Bt) do { __builtin_amdgcn_s_setprio(1); _Pragma("unroll") for (int m = 0; m < 4; ++m) _Pragma("unroll") for (int n = 0; n < 2; ++n) _Pragma("unroll") for (int k = 0; k < 2; ++k) \
;         acc[ai][bj][m][n] = __builtin_amdgcn_mfma_f32_16x16x32_bf16(Bt[n][k], At[m][k], acc[ai][bj][m][n], 0, 0, 0); __builtin_amdgcn_s_setprio(0); } while (0)
; #define PG8_WAIT_V(n) asm volatile("s_waitcnt vmcnt(" #n ")" ::: "memory")
; #define PG8_WAIT_L(n) asm volatile("s_waitcnt lgkmcnt(" #n ")" ::: "memory")
; #define PG8_BAR __builtin_amdgcn_s_barrier()
; #define PG8_SCHED __builtin_amdgcn_sched_barrier(0)
; template <class Epi, class Sched, bool ALIGN_EPI = false, bool SP2 = false>
; __device__ __forceinline__ void gemm_phase(PG8_LAS unsigned char* lds, const Gemm g, const Sched& S, const Epi& E) {
;     ...
;     for (;;) {
;         const bool has_next = S.next(ui + 1, nxt);
;         const size_t nA = has_next ? (size_t)nxt.pm * tstep : cA; const size_t nB = has_next ? (size_t)nxt.pn * tstep : cB;
;         for (int t = 0; t < nt; t += 2) {
;     ...
;             PG8_LDB(B0, 1, 0); PG8_LDB(B1, 1, 1); PG8_SCHED; PG8_LDA(At, 1, 0); PG8_STAGEA(PG8_SA(0, 1), a2 + hstep, voffA);
;             PG8_WAIT_V(8); PG8_WAIT_L(0); PG8_BAR; PG8_MMA(0, 0, At, B0); PG8_MMA(0, 1, At, B1); PG8_BAR; PG8_SCHED;
;             PG8_LDA(At, 1, 1); PG8_STAGEB(PG8_SB(1, 0), b3, voffB); PG8_STAGEB(PG8_SB(1, 1), b3 + hstep, voffB); PG8_STAGEA(PG8_SA(1, 0), a3, voffA);
;             PG8_WAIT_V(8); PG8_WAIT_L(0); PG8_BAR; PG8_MMA(1, 0, At, B0); PG8_MMA(1, 1, At, B1); PG8_BAR; PG8_SCHED;
	ds_read_b128 v[132:135], v130
	ds_read_b128 v[136:139], v130 offset:1024
	ds_read_b128 v[140:143], v130 offset:2048
	ds_read_b128 v[144:147], v130 offset:3072
	ds_read_b128 v[148:151], v131
	ds_read_b128 v[152:155], v131 offset:1024
	ds_read_b128 v[156:159], v131 offset:2048
	ds_read_b128 v[160:163], v131 offset:3072
	s_add_i32 vcc_hi, s95, 0x80000
	s_mov_b32 m0, s89
	ds_read_b128 v[164:167], v207 offset:32768
	ds_read_b128 v[168:171], v207 offset:33792
	ds_read_b128 v[172:175], v207 offset:34816
	ds_read_b128 v[176:179], v207 offset:35840
	ds_read_b128 v[180:183], v207 offset:36864
	ds_read_b128 v[184:187], v207 offset:37888
	ds_read_b128 v[188:191], v207 offset:38912
	ds_read_b128 v[210:213], v207 offset:39936
	buffer_load_dwordx4 v1, s[60:63], vcc_hi offen lds
	s_mov_b32 m0, s59
	s_nop 0
	buffer_load_dwordx4 v202, s[60:63], vcc_hi offen lds
	s_waitcnt vmcnt(8)
	s_waitcnt lgkmcnt(0)
	s_setprio 1
	s_barrier
	v_mfma_f32_16x16x32_bf16 v[126:129], v[132:135], v[164:167], v[126:129]
	v_mfma_f32_16x16x32_bf16 v[122:125], v[140:143], v[164:167], v[122:125]
	v_mfma_f32_16x16x32_bf16 v[118:121], v[132:135], v[172:175], v[118:121]
	v_mfma_f32_16x16x32_bf16 v[114:117], v[140:143], v[172:175], v[114:117]
	v_mfma_f32_16x16x32_bf16 v[110:113], v[132:135], v[180:183], v[110:113]
	v_mfma_f32_16x16x32_bf16 v[106:109], v[140:143], v[180:183], v[106:109]
	v_mfma_f32_16x16x32_bf16 v[102:105], v[132:135], v[188:191], v[102:105]
	v_mfma_f32_16x16x32_bf16 v[98:101], v[140:143], v[188:191], v[98:101]
	v_mfma_f32_16x16x32_bf16 v[126:129], v[136:139], v[168:171], v[126:129]
	v_mfma_f32_16x16x32_bf16 v[122:125], v[144:147], v[168:171], v[122:125]
	v_mfma_f32_16x16x32_bf16 v[118:121], v[136:139], v[176:179], v[118:121]
	v_mfma_f32_16x16x32_bf16 v[114:117], v[144:147], v[176:179], v[114:117]
	v_mfma_f32_16x16x32_bf16 v[110:113], v[136:139], v[184:187], v[110:113]
	v_mfma_f32_16x16x32_bf16 v[106:109], v[144:147], v[184:187], v[106:109]
	v_mfma_f32_16x16x32_bf16 v[102:105], v[136:139], v[210:213], v[102:105]
	v_mfma_f32_16x16x32_bf16 v[98:101], v[144:147], v[210:213], v[98:101]
	v_mfma_f32_16x16x32_bf16 v[94:97], v[148:151], v[164:167], v[94:97]
	v_mfma_f32_16x16x32_bf16 v[90:93], v[156:159], v[164:167], v[90:93]
	v_mfma_f32_16x16x32_bf16 v[86:89], v[148:151], v[172:175], v[86:89]
	v_mfma_f32_16x16x32_bf16 v[82:85], v[156:159], v[172:175], v[82:85]
	v_mfma_f32_16x16x32_bf16 v[78:81], v[148:151], v[180:183], v[78:81]
	v_mfma_f32_16x16x32_bf16 v[74:77], v[156:159], v[180:183], v[74:77]
	v_mfma_f32_16x16x32_bf16 v[70:73], v[148:151], v[188:191], v[70:73]
	v_mfma_f32_16x16x32_bf16 v[66:69], v[156:159], v[188:191], v[66:69]
	v_mfma_f32_16x16x32_bf16 v[94:97], v[152:155], v[168:171], v[94:97]
	v_mfma_f32_16x16x32_bf16 v[90:93], v[160:163], v[168:171], v[90:93]
	v_mfma_f32_16x16x32_bf16 v[86:89], v[152:155], v[176:179], v[86:89]
	v_mfma_f32_16x16x32_bf16 v[82:85], v[160:163], v[176:179], v[82:85]
	v_mfma_f32_16x16x32_bf16 v[78:81], v[152:155], v[184:187], v[78:81]
	v_mfma_f32_16x16x32_bf16 v[74:77], v[160:163], v[184:187], v[74:77]
	v_mfma_f32_16x16x32_bf16 v[70:73], v[152:155], v[210:213], v[70:73]
	v_mfma_f32_16x16x32_bf16 v[66:69], v[160:163], v[210:213], v[66:69]
	s_setprio 0
	s_barrier
	s_mov_b32 m0, s58
	s_add_i32 vcc_hi, vcc_lo, 0x80
	ds_read_b128 v[164:167], v207 offset:49152
	ds_read_b128 v[168:171], v207 offset:50176
	ds_read_b128 v[172:175], v207 offset:51200
	ds_read_b128 v[176:179], v207 offset:52224
	ds_read_b128 v[180:183], v207 offset:53248
	ds_read_b128 v[184:187], v207 offset:54272
	ds_read_b128 v[188:191], v207 offset:55296
	ds_read_b128 v[210:213], v207 offset:56320
	buffer_load_dwordx4 v195, s[72:75], vcc_hi offen lds
	s_mov_b32 m0, s2
	s_add_i32 vcc_lo, vcc_lo, 0x80080
	buffer_load_dwordx4 v203, s[72:75], vcc_hi offen lds
	s_mov_b32 m0, s70
	s_addk_i32 s95, 0x80
	buffer_load_dwordx4 v195, s[72:75], vcc_lo offen lds
	s_mov_b32 m0, s71
	s_nop 0
	buffer_load_dwordx4 v203, s[72:75], vcc_lo offen lds
	s_mov_b32 m0, s3
	s_nop 0
	buffer_load_dwordx4 v1, s[60:63], s95 offen lds
	s_mov_b32 m0, s57
	s_nop 0
	buffer_load_dwordx4 v202, s[60:63], s95 offen lds
	s_waitcnt vmcnt(8)
	s_waitcnt lgkmcnt(0)
	s_setprio 1
	s_barrier
	v_mfma_f32_16x16x32_bf16 v[62:65], v[132:135], v[164:167], v[62:65]
	v_mfma_f32_16x16x32_bf16 v[58:61], v[140:143], v[164:167], v[58:61]
	v_mfma_f32_16x16x32_bf16 v[54:57], v[132:135], v[172:175], v[54:57]
	v_mfma_f32_16x16x32_bf16 v[50:53], v[140:143], v[172:175], v[50:53]
	v_mfma_f32_16x16x32_bf16 v[46:49], v[132:135], v[180:183], v[46:49]
	v_mfma_f32_16x16x32_bf16 v[42:45], v[140:143], v[180:183], v[42:45]
	v_mfma_f32_16x16x32_bf16 v[38:41], v[132:135], v[188:191], v[38:41]
	v_mfma_f32_16x16x32_bf16 v[34:37], v[140:143], v[188:191], v[34:37]
	v_mfma_f32_16x16x32_bf16 v[62:65], v[136:139], v[168:171], v[62:65]
	v_mfma_f32_16x16x32_bf16 v[58:61], v[144:147], v[168:171], v[58:61]
	v_mfma_f32_16x16x32_bf16 v[54:57], v[136:139], v[176:179], v[54:57]
	v_mfma_f32_16x16x32_bf16 v[50:53], v[144:147], v[176:179], v[50:53]
	v_mfma_f32_16x16x32_bf16 v[46:49], v[136:139], v[184:187], v[46:49]
	v_mfma_f32_16x16x32_bf16 v[42:45], v[144:147], v[184:187], v[42:45]
	v_mfma_f32_16x16x32_bf16 v[38:41], v[136:139], v[210:213], v[38:41]
	v_mfma_f32_16x16x32_bf16 v[34:37], v[144:147], v[210:213], v[34:37]
	v_mfma_f32_16x16x32_bf16 v[30:33], v[148:151], v[164:167], v[30:33]
	v_mfma_f32_16x16x32_bf16 v[26:29], v[156:159], v[164:167], v[26:29]
	v_mfma_f32_16x16x32_bf16 v[22:25], v[148:151], v[172:175], v[22:25]
	v_mfma_f32_16x16x32_bf16 v[18:21], v[156:159], v[172:175], v[18:21]
	v_mfma_f32_16x16x32_bf16 v[14:17], v[148:151], v[180:183], v[14:17]
	v_mfma_f32_16x16x32_bf16 v[10:13], v[156:159], v[180:183], v[10:13]
	v_mfma_f32_16x16x32_bf16 v[6:9], v[148:151], v[188:191], v[6:9]
	v_mfma_f32_16x16x32_bf16 v[2:5], v[156:159], v[188:191], v[2:5]
	v_mfma_f32_16x16x32_bf16 v[30:33], v[152:155], v[168:171], v[30:33]
	v_mfma_f32_16x16x32_bf16 v[26:29], v[160:163], v[168:171], v[26:29]
	v_mfma_f32_16x16x32_bf16 v[22:25], v[152:155], v[176:179], v[22:25]
	v_mfma_f32_16x16x32_bf16 v[18:21], v[160:163], v[176:179], v[18:21]
	v_mfma_f32_16x16x32_bf16 v[14:17], v[152:155], v[184:187], v[14:17]
	v_mfma_f32_16x16x32_bf16 v[10:13], v[160:163], v[184:187], v[10:13]
	v_mfma_f32_16x16x32_bf16 v[6:9], v[152:155], v[210:213], v[6:9]
	v_mfma_f32_16x16x32_bf16 v[2:5], v[160:163], v[210:213], v[2:5]
	s_setprio 0
	s_barrier
	s_add_i32 s87, s87, 2
	s_add_u32 s8, s8, 0x100
	s_addc_u32 s9, s9, 0
	s_cmp_gt_u32 s87, 29
	s_cbranch_scc0 .LBB0_183
	v_readlane_b32 s8, v234, 53
	v_readlane_b32 s9, v234, 54
	s_and_b64 vcc, exec, s[8:9]
	s_cbranch_vccz .LBB0_186
	s_barrier

; #define PG8_STAGEA(bufoff, goff, voff) PG8_STAGEX(rsA, bufoff, goff, voff)
; #define PG8_STAGEB(bufoff, goff, voff) PG8_STAGEX(rsB, bufoff, goff, voff)
; #define PG8_LDA(dst, b, h) do { _Pragma("unroll") for (int m = 0; m < 4; ++m) _Pragma("unroll") for (int k = 0; k < 2; ++k) dst[m][k] = *(const PG8_LAS bf16x8*)(lds + PG8_SA(b, h) + aoff + m * 2048 + k * 1024); } while (0)
; #define PG8_MMA(ai, bj, At, Bt) do { __builtin_amdgcn_s_setprio(1); _Pragma("unroll") for (int m = 0; m < 4; ++m) _Pragma("unroll") for (int n = 0; n < 2; ++n) _Pragma("unroll") for (int k = 0; k < 2; ++k) \
;         acc[ai][bj][m][n] = __builtin_amdgcn_mfma_f32_16x16x32_bf16(Bt[n][k], At[m][k], acc[ai][bj][m][n], 0, 0, 0); __builtin_amdgcn_s_setprio(0); } while (0)
; #define PG8_WAIT_V(n) asm volatile("s_waitcnt vmcnt(" #n ")" ::: "memory")
; #define PG8_WAIT_L(n) asm volatile("s_waitcnt lgkmcnt(" #n ")" ::: "memory")
; #define PG8_BAR __builtin_amdgcn_s_barrier()
; #define PG8_SCHED __builtin_amdgcn_sched_barrier(0)
; template <class Epi, class Sched, bool ALIGN_EPI = false, bool SP2 = false>
; __device__ __forceinline__ void gemm_phase(PG8_LAS unsigned char* lds, const Gemm g, const Sched& S, const Epi& E) {
;     ...
;             PG8_WAIT_V(8); PG8_WAIT_L(0); PG8_BAR; PG8_MMA(0, 0, At, B0); PG8_MMA(0, 1, At, B1); PG8_BAR; PG8_SCHED;
;             PG8_LDA(At, 0, 1); PG8_STAGEB(PG8_SB(0, 0), b2, voffB); PG8_STAGEB(PG8_SB(0, 1), b2 + hstep, voffB); PG8_STAGEA(PG8_SA(0, 0), a2, voffA);
;             PG8_WAIT_V(8); PG8_WAIT_L(0); PG8_BAR; PG8_MMA(1, 0, At, B0); PG8_MMA(1, 1, At, B1); PG8_BAR; PG8_SCHED;
.LBB0_478:
	s_waitcnt vmcnt(8)
	s_waitcnt lgkmcnt(0)
	s_setprio 1
	s_barrier
	v_mfma_f32_16x16x32_bf16 v[126:129], v[146:149], v[186:189], v[126:129]
	v_mfma_f32_16x16x32_bf16 v[122:125], v[154:157], v[186:189], v[122:125]
	v_mfma_f32_16x16x32_bf16 v[110:113], v[146:149], v[178:181], v[110:113]
	v_mfma_f32_16x16x32_bf16 v[106:109], v[154:157], v[178:181], v[106:109]
	v_mfma_f32_16x16x32_bf16 v[94:97], v[146:149], v[170:173], v[94:97]
	v_mfma_f32_16x16x32_bf16 v[90:93], v[154:157], v[170:173], v[90:93]
	v_mfma_f32_16x16x32_bf16 v[78:81], v[146:149], v[162:165], v[78:81]
	v_mfma_f32_16x16x32_bf16 v[74:77], v[154:157], v[162:165], v[74:77]
	v_mfma_f32_16x16x32_bf16 v[126:129], v[150:153], v[190:193], v[126:129]
	v_mfma_f32_16x16x32_bf16 v[122:125], v[158:161], v[190:193], v[122:125]
	v_mfma_f32_16x16x32_bf16 v[110:113], v[150:153], v[182:185], v[110:113]
	v_mfma_f32_16x16x32_bf16 v[106:109], v[158:161], v[182:185], v[106:109]
	v_mfma_f32_16x16x32_bf16 v[94:97], v[150:153], v[174:177], v[94:97]
	v_mfma_f32_16x16x32_bf16 v[90:93], v[158:161], v[174:177], v[90:93]
	v_mfma_f32_16x16x32_bf16 v[78:81], v[150:153], v[166:169], v[78:81]
	v_mfma_f32_16x16x32_bf16 v[74:77], v[158:161], v[166:169], v[74:77]
	v_mfma_f32_16x16x32_bf16 v[118:121], v[130:133], v[186:189], v[118:121]
	v_mfma_f32_16x16x32_bf16 v[114:117], v[138:141], v[186:189], v[114:117]
	v_mfma_f32_16x16x32_bf16 v[102:105], v[130:133], v[178:181], v[102:105]
	v_mfma_f32_16x16x32_bf16 v[98:101], v[138:141], v[178:181], v[98:101]
	v_mfma_f32_16x16x32_bf16 v[86:89], v[130:133], v[170:173], v[86:89]
	v_mfma_f32_16x16x32_bf16 v[82:85], v[138:141], v[170:173], v[82:85]
	v_mfma_f32_16x16x32_bf16 v[70:73], v[130:133], v[162:165], v[70:73]
	v_mfma_f32_16x16x32_bf16 v[66:69], v[138:141], v[162:165], v[66:69]
	v_mfma_f32_16x16x32_bf16 v[118:121], v[134:137], v[190:193], v[118:121]
	v_mfma_f32_16x16x32_bf16 v[114:117], v[142:145], v[190:193], v[114:117]
	v_mfma_f32_16x16x32_bf16 v[102:105], v[134:137], v[182:185], v[102:105]
	v_mfma_f32_16x16x32_bf16 v[98:101], v[142:145], v[182:185], v[98:101]
	v_mfma_f32_16x16x32_bf16 v[86:89], v[134:137], v[174:177], v[86:89]
	v_mfma_f32_16x16x32_bf16 v[82:85], v[142:145], v[174:177], v[82:85]
	v_mfma_f32_16x16x32_bf16 v[70:73], v[134:137], v[166:169], v[70:73]
	v_mfma_f32_16x16x32_bf16 v[66:69], v[142:145], v[166:169], v[66:69]
	s_setprio 0
	s_barrier
	s_mov_b32 m0, s59
	s_add_i32 s78, s34, 0x100
	s_mov_b32 s70, s14
	s_mov_b32 s71, s15
	ds_read_b128 v[162:165], v227 offset:16384
	ds_read_b128 v[166:169], v227 offset:17408
	ds_read_b128 v[170:173], v227 offset:18432
	ds_read_b128 v[174:177], v227 offset:19456
	ds_read_b128 v[178:181], v227 offset:20480
	ds_read_b128 v[182:185], v227 offset:21504
	ds_read_b128 v[186:189], v227 offset:22528
	ds_read_b128 v[190:193], v227 offset:23552
	buffer_load_dwordx4 v212, s[68:71], s78 offen lds
	s_mov_b32 m0, s65
	s_nop 0
	buffer_load_dwordx4 v213, s[68:71], s78 offen lds
	s_add_i32 s78, s34, 0x18100
	s_mov_b32 m0, s80
	s_nop 0
	buffer_load_dwordx4 v212, s[68:71], s78 offen lds
	s_mov_b32 m0, s81
	s_nop 0
	buffer_load_dwordx4 v213, s[68:71], s78 offen lds
	s_add_i32 s78, s38, 0x100
	s_mov_b32 m0, s58
	s_nop 0
	buffer_load_dwordx4 v212, s[12:15], s78 offen lds
	s_mov_b32 m0, s82
	s_nop 0
	buffer_load_dwordx4 v213, s[12:15], s78 offen lds
	s_waitcnt vmcnt(8)
	s_waitcnt lgkmcnt(0)
	s_setprio 1
	s_barrier
	v_mfma_f32_16x16x32_bf16 v[62:65], v[146:149], v[162:165], v[62:65]
	v_mfma_f32_16x16x32_bf16 v[58:61], v[154:157], v[162:165], v[58:61]
	v_mfma_f32_16x16x32_bf16 v[46:49], v[146:149], v[170:173], v[46:49]
	v_mfma_f32_16x16x32_bf16 v[42:45], v[154:157], v[170:173], v[42:45]
	v_mfma_f32_16x16x32_bf16 v[30:33], v[146:149], v[178:181], v[30:33]
	v_mfma_f32_16x16x32_bf16 v[26:29], v[154:157], v[178:181], v[26:29]
	v_mfma_f32_16x16x32_bf16 v[14:17], v[146:149], v[186:189], v[14:17]
	v_mfma_f32_16x16x32_bf16 v[10:13], v[154:157], v[186:189], v[10:13]
	v_mfma_f32_16x16x32_bf16 v[62:65], v[150:153], v[166:169], v[62:65]
	v_mfma_f32_16x16x32_bf16 v[58:61], v[158:161], v[166:169], v[58:61]
	v_mfma_f32_16x16x32_bf16 v[46:49], v[150:153], v[174:177], v[46:49]
	v_mfma_f32_16x16x32_bf16 v[42:45], v[158:161], v[174:177], v[42:45]
	v_mfma_f32_16x16x32_bf16 v[30:33], v[150:153], v[182:185], v[30:33]
	v_mfma_f32_16x16x32_bf16 v[26:29], v[158:161], v[182:185], v[26:29]
	v_mfma_f32_16x16x32_bf16 v[14:17], v[150:153], v[190:193], v[14:17]
	v_mfma_f32_16x16x32_bf16 v[10:13], v[158:161], v[190:193], v[10:13]
	v_mfma_f32_16x16x32_bf16 v[54:57], v[130:133], v[162:165], v[54:57]
	v_mfma_f32_16x16x32_bf16 v[50:53], v[138:141], v[162:165], v[50:53]
	v_mfma_f32_16x16x32_bf16 v[38:41], v[130:133], v[170:173], v[38:41]
	v_mfma_f32_16x16x32_bf16 v[34:37], v[138:141], v[170:173], v[34:37]
	v_mfma_f32_16x16x32_bf16 v[22:25], v[130:133], v[178:181], v[22:25]
	v_mfma_f32_16x16x32_bf16 v[18:21], v[138:141], v[178:181], v[18:21]
	v_mfma_f32_16x16x32_bf16 v[6:9], v[130:133], v[186:189], v[6:9]
	v_mfma_f32_16x16x32_bf16 v[2:5], v[138:141], v[186:189], v[2:5]
	v_mfma_f32_16x16x32_bf16 v[54:57], v[134:137], v[166:169], v[54:57]
	v_mfma_f32_16x16x32_bf16 v[50:53], v[142:145], v[166:169], v[50:53]
	v_mfma_f32_16x16x32_bf16 v[38:41], v[134:137], v[174:177], v[38:41]
	v_mfma_f32_16x16x32_bf16 v[34:37], v[142:145], v[174:177], v[34:37]
	v_mfma_f32_16x16x32_bf16 v[22:25], v[134:137], v[182:185], v[22:25]
	v_mfma_f32_16x16x32_bf16 v[18:21], v[142:145], v[182:185], v[18:21]
	v_mfma_f32_16x16x32_bf16 v[6:9], v[134:137], v[190:193], v[6:9]
	v_mfma_f32_16x16x32_bf16 v[2:5], v[142:145], v[190:193], v[2:5]
	s_setprio 0
	s_barrier
; #define PG8_STAGEA(bufoff, goff, voff) PG8_STAGEX(rsA, bufoff, goff, voff)
; #define PG8_STAGEB(bufoff, goff, voff) PG8_STAGEX(rsB, bufoff, goff, voff)
; #define PG8_LDA(dst, b, h) do { _Pragma("unroll") for (int m = 0; m < 4; ++m) _Pragma("unroll") for (int k = 0; k < 2; ++k) dst[m][k] = *(const PG8_LAS bf16x8*)(lds + PG8_SA(b, h) + aoff + m * 2048 + k * 1024); } while (0)
; #define PG8_LDB(dst, b, h) do { _Pragma("unroll") for (int n = 0; n < 2; ++n) _Pragma("unroll") for (int k = 0; k < 2; ++k) dst[n][k] = *(const PG8_LAS bf16x8*)(lds + PG8_SB(b, h) + boff + n * 2048 + k * 1024); } while (0)
; #define PG8_MMA(ai, bj, At, Bt) do { __builtin_amdgcn_s_setprio(1); _Pragma("unroll") for (int m = 0; m < 4; ++m) _Pragma("unroll") for (int n = 0; n < 2; ++n) _Pragma("unroll") for (int k = 0; k < 2; ++k) \
;         acc[ai][bj][m][n] = __builtin_amdgcn_mfma_f32_16x16x32_bf16(Bt[n][k], At[m][k], acc[ai][bj][m][n], 0, 0, 0); __builtin_amdgcn_s_setprio(0); } while (0)
; #define PG8_WAIT_V(n) asm volatile("s_waitcnt vmcnt(" #n ")" ::: "memory")
; #define PG8_WAIT_L(n) asm volatile("s_waitcnt lgkmcnt(" #n ")" ::: "memory")
; #define PG8_BAR __builtin_amdgcn_s_barrier()
; #define PG8_SCHED __builtin_amdgcn_sched_barrier(0)
; template <class Epi, class Sched, bool ALIGN_EPI = false, bool SP2 = false>
; __device__ __forceinline__ void gemm_phase(PG8_LAS unsigned char* lds, const Gemm g, const Sched& S, const Epi& E) {
;     ...
;             PG8_LDB(B0, 1, 0); PG8_LDB(B1, 1, 1); PG8_SCHED; PG8_LDA(At, 1, 0); PG8_STAGEA(PG8_SA(0, 1), a2 + hstep, voffA);
;             PG8_WAIT_V(8); PG8_WAIT_L(0); PG8_BAR; PG8_MMA(0, 0, At, B0); PG8_MMA(0, 1, At, B1); PG8_BAR; PG8_SCHED;
;             PG8_LDA(At, 1, 1); PG8_STAGEB(PG8_SB(1, 0), b3, voffB); PG8_STAGEB(PG8_SB(1, 1), b3 + hstep, voffB); PG8_STAGEA(PG8_SA(1, 0), a3, voffA);
;             PG8_WAIT_V(8); PG8_WAIT_L(0); PG8_BAR; PG8_MMA(1, 0, At, B0); PG8_MMA(1, 1, At, B1); PG8_BAR; PG8_SCHED;
	v_add_u32_e32 v130, 0x18000, v196
	v_add_u32_e32 v131, 0x1c000, v196
	ds_read_b128 v[132:135], v130
	ds_read_b128 v[136:139], v130 offset:1024
	ds_read_b128 v[140:143], v130 offset:2048
	ds_read_b128 v[144:147], v130 offset:3072
	ds_read_b128 v[148:151], v131
	ds_read_b128 v[152:155], v131 offset:1024
	ds_read_b128 v[156:159], v131 offset:2048
	ds_read_b128 v[160:163], v131 offset:3072
	s_add_i32 s78, s38, 0x18100
	s_mov_b32 m0, s83
	ds_read_b128 v[164:167], v227 offset:32768
	ds_read_b128 v[168:171], v227 offset:33792
	ds_read_b128 v[172:175], v227 offset:34816
	ds_read_b128 v[176:179], v227 offset:35840
	ds_read_b128 v[180:183], v227 offset:36864
	ds_read_b128 v[184:187], v227 offset:37888
	ds_read_b128 v[188:191], v227 offset:38912
	ds_read_b128 v[230:233], v227 offset:39936
	buffer_load_dwordx4 v212, s[12:15], s78 offen lds
	s_mov_b32 m0, s84
	s_nop 0
	buffer_load_dwordx4 v213, s[12:15], s78 offen lds
	s_waitcnt vmcnt(8)
	s_waitcnt lgkmcnt(0)
	s_setprio 1
	s_barrier
	v_mfma_f32_16x16x32_bf16 v[126:129], v[132:135], v[164:167], v[126:129]
	v_mfma_f32_16x16x32_bf16 v[122:125], v[140:143], v[164:167], v[122:125]
	v_mfma_f32_16x16x32_bf16 v[110:113], v[132:135], v[172:175], v[110:113]
	v_mfma_f32_16x16x32_bf16 v[106:109], v[140:143], v[172:175], v[106:109]
	v_mfma_f32_16x16x32_bf16 v[94:97], v[132:135], v[180:183], v[94:97]
	v_mfma_f32_16x16x32_bf16 v[90:93], v[140:143], v[180:183], v[90:93]
	v_mfma_f32_16x16x32_bf16 v[78:81], v[132:135], v[188:191], v[78:81]
	v_mfma_f32_16x16x32_bf16 v[74:77], v[140:143], v[188:191], v[74:77]
	v_mfma_f32_16x16x32_bf16 v[126:129], v[136:139], v[168:171], v[126:129]
	v_mfma_f32_16x16x32_bf16 v[122:125], v[144:147], v[168:171], v[122:125]
	v_mfma_f32_16x16x32_bf16 v[110:113], v[136:139], v[176:179], v[110:113]
	v_mfma_f32_16x16x32_bf16 v[106:109], v[144:147], v[176:179], v[106:109]
	v_mfma_f32_16x16x32_bf16 v[94:97], v[136:139], v[184:187], v[94:97]
	v_mfma_f32_16x16x32_bf16 v[90:93], v[144:147], v[184:187], v[90:93]
	v_mfma_f32_16x16x32_bf16 v[78:81], v[136:139], v[230:233], v[78:81]
	v_mfma_f32_16x16x32_bf16 v[74:77], v[144:147], v[230:233], v[74:77]
	v_mfma_f32_16x16x32_bf16 v[118:121], v[148:151], v[164:167], v[118:121]
	v_mfma_f32_16x16x32_bf16 v[114:117], v[156:159], v[164:167], v[114:117]
	v_mfma_f32_16x16x32_bf16 v[102:105], v[148:151], v[172:175], v[102:105]
	v_mfma_f32_16x16x32_bf16 v[98:101], v[156:159], v[172:175], v[98:101]
	v_mfma_f32_16x16x32_bf16 v[86:89], v[148:151], v[180:183], v[86:89]
	v_mfma_f32_16x16x32_bf16 v[82:85], v[156:159], v[180:183], v[82:85]
	v_mfma_f32_16x16x32_bf16 v[70:73], v[148:151], v[188:191], v[70:73]
	v_mfma_f32_16x16x32_bf16 v[66:69], v[156:159], v[188:191], v[66:69]
	v_mfma_f32_16x16x32_bf16 v[118:121], v[152:155], v[168:171], v[118:121]
	v_mfma_f32_16x16x32_bf16 v[114:117], v[160:163], v[168:171], v[114:117]
	v_mfma_f32_16x16x32_bf16 v[102:105], v[152:155], v[176:179], v[102:105]
	v_mfma_f32_16x16x32_bf16 v[98:101], v[160:163], v[176:179], v[98:101]
	v_mfma_f32_16x16x32_bf16 v[86:89], v[152:155], v[184:187], v[86:89]
	v_mfma_f32_16x16x32_bf16 v[82:85], v[160:163], v[184:187], v[82:85]
	v_mfma_f32_16x16x32_bf16 v[70:73], v[152:155], v[230:233], v[70:73]
	v_mfma_f32_16x16x32_bf16 v[66:69], v[160:163], v[230:233], v[66:69]
	s_setprio 0
	s_barrier
	s_mov_b32 m0, s85
	s_add_i32 s78, s34, 0x180
	ds_read_b128 v[164:167], v227 offset:49152
	ds_read_b128 v[168:171], v227 offset:50176
	ds_read_b128 v[172:175], v227 offset:51200
	ds_read_b128 v[176:179], v227 offset:52224
	ds_read_b128 v[180:183], v227 offset:53248
	ds_read_b128 v[184:187], v227 offset:54272
	ds_read_b128 v[188:191], v227 offset:55296
	ds_read_b128 v[230:233], v227 offset:56320
	buffer_load_dwordx4 v212, s[68:71], s78 offen lds
	s_mov_b32 m0, s87
	s_nop 0
	buffer_load_dwordx4 v213, s[68:71], s78 offen lds
	s_add_i32 s78, s34, 0x18180
	s_mov_b32 m0, s90
	s_nop 0
	buffer_load_dwordx4 v212, s[68:71], s78 offen lds
	s_mov_b32 m0, s91
	s_nop 0
	buffer_load_dwordx4 v213, s[68:71], s78 offen lds
	s_add_i32 s78, s38, 0x180
	s_mov_b32 m0, s88
	s_nop 0
	buffer_load_dwordx4 v212, s[12:15], s78 offen lds
	s_mov_b32 m0, s89
	s_nop 0
	buffer_load_dwordx4 v213, s[12:15], s78 offen lds
	s_waitcnt vmcnt(8)
	s_waitcnt lgkmcnt(0)
	s_setprio 1
	s_barrier
	v_mfma_f32_16x16x32_bf16 v[62:65], v[132:135], v[164:167], v[62:65]
	v_mfma_f32_16x16x32_bf16 v[58:61], v[140:143], v[164:167], v[58:61]
	v_mfma_f32_16x16x32_bf16 v[46:49], v[132:135], v[172:175], v[46:49]
	v_mfma_f32_16x16x32_bf16 v[42:45], v[140:143], v[172:175], v[42:45]
	v_mfma_f32_16x16x32_bf16 v[30:33], v[132:135], v[180:183], v[30:33]
	v_mfma_f32_16x16x32_bf16 v[26:29], v[140:143], v[180:183], v[26:29]
	v_mfma_f32_16x16x32_bf16 v[14:17], v[132:135], v[188:191], v[14:17]
	v_mfma_f32_16x16x32_bf16 v[10:13], v[140:143], v[188:191], v[10:13]
	v_mfma_f32_16x16x32_bf16 v[62:65], v[136:139], v[168:171], v[62:65]
	v_mfma_f32_16x16x32_bf16 v[58:61], v[144:147], v[168:171], v[58:61]
	v_mfma_f32_16x16x32_bf16 v[46:49], v[136:139], v[176:179], v[46:49]
	v_mfma_f32_16x16x32_bf16 v[42:45], v[144:147], v[176:179], v[42:45]
	v_mfma_f32_16x16x32_bf16 v[30:33], v[136:139], v[184:187], v[30:33]
	v_mfma_f32_16x16x32_bf16 v[26:29], v[144:147], v[184:187], v[26:29]
	v_mfma_f32_16x16x32_bf16 v[14:17], v[136:139], v[230:233], v[14:17]
	v_mfma_f32_16x16x32_bf16 v[10:13], v[144:147], v[230:233], v[10:13]
	v_mfma_f32_16x16x32_bf16 v[54:57], v[148:151], v[164:167], v[54:57]
	v_mfma_f32_16x16x32_bf16 v[50:53], v[156:159], v[164:167], v[50:53]
	v_mfma_f32_16x16x32_bf16 v[38:41], v[148:151], v[172:175], v[38:41]
	v_mfma_f32_16x16x32_bf16 v[34:37], v[156:159], v[172:175], v[34:37]
	v_mfma_f32_16x16x32_bf16 v[22:25], v[148:151], v[180:183], v[22:25]
	v_mfma_f32_16x16x32_bf16 v[18:21], v[156:159], v[180:183], v[18:21]
	v_mfma_f32_16x16x32_bf16 v[6:9], v[148:151], v[188:191], v[6:9]
	v_mfma_f32_16x16x32_bf16 v[2:5], v[156:159], v[188:191], v[2:5]
	v_mfma_f32_16x16x32_bf16 v[54:57], v[152:155], v[168:171], v[54:57]
	v_mfma_f32_16x16x32_bf16 v[50:53], v[160:163], v[168:171], v[50:53]
	v_mfma_f32_16x16x32_bf16 v[38:41], v[152:155], v[176:179], v[38:41]
	v_mfma_f32_16x16x32_bf16 v[34:37], v[160:163], v[176:179], v[34:37]
	v_mfma_f32_16x16x32_bf16 v[22:25], v[152:155], v[184:187], v[22:25]
	v_mfma_f32_16x16x32_bf16 v[18:21], v[160:163], v[184:187], v[18:21]
	v_mfma_f32_16x16x32_bf16 v[6:9], v[152:155], v[230:233], v[6:9]
	v_mfma_f32_16x16x32_bf16 v[2:5], v[160:163], v[230:233], v[2:5]
	s_setprio 0
	s_barrier
	s_mov_b32 vcc_lo, 0
	s_mov_b64 s[78:79], 0x18180
; #define PG8_STAGEA(bufoff, goff, voff) PG8_STAGEX(rsA, bufoff, goff, voff)
; #define PG8_STAGEB(bufoff, goff, voff) PG8_STAGEX(rsB, bufoff, goff, voff)
; #define PG8_LDA(dst, b, h) do { _Pragma("unroll") for (int m = 0; m < 4; ++m) _Pragma("unroll") for (int k = 0; k < 2; ++k) dst[m][k] = *(const PG8_LAS bf16x8*)(lds + PG8_SA(b, h) + aoff + m * 2048 + k * 1024); } while (0)
; #define PG8_LDB(dst, b, h) do { _Pragma("unroll") for (int n = 0; n < 2; ++n) _Pragma("unroll") for (int k = 0; k < 2; ++k) dst[n][k] = *(const PG8_LAS bf16x8*)(lds + PG8_SB(b, h) + boff + n * 2048 + k * 1024); } while (0)
; #define PG8_MMA(ai, bj, At, Bt) do { __builtin_amdgcn_s_setprio(1); _Pragma("unroll") for (int m = 0; m < 4; ++m) _Pragma("unroll") for (int n = 0; n < 2; ++n) _Pragma("unroll") for (int k = 0; k < 2; ++k) \
;         acc[ai][bj][m][n] = __builtin_amdgcn_mfma_f32_16x16x32_bf16(Bt[n][k], At[m][k], acc[ai][bj][m][n], 0, 0, 0); __builtin_amdgcn_s_setprio(0); } while (0)
; #define PG8_WAIT_V(n) asm volatile("s_waitcnt vmcnt(" #n ")" ::: "memory")
; #define PG8_WAIT_L(n) asm volatile("s_waitcnt lgkmcnt(" #n ")" ::: "memory")
; #define PG8_BAR __builtin_amdgcn_s_barrier()
; #define PG8_SCHED __builtin_amdgcn_sched_barrier(0)
; template <class Epi, class Sched, bool ALIGN_EPI = false, bool SP2 = false>
; __device__ __forceinline__ void gemm_phase(PG8_LAS unsigned char* lds, const Gemm g, const Sched& S, const Epi& E) {
;     ...
;             PG8_LDB(B0, 0, 0); PG8_LDB(B1, 0, 1); PG8_SCHED; PG8_LDA(At, 0, 0); PG8_STAGEA(PG8_SA(1, 1), a1 + hstep, voffA);
;             if (t == 0 && ui > 0) {
; #pragma unroll
;                 for (int a = 0; a < 2; ++a)
; #pragma unroll
;                     for (int b = 0; b < 2; ++b)
; #pragma unroll
;                         for (int m = 0; m < 4; ++m)
; #pragma unroll
;                             for (int n = 0; n < 2; ++n) acc[a][b][m][n] = (f32x4){0.f, 0.f, 0.f, 0.f}; }
;             PG8_WAIT_V(8); PG8_WAIT_L(0); PG8_BAR; PG8_MMA(0, 0, At, B0); PG8_MMA(0, 1, At, B1); PG8_BAR; PG8_SCHED;
;             PG8_LDA(At, 0, 1); PG8_STAGEB(PG8_SB(0, 0), b2, voffB); PG8_STAGEB(PG8_SB(0, 1), b2 + hstep, voffB); PG8_STAGEA(PG8_SA(0, 0), a2, voffA);
;             PG8_WAIT_V(8); PG8_WAIT_L(0); PG8_BAR; PG8_MMA(1, 0, At, B0); PG8_MMA(1, 1, At, B1); PG8_BAR; PG8_SCHED;
.LBB0_479:
	ds_read_b128 v[132:135], v228
	ds_read_b128 v[136:139], v228 offset:1024
	ds_read_b128 v[140:143], v228 offset:2048
	ds_read_b128 v[144:147], v228 offset:3072
	ds_read_b128 v[148:151], v229
	ds_read_b128 v[152:155], v229 offset:1024
	ds_read_b128 v[156:159], v229 offset:2048
	ds_read_b128 v[160:163], v229 offset:3072
	s_mov_b32 m0, s92
	s_add_i32 vcc_hi, s38, s78
	ds_read_b128 v[164:167], v227
	ds_read_b128 v[168:171], v227 offset:1024
	ds_read_b128 v[172:175], v227 offset:2048
	ds_read_b128 v[176:179], v227 offset:3072
	ds_read_b128 v[180:183], v227 offset:4096
	ds_read_b128 v[184:187], v227 offset:5120
	ds_read_b128 v[188:191], v227 offset:6144
	ds_read_b128 v[230:233], v227 offset:7168
	buffer_load_dwordx4 v212, s[12:15], vcc_hi offen lds
	s_mov_b32 m0, s93
	s_add_i32 s41, s34, s78
	buffer_load_dwordx4 v213, s[12:15], vcc_hi offen lds
	s_waitcnt vmcnt(8)
	s_waitcnt lgkmcnt(0)
	s_add_i32 s41, s41, 0xfffe8080
	s_add_i32 vcc_hi, vcc_hi, 0xfffe8080
	s_cmp_eq_u32 vcc_lo, 2
	s_setprio 1
	s_barrier
	v_mfma_f32_16x16x32_bf16 v[126:129], v[132:135], v[164:167], v[126:129]
	v_mfma_f32_16x16x32_bf16 v[122:125], v[140:143], v[164:167], v[122:125]
	v_mfma_f32_16x16x32_bf16 v[110:113], v[132:135], v[172:175], v[110:113]
	v_mfma_f32_16x16x32_bf16 v[106:109], v[140:143], v[172:175], v[106:109]
	v_mfma_f32_16x16x32_bf16 v[94:97], v[132:135], v[180:183], v[94:97]
	v_mfma_f32_16x16x32_bf16 v[90:93], v[140:143], v[180:183], v[90:93]
	v_mfma_f32_16x16x32_bf16 v[78:81], v[132:135], v[188:191], v[78:81]
	v_mfma_f32_16x16x32_bf16 v[74:77], v[140:143], v[188:191], v[74:77]
	v_mfma_f32_16x16x32_bf16 v[126:129], v[136:139], v[168:171], v[126:129]
	v_mfma_f32_16x16x32_bf16 v[122:125], v[144:147], v[168:171], v[122:125]
	v_mfma_f32_16x16x32_bf16 v[110:113], v[136:139], v[176:179], v[110:113]
	v_mfma_f32_16x16x32_bf16 v[106:109], v[144:147], v[176:179], v[106:109]
	v_mfma_f32_16x16x32_bf16 v[94:97], v[136:139], v[184:187], v[94:97]
	v_mfma_f32_16x16x32_bf16 v[90:93], v[144:147], v[184:187], v[90:93]
	v_mfma_f32_16x16x32_bf16 v[78:81], v[136:139], v[230:233], v[78:81]
	v_mfma_f32_16x16x32_bf16 v[74:77], v[144:147], v[230:233], v[74:77]
	v_mfma_f32_16x16x32_bf16 v[118:121], v[148:151], v[164:167], v[118:121]
	v_mfma_f32_16x16x32_bf16 v[114:117], v[156:159], v[164:167], v[114:117]
	v_mfma_f32_16x16x32_bf16 v[102:105], v[148:151], v[172:175], v[102:105]
	v_mfma_f32_16x16x32_bf16 v[98:101], v[156:159], v[172:175], v[98:101]
	v_mfma_f32_16x16x32_bf16 v[86:89], v[148:151], v[180:183], v[86:89]
	v_mfma_f32_16x16x32_bf16 v[82:85], v[156:159], v[180:183], v[82:85]
	v_mfma_f32_16x16x32_bf16 v[70:73], v[148:151], v[188:191], v[70:73]
	v_mfma_f32_16x16x32_bf16 v[66:69], v[156:159], v[188:191], v[66:69]
	v_mfma_f32_16x16x32_bf16 v[118:121], v[152:155], v[168:171], v[118:121]
	v_mfma_f32_16x16x32_bf16 v[114:117], v[160:163], v[168:171], v[114:117]
	v_mfma_f32_16x16x32_bf16 v[102:105], v[152:155], v[176:179], v[102:105]
	v_mfma_f32_16x16x32_bf16 v[98:101], v[160:163], v[176:179], v[98:101]
	v_mfma_f32_16x16x32_bf16 v[86:89], v[152:155], v[184:187], v[86:89]
	v_mfma_f32_16x16x32_bf16 v[82:85], v[160:163], v[184:187], v[82:85]
	v_mfma_f32_16x16x32_bf16 v[70:73], v[152:155], v[230:233], v[70:73]
	v_mfma_f32_16x16x32_bf16 v[66:69], v[160:163], v[230:233], v[66:69]
	s_setprio 0
	s_barrier
	s_mov_b32 m0, s59
	s_cselect_b32 s30, s76, s41
	ds_read_b128 v[164:167], v227 offset:16384
	ds_read_b128 v[168:171], v227 offset:17408
	ds_read_b128 v[172:175], v227 offset:18432
	ds_read_b128 v[176:179], v227 offset:19456
	ds_read_b128 v[180:183], v227 offset:20480
	ds_read_b128 v[184:187], v227 offset:21504
	ds_read_b128 v[188:191], v227 offset:22528
	ds_read_b128 v[230:233], v227 offset:23552
	buffer_load_dwordx4 v212, s[68:71], s30 offen lds
	s_mov_b32 m0, s65
	s_cselect_b32 vcc_hi, s72, vcc_hi
	buffer_load_dwordx4 v213, s[68:71], s30 offen lds
	s_add_i32 s41, s30, 0x18000
	s_mov_b32 m0, s80
	s_nop 0
	buffer_load_dwordx4 v212, s[68:71], s41 offen lds
	s_mov_b32 m0, s81
	s_nop 0
	buffer_load_dwordx4 v213, s[68:71], s41 offen lds
	s_mov_b32 m0, s58
	s_nop 0
	buffer_load_dwordx4 v212, s[12:15], vcc_hi offen lds
	s_mov_b32 m0, s82
	s_nop 0
	buffer_load_dwordx4 v213, s[12:15], vcc_hi offen lds
	s_waitcnt vmcnt(8)
	s_waitcnt lgkmcnt(0)
	s_setprio 1
	s_barrier
	v_mfma_f32_16x16x32_bf16 v[62:65], v[132:135], v[164:167], v[62:65]
	v_mfma_f32_16x16x32_bf16 v[58:61], v[140:143], v[164:167], v[58:61]
	v_mfma_f32_16x16x32_bf16 v[46:49], v[132:135], v[172:175], v[46:49]
	v_mfma_f32_16x16x32_bf16 v[42:45], v[140:143], v[172:175], v[42:45]
	v_mfma_f32_16x16x32_bf16 v[30:33], v[132:135], v[180:183], v[30:33]
	v_mfma_f32_16x16x32_bf16 v[26:29], v[140:143], v[180:183], v[26:29]
	v_mfma_f32_16x16x32_bf16 v[14:17], v[132:135], v[188:191], v[14:17]
	v_mfma_f32_16x16x32_bf16 v[10:13], v[140:143], v[188:191], v[10:13]
	v_mfma_f32_16x16x32_bf16 v[62:65], v[136:139], v[168:171], v[62:65]
	v_mfma_f32_16x16x32_bf16 v[58:61], v[144:147], v[168:171], v[58:61]
	v_mfma_f32_16x16x32_bf16 v[46:49], v[136:139], v[176:179], v[46:49]
	v_mfma_f32_16x16x32_bf16 v[42:45], v[144:147], v[176:179], v[42:45]
	v_mfma_f32_16x16x32_bf16 v[30:33], v[136:139], v[184:187], v[30:33]
	v_mfma_f32_16x16x32_bf16 v[26:29], v[144:147], v[184:187], v[26:29]
	v_mfma_f32_16x16x32_bf16 v[14:17], v[136:139], v[230:233], v[14:17]
	v_mfma_f32_16x16x32_bf16 v[10:13], v[144:147], v[230:233], v[10:13]
	v_mfma_f32_16x16x32_bf16 v[54:57], v[148:151], v[164:167], v[54:57]
	v_mfma_f32_16x16x32_bf16 v[50:53], v[156:159], v[164:167], v[50:53]
	v_mfma_f32_16x16x32_bf16 v[38:41], v[148:151], v[172:175], v[38:41]
	v_mfma_f32_16x16x32_bf16 v[34:37], v[156:159], v[172:175], v[34:37]
	v_mfma_f32_16x16x32_bf16 v[22:25], v[148:151], v[180:183], v[22:25]
	v_mfma_f32_16x16x32_bf16 v[18:21], v[156:159], v[180:183], v[18:21]
	v_mfma_f32_16x16x32_bf16 v[6:9], v[148:151], v[188:191], v[6:9]
	v_mfma_f32_16x16x32_bf16 v[2:5], v[156:159], v[188:191], v[2:5]
	v_mfma_f32_16x16x32_bf16 v[54:57], v[152:155], v[168:171], v[54:57]
	v_mfma_f32_16x16x32_bf16 v[50:53], v[160:163], v[168:171], v[50:53]
	v_mfma_f32_16x16x32_bf16 v[38:41], v[152:155], v[176:179], v[38:41]
	v_mfma_f32_16x16x32_bf16 v[34:37], v[160:163], v[176:179], v[34:37]
	v_mfma_f32_16x16x32_bf16 v[22:25], v[152:155], v[184:187], v[22:25]
	v_mfma_f32_16x16x32_bf16 v[18:21], v[160:163], v[184:187], v[18:21]
	v_mfma_f32_16x16x32_bf16 v[6:9], v[152:155], v[230:233], v[6:9]
	v_mfma_f32_16x16x32_bf16 v[2:5], v[160:163], v[230:233], v[2:5]
	s_setprio 0
	s_barrier
; #define PG8_STAGEA(bufoff, goff, voff) PG8_STAGEX(rsA, bufoff, goff, voff)
; #define PG8_STAGEB(bufoff, goff, voff) PG8_STAGEX(rsB, bufoff, goff, voff)
; #define PG8_LDA(dst, b, h) do { _Pragma("unroll") for (int m = 0; m < 4; ++m) _Pragma("unroll") for (int k = 0; k < 2; ++k) dst[m][k] = *(const PG8_LAS bf16x8*)(lds + PG8_SA(b, h) + aoff + m * 2048 + k * 1024); } while (0)
; #define PG8_LDB(dst, b, h) do { _Pragma("unroll") for (int n = 0; n < 2; ++n) _Pragma("unroll") for (int k = 0; k < 2; ++k) dst[n][k] = *(const PG8_LAS bf16x8*)(lds + PG8_SB(b, h) + boff + n * 2048 + k * 1024); } while (0)
; #define PG8_MMA(ai, bj, At, Bt) do { __builtin_amdgcn_s_setprio(1); _Pragma("unroll") for (int m = 0; m < 4; ++m) _Pragma("unroll") for (int n = 0; n < 2; ++n) _Pragma("unroll") for (int k = 0; k < 2; ++k) \
;         acc[ai][bj][m][n] = __builtin_amdgcn_mfma_f32_16x16x32_bf16(Bt[n][k], At[m][k], acc[ai][bj][m][n], 0, 0, 0); __builtin_amdgcn_s_setprio(0); } while (0)
; #define PG8_WAIT_V(n) asm volatile("s_waitcnt vmcnt(" #n ")" ::: "memory")
; #define PG8_WAIT_L(n) asm volatile("s_waitcnt lgkmcnt(" #n ")" ::: "memory")
; #define PG8_BAR __builtin_amdgcn_s_barrier()
; #define PG8_SCHED __builtin_amdgcn_sched_barrier(0)
; template <class Epi, class Sched, bool ALIGN_EPI = false, bool SP2 = false>
; __device__ __forceinline__ void gemm_phase(PG8_LAS unsigned char* lds, const Gemm g, const Sched& S, const Epi& E) {
;     ...
;             PG8_LDB(B0, 1, 0); PG8_LDB(B1, 1, 1); PG8_SCHED; PG8_LDA(At, 1, 0); PG8_STAGEA(PG8_SA(0, 1), a2 + hstep, voffA);
;             PG8_WAIT_V(8); PG8_WAIT_L(0); PG8_BAR; PG8_MMA(0, 0, At, B0); PG8_MMA(0, 1, At, B1); PG8_BAR; PG8_SCHED;
;             PG8_LDA(At, 1, 1); PG8_STAGEB(PG8_SB(1, 0), b3, voffB); PG8_STAGEB(PG8_SB(1, 1), b3 + hstep, voffB); PG8_STAGEA(PG8_SA(1, 0), a3, voffA);
;             PG8_WAIT_V(8); PG8_WAIT_L(0); PG8_BAR; PG8_MMA(1, 0, At, B0); PG8_MMA(1, 1, At, B1); PG8_BAR; PG8_SCHED;
;     ...
;         if (!has_next) break;
;         cur = nxt; cA = nA; cB = nB; ++ui;
	ds_read_b128 v[132:135], v130
	ds_read_b128 v[136:139], v130 offset:1024
	ds_read_b128 v[140:143], v130 offset:2048
	ds_read_b128 v[144:147], v130 offset:3072
	ds_read_b128 v[148:151], v131
	ds_read_b128 v[152:155], v131 offset:1024
	ds_read_b128 v[156:159], v131 offset:2048
	ds_read_b128 v[160:163], v131 offset:3072
	s_add_i32 s41, vcc_hi, 0x18000
	s_mov_b32 m0, s83
	ds_read_b128 v[164:167], v227 offset:32768
	ds_read_b128 v[168:171], v227 offset:33792
	ds_read_b128 v[172:175], v227 offset:34816
	ds_read_b128 v[176:179], v227 offset:35840
	ds_read_b128 v[180:183], v227 offset:36864
	ds_read_b128 v[184:187], v227 offset:37888
	ds_read_b128 v[188:191], v227 offset:38912
	ds_read_b128 v[230:233], v227 offset:39936
	buffer_load_dwordx4 v212, s[12:15], s41 offen lds
	s_mov_b32 m0, s84
	s_nop 0
	buffer_load_dwordx4 v213, s[12:15], s41 offen lds
	s_waitcnt vmcnt(8)
	s_waitcnt lgkmcnt(0)
	s_setprio 1
	s_barrier
	v_mfma_f32_16x16x32_bf16 v[126:129], v[132:135], v[164:167], v[126:129]
	v_mfma_f32_16x16x32_bf16 v[122:125], v[140:143], v[164:167], v[122:125]
	v_mfma_f32_16x16x32_bf16 v[110:113], v[132:135], v[172:175], v[110:113]
	v_mfma_f32_16x16x32_bf16 v[106:109], v[140:143], v[172:175], v[106:109]
	v_mfma_f32_16x16x32_bf16 v[94:97], v[132:135], v[180:183], v[94:97]
	v_mfma_f32_16x16x32_bf16 v[90:93], v[140:143], v[180:183], v[90:93]
	v_mfma_f32_16x16x32_bf16 v[78:81], v[132:135], v[188:191], v[78:81]
	v_mfma_f32_16x16x32_bf16 v[74:77], v[140:143], v[188:191], v[74:77]
	v_mfma_f32_16x16x32_bf16 v[126:129], v[136:139], v[168:171], v[126:129]
	v_mfma_f32_16x16x32_bf16 v[122:125], v[144:147], v[168:171], v[122:125]
	v_mfma_f32_16x16x32_bf16 v[110:113], v[136:139], v[176:179], v[110:113]
	v_mfma_f32_16x16x32_bf16 v[106:109], v[144:147], v[176:179], v[106:109]
	v_mfma_f32_16x16x32_bf16 v[94:97], v[136:139], v[184:187], v[94:97]
	v_mfma_f32_16x16x32_bf16 v[90:93], v[144:147], v[184:187], v[90:93]
	v_mfma_f32_16x16x32_bf16 v[78:81], v[136:139], v[230:233], v[78:81]
	v_mfma_f32_16x16x32_bf16 v[74:77], v[144:147], v[230:233], v[74:77]
	v_mfma_f32_16x16x32_bf16 v[118:121], v[148:151], v[164:167], v[118:121]
	v_mfma_f32_16x16x32_bf16 v[114:117], v[156:159], v[164:167], v[114:117]
	v_mfma_f32_16x16x32_bf16 v[102:105], v[148:151], v[172:175], v[102:105]
	v_mfma_f32_16x16x32_bf16 v[98:101], v[156:159], v[172:175], v[98:101]
	v_mfma_f32_16x16x32_bf16 v[86:89], v[148:151], v[180:183], v[86:89]
	v_mfma_f32_16x16x32_bf16 v[82:85], v[156:159], v[180:183], v[82:85]
	v_mfma_f32_16x16x32_bf16 v[70:73], v[148:151], v[188:191], v[70:73]
	v_mfma_f32_16x16x32_bf16 v[66:69], v[156:159], v[188:191], v[66:69]
	v_mfma_f32_16x16x32_bf16 v[118:121], v[152:155], v[168:171], v[118:121]
	v_mfma_f32_16x16x32_bf16 v[114:117], v[160:163], v[168:171], v[114:117]
	v_mfma_f32_16x16x32_bf16 v[102:105], v[152:155], v[176:179], v[102:105]
	v_mfma_f32_16x16x32_bf16 v[98:101], v[160:163], v[176:179], v[98:101]
	v_mfma_f32_16x16x32_bf16 v[86:89], v[152:155], v[184:187], v[86:89]
	v_mfma_f32_16x16x32_bf16 v[82:85], v[160:163], v[184:187], v[82:85]
	v_mfma_f32_16x16x32_bf16 v[70:73], v[152:155], v[230:233], v[70:73]
	v_mfma_f32_16x16x32_bf16 v[66:69], v[160:163], v[230:233], v[66:69]
	s_setprio 0
	s_barrier
	s_mov_b32 m0, s85
	s_add_i32 s41, s30, 0x80
	ds_read_b128 v[164:167], v227 offset:49152
	ds_read_b128 v[168:171], v227 offset:50176
	ds_read_b128 v[172:175], v227 offset:51200
	ds_read_b128 v[176:179], v227 offset:52224
	ds_read_b128 v[180:183], v227 offset:53248
	ds_read_b128 v[184:187], v227 offset:54272
	ds_read_b128 v[188:191], v227 offset:55296
	ds_read_b128 v[230:233], v227 offset:56320
	buffer_load_dwordx4 v212, s[68:71], s41 offen lds
	s_mov_b32 m0, s87
	s_add_i32 s30, s30, 0x18080
	buffer_load_dwordx4 v213, s[68:71], s41 offen lds
	s_mov_b32 m0, s90
	s_addk_i32 vcc_hi, 0x80
	buffer_load_dwordx4 v212, s[68:71], s30 offen lds
	s_mov_b32 m0, s91
	s_nop 0
	buffer_load_dwordx4 v213, s[68:71], s30 offen lds
	s_mov_b32 m0, s88
	s_nop 0
	buffer_load_dwordx4 v212, s[12:15], vcc_hi offen lds
	s_mov_b32 m0, s89
	s_nop 0
	buffer_load_dwordx4 v213, s[12:15], vcc_hi offen lds
	s_waitcnt vmcnt(8)
	s_waitcnt lgkmcnt(0)
	s_setprio 1
	s_barrier
	v_mfma_f32_16x16x32_bf16 v[62:65], v[132:135], v[164:167], v[62:65]
	v_mfma_f32_16x16x32_bf16 v[58:61], v[140:143], v[164:167], v[58:61]
	v_mfma_f32_16x16x32_bf16 v[46:49], v[132:135], v[172:175], v[46:49]
	v_mfma_f32_16x16x32_bf16 v[42:45], v[140:143], v[172:175], v[42:45]
	v_mfma_f32_16x16x32_bf16 v[30:33], v[132:135], v[180:183], v[30:33]
	v_mfma_f32_16x16x32_bf16 v[26:29], v[140:143], v[180:183], v[26:29]
	v_mfma_f32_16x16x32_bf16 v[14:17], v[132:135], v[188:191], v[14:17]
	v_mfma_f32_16x16x32_bf16 v[10:13], v[140:143], v[188:191], v[10:13]
	v_mfma_f32_16x16x32_bf16 v[62:65], v[136:139], v[168:171], v[62:65]
	v_mfma_f32_16x16x32_bf16 v[58:61], v[144:147], v[168:171], v[58:61]
	v_mfma_f32_16x16x32_bf16 v[46:49], v[136:139], v[176:179], v[46:49]
	v_mfma_f32_16x16x32_bf16 v[42:45], v[144:147], v[176:179], v[42:45]
	v_mfma_f32_16x16x32_bf16 v[30:33], v[136:139], v[184:187], v[30:33]
	v_mfma_f32_16x16x32_bf16 v[26:29], v[144:147], v[184:187], v[26:29]
	v_mfma_f32_16x16x32_bf16 v[14:17], v[136:139], v[230:233], v[14:17]
	v_mfma_f32_16x16x32_bf16 v[10:13], v[144:147], v[230:233], v[10:13]
	v_mfma_f32_16x16x32_bf16 v[54:57], v[148:151], v[164:167], v[54:57]
	v_mfma_f32_16x16x32_bf16 v[50:53], v[156:159], v[164:167], v[50:53]
	v_mfma_f32_16x16x32_bf16 v[38:41], v[148:151], v[172:175], v[38:41]
	v_mfma_f32_16x16x32_bf16 v[34:37], v[156:159], v[172:175], v[34:37]
	v_mfma_f32_16x16x32_bf16 v[22:25], v[148:151], v[180:183], v[22:25]
	v_mfma_f32_16x16x32_bf16 v[18:21], v[156:159], v[180:183], v[18:21]
	v_mfma_f32_16x16x32_bf16 v[6:9], v[148:151], v[188:191], v[6:9]
	v_mfma_f32_16x16x32_bf16 v[2:5], v[156:159], v[188:191], v[2:5]
	v_mfma_f32_16x16x32_bf16 v[54:57], v[152:155], v[168:171], v[54:57]
	v_mfma_f32_16x16x32_bf16 v[50:53], v[160:163], v[168:171], v[50:53]
	v_mfma_f32_16x16x32_bf16 v[38:41], v[152:155], v[176:179], v[38:41]
	v_mfma_f32_16x16x32_bf16 v[34:37], v[160:163], v[176:179], v[34:37]
	v_mfma_f32_16x16x32_bf16 v[22:25], v[152:155], v[184:187], v[22:25]
	v_mfma_f32_16x16x32_bf16 v[18:21], v[160:163], v[184:187], v[18:21]
	v_mfma_f32_16x16x32_bf16 v[6:9], v[152:155], v[230:233], v[6:9]
	v_mfma_f32_16x16x32_bf16 v[2:5], v[160:163], v[230:233], v[2:5]
	s_setprio 0
	s_barrier
	s_add_i32 vcc_lo, vcc_lo, 2
	s_add_u32 s78, s78, 0x100
	s_addc_u32 s79, s79, 0
	s_cmp_gt_u32 vcc_lo, 3
	s_cbranch_scc0 .LBB0_479
	s_and_b64 vcc, exec, s[74:75]
	s_cbranch_vccz .LBB0_471
	s_mov_b32 s61, s97
	s_mov_b32 s86, s96
	s_mov_b64 s[34:35], s[76:77]
	s_mov_b64 s[38:39], s[72:73]
	s_mov_b32 s94, s95
	s_branch .LBB0_471

; #define PG8_STAGEA(bufoff, goff, voff) PG8_STAGEX(rsA, bufoff, goff, voff)
; #define PG8_STAGEB(bufoff, goff, voff) PG8_STAGEX(rsB, bufoff, goff, voff)
; #define PG8_LDA(dst, b, h) do { _Pragma("unroll") for (int m = 0; m < 4; ++m) _Pragma("unroll") for (int k = 0; k < 2; ++k) dst[m][k] = *(const PG8_LAS bf16x8*)(lds + PG8_SA(b, h) + aoff + m * 2048 + k * 1024); } while (0)
; #define PG8_MMA(ai, bj, At, Bt) do { __builtin_amdgcn_s_setprio(1); _Pragma("unroll") for (int m = 0; m < 4; ++m) _Pragma("unroll") for (int n = 0; n < 2; ++n) _Pragma("unroll") for (int k = 0; k < 2; ++k) \
;         acc[ai][bj][m][n] = __builtin_amdgcn_mfma_f32_16x16x32_bf16(Bt[n][k], At[m][k], acc[ai][bj][m][n], 0, 0, 0); __builtin_amdgcn_s_setprio(0); } while (0)
; #define PG8_WAIT_V(n) asm volatile("s_waitcnt vmcnt(" #n ")" ::: "memory")
; #define PG8_WAIT_L(n) asm volatile("s_waitcnt lgkmcnt(" #n ")" ::: "memory")
; #define PG8_BAR __builtin_amdgcn_s_barrier()
; #define PG8_SCHED __builtin_amdgcn_sched_barrier(0)
; template <class Epi, class Sched, bool ALIGN_EPI = false, bool SP2 = false>
; __device__ __forceinline__ void gemm_phase(PG8_LAS unsigned char* lds, const Gemm g, const Sched& S, const Epi& E) {
;     ...
;         const size_t nA = has_next ? (size_t)nxt.pm * tstep : cA; const size_t nB = has_next ? (size_t)nxt.pn * tstep : cB;
;         for (int t = 0; t < nt; t += 2) {
;             const bool last = (t == nt - 2);
;             if constexpr (Epi::MIDK) { if (t == (nt >> 1)) E.midk(acc, wr, fr, lds); }
;             const size_t a1 = cA + (size_t)(t + 1) * kstep;
;             const size_t a2 = last ? nA : cA + (size_t)(t + 2) * kstep; const size_t b2 = last ? nB : cB + (size_t)(t + 2) * kstep;
;     ...
;             PG8_WAIT_V(8); PG8_WAIT_L(0); PG8_BAR; PG8_MMA(0, 0, At, B0); PG8_MMA(0, 1, At, B1); PG8_BAR; PG8_SCHED;
;             PG8_LDA(At, 0, 1); PG8_STAGEB(PG8_SB(0, 0), b2, voffB); PG8_STAGEB(PG8_SB(0, 1), b2 + hstep, voffB); PG8_STAGEA(PG8_SA(0, 0), a2, voffA);
;             PG8_WAIT_V(8); PG8_WAIT_L(0); PG8_BAR; PG8_MMA(1, 0, At, B0); PG8_MMA(1, 1, At, B1); PG8_BAR; PG8_SCHED;
.LBB0_630:
	s_ashr_i32 s31, s30, 31
	s_lshl_b64 s[34:35], s[30:31], 20
	s_and_b64 s[38:39], vcc, exec
	s_cselect_b32 s21, s34, s20
	s_ashr_i32 s23, s22, 31
	s_waitcnt vmcnt(8)
	s_lshl_b64 s[38:39], s[22:23], 20
	s_waitcnt lgkmcnt(0)
	s_and_b64 s[42:43], vcc, exec
	s_cselect_b32 s23, s38, s18
	s_add_u32 s31, s18, 0x200
	s_setprio 1
	s_barrier
	v_mfma_f32_16x16x32_bf16 v[126:129], v[146:149], v[186:189], v[126:129]
	v_mfma_f32_16x16x32_bf16 v[122:125], v[154:157], v[186:189], v[122:125]
	v_mfma_f32_16x16x32_bf16 v[110:113], v[146:149], v[178:181], v[110:113]
	v_mfma_f32_16x16x32_bf16 v[106:109], v[154:157], v[178:181], v[106:109]
	v_mfma_f32_16x16x32_bf16 v[94:97], v[146:149], v[170:173], v[94:97]
	v_mfma_f32_16x16x32_bf16 v[90:93], v[154:157], v[170:173], v[90:93]
	v_mfma_f32_16x16x32_bf16 v[78:81], v[146:149], v[162:165], v[78:81]
	v_mfma_f32_16x16x32_bf16 v[74:77], v[154:157], v[162:165], v[74:77]
	v_mfma_f32_16x16x32_bf16 v[126:129], v[150:153], v[190:193], v[126:129]
	v_mfma_f32_16x16x32_bf16 v[122:125], v[158:161], v[190:193], v[122:125]
	v_mfma_f32_16x16x32_bf16 v[110:113], v[150:153], v[182:185], v[110:113]
	v_mfma_f32_16x16x32_bf16 v[106:109], v[158:161], v[182:185], v[106:109]
	v_mfma_f32_16x16x32_bf16 v[94:97], v[150:153], v[174:177], v[94:97]
	v_mfma_f32_16x16x32_bf16 v[90:93], v[158:161], v[174:177], v[90:93]
	v_mfma_f32_16x16x32_bf16 v[78:81], v[150:153], v[166:169], v[78:81]
	v_mfma_f32_16x16x32_bf16 v[74:77], v[158:161], v[166:169], v[74:77]
	v_mfma_f32_16x16x32_bf16 v[118:121], v[130:133], v[186:189], v[118:121]
	v_mfma_f32_16x16x32_bf16 v[114:117], v[138:141], v[186:189], v[114:117]
	v_mfma_f32_16x16x32_bf16 v[102:105], v[130:133], v[178:181], v[102:105]
	v_mfma_f32_16x16x32_bf16 v[98:101], v[138:141], v[178:181], v[98:101]
	v_mfma_f32_16x16x32_bf16 v[86:89], v[130:133], v[170:173], v[86:89]
	v_mfma_f32_16x16x32_bf16 v[82:85], v[138:141], v[170:173], v[82:85]
	v_mfma_f32_16x16x32_bf16 v[70:73], v[130:133], v[162:165], v[70:73]
	v_mfma_f32_16x16x32_bf16 v[66:69], v[138:141], v[162:165], v[66:69]
	v_mfma_f32_16x16x32_bf16 v[118:121], v[134:137], v[190:193], v[118:121]
	v_mfma_f32_16x16x32_bf16 v[114:117], v[142:145], v[190:193], v[114:117]
	v_mfma_f32_16x16x32_bf16 v[102:105], v[134:137], v[182:185], v[102:105]
	v_mfma_f32_16x16x32_bf16 v[98:101], v[142:145], v[182:185], v[98:101]
	v_mfma_f32_16x16x32_bf16 v[86:89], v[134:137], v[174:177], v[86:89]
	v_mfma_f32_16x16x32_bf16 v[82:85], v[142:145], v[174:177], v[82:85]
	v_mfma_f32_16x16x32_bf16 v[70:73], v[134:137], v[166:169], v[70:73]
	v_mfma_f32_16x16x32_bf16 v[66:69], v[142:145], v[166:169], v[66:69]
	s_setprio 0
	s_barrier
	s_mov_b32 m0, s46
	s_or_b32 s41, s18, 0x100
	s_mov_b32 s66, s6
	s_mov_b32 s67, s7
	ds_read_b128 v[162:165], v205 offset:16384
	ds_read_b128 v[166:169], v205 offset:17408
	ds_read_b128 v[170:173], v205 offset:18432
	ds_read_b128 v[174:177], v205 offset:19456
	ds_read_b128 v[178:181], v205 offset:20480
	ds_read_b128 v[182:185], v205 offset:21504
	ds_read_b128 v[186:189], v205 offset:22528
	ds_read_b128 v[190:193], v205 offset:23552
	buffer_load_dwordx4 v200, s[64:67], s41 offen lds
	s_mov_b32 m0, s47
	s_nop 0
	buffer_load_dwordx4 v201, s[64:67], s41 offen lds
	s_or_b32 s41, s18, 0x80100
	s_mov_b32 m0, s48
	s_nop 0
	buffer_load_dwordx4 v200, s[64:67], s41 offen lds
	s_mov_b32 m0, s49
	s_nop 0
	buffer_load_dwordx4 v201, s[64:67], s41 offen lds
	s_or_b32 s41, s20, 0x100
	s_mov_b32 m0, s45
	s_nop 0
	buffer_load_dwordx4 v200, s[4:7], s41 offen lds
	s_mov_b32 m0, s50
	s_nop 0
	buffer_load_dwordx4 v201, s[4:7], s41 offen lds
	s_waitcnt vmcnt(8)
	s_waitcnt lgkmcnt(0)
	s_setprio 1
	s_barrier
	v_mfma_f32_16x16x32_bf16 v[62:65], v[146:149], v[162:165], v[62:65]
	v_mfma_f32_16x16x32_bf16 v[58:61], v[154:157], v[162:165], v[58:61]
	v_mfma_f32_16x16x32_bf16 v[46:49], v[146:149], v[170:173], v[46:49]
	v_mfma_f32_16x16x32_bf16 v[42:45], v[154:157], v[170:173], v[42:45]
	v_mfma_f32_16x16x32_bf16 v[30:33], v[146:149], v[178:181], v[30:33]
	v_mfma_f32_16x16x32_bf16 v[26:29], v[154:157], v[178:181], v[26:29]
	v_mfma_f32_16x16x32_bf16 v[14:17], v[146:149], v[186:189], v[14:17]
	v_mfma_f32_16x16x32_bf16 v[10:13], v[154:157], v[186:189], v[10:13]
	v_mfma_f32_16x16x32_bf16 v[62:65], v[150:153], v[166:169], v[62:65]
	v_mfma_f32_16x16x32_bf16 v[58:61], v[158:161], v[166:169], v[58:61]
	v_mfma_f32_16x16x32_bf16 v[46:49], v[150:153], v[174:177], v[46:49]
	v_mfma_f32_16x16x32_bf16 v[42:45], v[158:161], v[174:177], v[42:45]
	v_mfma_f32_16x16x32_bf16 v[30:33], v[150:153], v[182:185], v[30:33]
	v_mfma_f32_16x16x32_bf16 v[26:29], v[158:161], v[182:185], v[26:29]
	v_mfma_f32_16x16x32_bf16 v[14:17], v[150:153], v[190:193], v[14:17]
	v_mfma_f32_16x16x32_bf16 v[10:13], v[158:161], v[190:193], v[10:13]
	v_mfma_f32_16x16x32_bf16 v[54:57], v[130:133], v[162:165], v[54:57]
	v_mfma_f32_16x16x32_bf16 v[50:53], v[138:141], v[162:165], v[50:53]
	v_mfma_f32_16x16x32_bf16 v[38:41], v[130:133], v[170:173], v[38:41]
	v_mfma_f32_16x16x32_bf16 v[34:37], v[138:141], v[170:173], v[34:37]
	v_mfma_f32_16x16x32_bf16 v[22:25], v[130:133], v[178:181], v[22:25]
	v_mfma_f32_16x16x32_bf16 v[18:21], v[138:141], v[178:181], v[18:21]
	v_mfma_f32_16x16x32_bf16 v[6:9], v[130:133], v[186:189], v[6:9]
	v_mfma_f32_16x16x32_bf16 v[2:5], v[138:141], v[186:189], v[2:5]
	v_mfma_f32_16x16x32_bf16 v[54:57], v[134:137], v[166:169], v[54:57]
	v_mfma_f32_16x16x32_bf16 v[50:53], v[142:145], v[166:169], v[50:53]
	v_mfma_f32_16x16x32_bf16 v[38:41], v[134:137], v[174:177], v[38:41]
	v_mfma_f32_16x16x32_bf16 v[34:37], v[142:145], v[174:177], v[34:37]
	v_mfma_f32_16x16x32_bf16 v[22:25], v[134:137], v[182:185], v[22:25]
	v_mfma_f32_16x16x32_bf16 v[18:21], v[142:145], v[182:185], v[18:21]
	v_mfma_f32_16x16x32_bf16 v[6:9], v[134:137], v[190:193], v[6:9]
	v_mfma_f32_16x16x32_bf16 v[2:5], v[142:145], v[190:193], v[2:5]
	s_setprio 0
	s_barrier
; #define PG8_STAGEA(bufoff, goff, voff) PG8_STAGEX(rsA, bufoff, goff, voff)
; #define PG8_STAGEB(bufoff, goff, voff) PG8_STAGEX(rsB, bufoff, goff, voff)
; #define PG8_LDA(dst, b, h) do { _Pragma("unroll") for (int m = 0; m < 4; ++m) _Pragma("unroll") for (int k = 0; k < 2; ++k) dst[m][k] = *(const PG8_LAS bf16x8*)(lds + PG8_SA(b, h) + aoff + m * 2048 + k * 1024); } while (0)
; #define PG8_LDB(dst, b, h) do { _Pragma("unroll") for (int n = 0; n < 2; ++n) _Pragma("unroll") for (int k = 0; k < 2; ++k) dst[n][k] = *(const PG8_LAS bf16x8*)(lds + PG8_SB(b, h) + boff + n * 2048 + k * 1024); } while (0)
; #define PG8_MMA(ai, bj, At, Bt) do { __builtin_amdgcn_s_setprio(1); _Pragma("unroll") for (int m = 0; m < 4; ++m) _Pragma("unroll") for (int n = 0; n < 2; ++n) _Pragma("unroll") for (int k = 0; k < 2; ++k) \
;         acc[ai][bj][m][n] = __builtin_amdgcn_mfma_f32_16x16x32_bf16(Bt[n][k], At[m][k], acc[ai][bj][m][n], 0, 0, 0); __builtin_amdgcn_s_setprio(0); } while (0)
; #define PG8_WAIT_V(n) asm volatile("s_waitcnt vmcnt(" #n ")" ::: "memory")
; #define PG8_WAIT_L(n) asm volatile("s_waitcnt lgkmcnt(" #n ")" ::: "memory")
; #define PG8_BAR __builtin_amdgcn_s_barrier()
; #define PG8_SCHED __builtin_amdgcn_sched_barrier(0)
; template <class Epi, class Sched, bool ALIGN_EPI = false, bool SP2 = false>
; __device__ __forceinline__ void gemm_phase(PG8_LAS unsigned char* lds, const Gemm g, const Sched& S, const Epi& E) {
;     ...
;             PG8_LDB(B0, 1, 0); PG8_LDB(B1, 1, 1); PG8_SCHED; PG8_LDA(At, 1, 0); PG8_STAGEA(PG8_SA(0, 1), a2 + hstep, voffA);
;             PG8_WAIT_V(8); PG8_WAIT_L(0); PG8_BAR; PG8_MMA(0, 0, At, B0); PG8_MMA(0, 1, At, B1); PG8_BAR; PG8_SCHED;
;             PG8_LDA(At, 1, 1); PG8_STAGEB(PG8_SB(1, 0), b3, voffB); PG8_STAGEB(PG8_SB(1, 1), b3 + hstep, voffB); PG8_STAGEA(PG8_SA(1, 0), a3, voffA);
;             PG8_WAIT_V(8); PG8_WAIT_L(0); PG8_BAR; PG8_MMA(1, 0, At, B0); PG8_MMA(1, 1, At, B1); PG8_BAR; PG8_SCHED;
	v_add_u32_e32 v130, 0x18000, v204
	v_add_u32_e32 v131, 0x1c000, v204
	ds_read_b128 v[132:135], v130
	ds_read_b128 v[136:139], v130 offset:1024
	ds_read_b128 v[140:143], v130 offset:2048
	ds_read_b128 v[144:147], v130 offset:3072
	ds_read_b128 v[148:151], v131
	ds_read_b128 v[152:155], v131 offset:1024
	ds_read_b128 v[156:159], v131 offset:2048
	ds_read_b128 v[160:163], v131 offset:3072
	s_or_b32 s41, s20, 0x80100
	s_mov_b32 m0, s51
	ds_read_b128 v[164:167], v205 offset:32768
	ds_read_b128 v[168:171], v205 offset:33792
	ds_read_b128 v[172:175], v205 offset:34816
	ds_read_b128 v[176:179], v205 offset:35840
	ds_read_b128 v[180:183], v205 offset:36864
	ds_read_b128 v[184:187], v205 offset:37888
	ds_read_b128 v[188:191], v205 offset:38912
	ds_read_b128 v[208:211], v205 offset:39936
	buffer_load_dwordx4 v200, s[4:7], s41 offen lds
	s_mov_b32 m0, s56
	s_nop 0
	buffer_load_dwordx4 v201, s[4:7], s41 offen lds
	s_waitcnt vmcnt(8)
	s_waitcnt lgkmcnt(0)
	s_setprio 1
	s_barrier
	v_mfma_f32_16x16x32_bf16 v[126:129], v[132:135], v[164:167], v[126:129]
	v_mfma_f32_16x16x32_bf16 v[122:125], v[140:143], v[164:167], v[122:125]
	v_mfma_f32_16x16x32_bf16 v[110:113], v[132:135], v[172:175], v[110:113]
	v_mfma_f32_16x16x32_bf16 v[106:109], v[140:143], v[172:175], v[106:109]
	v_mfma_f32_16x16x32_bf16 v[94:97], v[132:135], v[180:183], v[94:97]
	v_mfma_f32_16x16x32_bf16 v[90:93], v[140:143], v[180:183], v[90:93]
	v_mfma_f32_16x16x32_bf16 v[78:81], v[132:135], v[188:191], v[78:81]
	v_mfma_f32_16x16x32_bf16 v[74:77], v[140:143], v[188:191], v[74:77]
	v_mfma_f32_16x16x32_bf16 v[126:129], v[136:139], v[168:171], v[126:129]
	v_mfma_f32_16x16x32_bf16 v[122:125], v[144:147], v[168:171], v[122:125]
	v_mfma_f32_16x16x32_bf16 v[110:113], v[136:139], v[176:179], v[110:113]
	v_mfma_f32_16x16x32_bf16 v[106:109], v[144:147], v[176:179], v[106:109]
	v_mfma_f32_16x16x32_bf16 v[94:97], v[136:139], v[184:187], v[94:97]
	v_mfma_f32_16x16x32_bf16 v[90:93], v[144:147], v[184:187], v[90:93]
	v_mfma_f32_16x16x32_bf16 v[78:81], v[136:139], v[208:211], v[78:81]
	v_mfma_f32_16x16x32_bf16 v[74:77], v[144:147], v[208:211], v[74:77]
	v_mfma_f32_16x16x32_bf16 v[118:121], v[148:151], v[164:167], v[118:121]
	v_mfma_f32_16x16x32_bf16 v[114:117], v[156:159], v[164:167], v[114:117]
	v_mfma_f32_16x16x32_bf16 v[102:105], v[148:151], v[172:175], v[102:105]
	v_mfma_f32_16x16x32_bf16 v[98:101], v[156:159], v[172:175], v[98:101]
	v_mfma_f32_16x16x32_bf16 v[86:89], v[148:151], v[180:183], v[86:89]
	v_mfma_f32_16x16x32_bf16 v[82:85], v[156:159], v[180:183], v[82:85]
	v_mfma_f32_16x16x32_bf16 v[70:73], v[148:151], v[188:191], v[70:73]
	v_mfma_f32_16x16x32_bf16 v[66:69], v[156:159], v[188:191], v[66:69]
	v_mfma_f32_16x16x32_bf16 v[118:121], v[152:155], v[168:171], v[118:121]
	v_mfma_f32_16x16x32_bf16 v[114:117], v[160:163], v[168:171], v[114:117]
	v_mfma_f32_16x16x32_bf16 v[102:105], v[152:155], v[176:179], v[102:105]
	v_mfma_f32_16x16x32_bf16 v[98:101], v[160:163], v[176:179], v[98:101]
	v_mfma_f32_16x16x32_bf16 v[86:89], v[152:155], v[184:187], v[86:89]
	v_mfma_f32_16x16x32_bf16 v[82:85], v[160:163], v[184:187], v[82:85]
	v_mfma_f32_16x16x32_bf16 v[70:73], v[152:155], v[208:211], v[70:73]
	v_mfma_f32_16x16x32_bf16 v[66:69], v[160:163], v[208:211], v[66:69]
	s_setprio 0
	s_barrier
	s_mov_b32 m0, s57
	s_or_b32 s41, s18, 0x180
	ds_read_b128 v[164:167], v205 offset:49152
	ds_read_b128 v[168:171], v205 offset:50176
	ds_read_b128 v[172:175], v205 offset:51200
	ds_read_b128 v[176:179], v205 offset:52224
	ds_read_b128 v[180:183], v205 offset:53248
	ds_read_b128 v[184:187], v205 offset:54272
	ds_read_b128 v[188:191], v205 offset:55296
	ds_read_b128 v[208:211], v205 offset:56320
	buffer_load_dwordx4 v200, s[64:67], s41 offen lds
	s_mov_b32 m0, s58
	s_nop 0
	buffer_load_dwordx4 v201, s[64:67], s41 offen lds
	s_or_b32 s41, s18, 0x80180
	s_mov_b32 m0, s62
	s_nop 0
	buffer_load_dwordx4 v200, s[64:67], s41 offen lds
	s_mov_b32 m0, s63
	s_nop 0
	buffer_load_dwordx4 v201, s[64:67], s41 offen lds
	s_or_b32 s41, s20, 0x180
	s_mov_b32 m0, s59
	s_nop 0
	buffer_load_dwordx4 v200, s[4:7], s41 offen lds
	s_mov_b32 m0, s61
	s_nop 0
	buffer_load_dwordx4 v201, s[4:7], s41 offen lds
	s_waitcnt vmcnt(8)
	s_waitcnt lgkmcnt(0)
	s_setprio 1
	s_barrier
	v_mfma_f32_16x16x32_bf16 v[62:65], v[132:135], v[164:167], v[62:65]
	v_mfma_f32_16x16x32_bf16 v[58:61], v[140:143], v[164:167], v[58:61]
	v_mfma_f32_16x16x32_bf16 v[46:49], v[132:135], v[172:175], v[46:49]
	v_mfma_f32_16x16x32_bf16 v[42:45], v[140:143], v[172:175], v[42:45]
	v_mfma_f32_16x16x32_bf16 v[30:33], v[132:135], v[180:183], v[30:33]
	v_mfma_f32_16x16x32_bf16 v[26:29], v[140:143], v[180:183], v[26:29]
	v_mfma_f32_16x16x32_bf16 v[14:17], v[132:135], v[188:191], v[14:17]
	v_mfma_f32_16x16x32_bf16 v[10:13], v[140:143], v[188:191], v[10:13]
	v_mfma_f32_16x16x32_bf16 v[62:65], v[136:139], v[168:171], v[62:65]
	v_mfma_f32_16x16x32_bf16 v[58:61], v[144:147], v[168:171], v[58:61]
	v_mfma_f32_16x16x32_bf16 v[46:49], v[136:139], v[176:179], v[46:49]
	v_mfma_f32_16x16x32_bf16 v[42:45], v[144:147], v[176:179], v[42:45]
	v_mfma_f32_16x16x32_bf16 v[30:33], v[136:139], v[184:187], v[30:33]
	v_mfma_f32_16x16x32_bf16 v[26:29], v[144:147], v[184:187], v[26:29]
	v_mfma_f32_16x16x32_bf16 v[14:17], v[136:139], v[208:211], v[14:17]
	v_mfma_f32_16x16x32_bf16 v[10:13], v[144:147], v[208:211], v[10:13]
	v_mfma_f32_16x16x32_bf16 v[54:57], v[148:151], v[164:167], v[54:57]
	v_mfma_f32_16x16x32_bf16 v[50:53], v[156:159], v[164:167], v[50:53]
	v_mfma_f32_16x16x32_bf16 v[38:41], v[148:151], v[172:175], v[38:41]
	v_mfma_f32_16x16x32_bf16 v[34:37], v[156:159], v[172:175], v[34:37]
	v_mfma_f32_16x16x32_bf16 v[22:25], v[148:151], v[180:183], v[22:25]
	v_mfma_f32_16x16x32_bf16 v[18:21], v[156:159], v[180:183], v[18:21]
	v_mfma_f32_16x16x32_bf16 v[6:9], v[148:151], v[188:191], v[6:9]
	v_mfma_f32_16x16x32_bf16 v[2:5], v[156:159], v[188:191], v[2:5]
	v_mfma_f32_16x16x32_bf16 v[54:57], v[152:155], v[168:171], v[54:57]
	v_mfma_f32_16x16x32_bf16 v[50:53], v[160:163], v[168:171], v[50:53]
	v_mfma_f32_16x16x32_bf16 v[38:41], v[152:155], v[176:179], v[38:41]
	v_mfma_f32_16x16x32_bf16 v[34:37], v[160:163], v[176:179], v[34:37]
	v_mfma_f32_16x16x32_bf16 v[22:25], v[152:155], v[184:187], v[22:25]
	v_mfma_f32_16x16x32_bf16 v[18:21], v[160:163], v[184:187], v[18:21]
	v_mfma_f32_16x16x32_bf16 v[6:9], v[152:155], v[208:211], v[6:9]
	v_mfma_f32_16x16x32_bf16 v[2:5], v[160:163], v[208:211], v[2:5]
	s_setprio 0
	s_barrier
	s_add_u32 s71, s20, 0x200
	s_mov_b32 s72, 0
	s_mov_b64 s[42:43], 0
	s_branch .LBB0_632
; #define PG8_STAGEA(bufoff, goff, voff) PG8_STAGEX(rsA, bufoff, goff, voff)
; #define PG8_STAGEB(bufoff, goff, voff) PG8_STAGEX(rsB, bufoff, goff, voff)
; #define PG8_LDA(dst, b, h) do { _Pragma("unroll") for (int m = 0; m < 4; ++m) _Pragma("unroll") for (int k = 0; k < 2; ++k) dst[m][k] = *(const PG8_LAS bf16x8*)(lds + PG8_SA(b, h) + aoff + m * 2048 + k * 1024); } while (0)
; #define PG8_LDB(dst, b, h) do { _Pragma("unroll") for (int n = 0; n < 2; ++n) _Pragma("unroll") for (int k = 0; k < 2; ++k) dst[n][k] = *(const PG8_LAS bf16x8*)(lds + PG8_SB(b, h) + boff + n * 2048 + k * 1024); } while (0)
; #define PG8_MMA(ai, bj, At, Bt) do { __builtin_amdgcn_s_setprio(1); _Pragma("unroll") for (int m = 0; m < 4; ++m) _Pragma("unroll") for (int n = 0; n < 2; ++n) _Pragma("unroll") for (int k = 0; k < 2; ++k) \
;         acc[ai][bj][m][n] = __builtin_amdgcn_mfma_f32_16x16x32_bf16(Bt[n][k], At[m][k], acc[ai][bj][m][n], 0, 0, 0); __builtin_amdgcn_s_setprio(0); } while (0)
; #define PG8_WAIT_V(n) asm volatile("s_waitcnt vmcnt(" #n ")" ::: "memory")
; #define PG8_WAIT_L(n) asm volatile("s_waitcnt lgkmcnt(" #n ")" ::: "memory")
; #define PG8_BAR __builtin_amdgcn_s_barrier()
; #define PG8_SCHED __builtin_amdgcn_sched_barrier(0)
; template <class Epi, class Sched, bool ALIGN_EPI = false, bool SP2 = false>
; __device__ __forceinline__ void gemm_phase(PG8_LAS unsigned char* lds, const Gemm g, const Sched& S, const Epi& E) {
;     ...
;             PG8_LDB(B0, 0, 0); PG8_LDB(B1, 0, 1); PG8_SCHED; PG8_LDA(At, 0, 0); PG8_STAGEA(PG8_SA(1, 1), a1 + hstep, voffA);
;             if (t == 0 && ui > 0) {
; #pragma unroll
;                 for (int a = 0; a < 2; ++a)
; #pragma unroll
;                     for (int b = 0; b < 2; ++b)
; #pragma unroll
;                         for (int m = 0; m < 4; ++m)
; #pragma unroll
;                             for (int n = 0; n < 2; ++n) acc[a][b][m][n] = (f32x4){0.f, 0.f, 0.f, 0.f}; }
;             PG8_WAIT_V(8); PG8_WAIT_L(0); PG8_BAR; PG8_MMA(0, 0, At, B0); PG8_MMA(0, 1, At, B1); PG8_BAR; PG8_SCHED;
;             PG8_LDA(At, 0, 1); PG8_STAGEB(PG8_SB(0, 0), b2, voffB); PG8_STAGEB(PG8_SB(0, 1), b2 + hstep, voffB); PG8_STAGEA(PG8_SA(0, 0), a2, voffA);
;             PG8_WAIT_V(8); PG8_WAIT_L(0); PG8_BAR; PG8_MMA(1, 0, At, B0); PG8_MMA(1, 1, At, B1); PG8_BAR; PG8_SCHED;
.LBB0_631:
	ds_read_b128 v[132:135], v206
	ds_read_b128 v[136:139], v206 offset:1024
	ds_read_b128 v[140:143], v206 offset:2048
	ds_read_b128 v[144:147], v206 offset:3072
	ds_read_b128 v[148:151], v207
	ds_read_b128 v[152:155], v207 offset:1024
	ds_read_b128 v[156:159], v207 offset:2048
	ds_read_b128 v[160:163], v207 offset:3072
	s_add_i32 s41, s20, s42
	s_add_i32 s41, s41, 0x80180
	s_add_i32 s66, s31, s42
	s_add_i32 s73, s71, s42
	s_cmpk_eq_i32 s42, 0xe00
	s_mov_b32 m0, s68
	ds_read_b128 v[164:167], v205
	ds_read_b128 v[168:171], v205 offset:1024
	ds_read_b128 v[172:175], v205 offset:2048
	ds_read_b128 v[176:179], v205 offset:3072
	ds_read_b128 v[180:183], v205 offset:4096
	ds_read_b128 v[184:187], v205 offset:5120
	ds_read_b128 v[188:191], v205 offset:6144
	ds_read_b128 v[208:211], v205 offset:7168
	buffer_load_dwordx4 v200, s[4:7], s41 offen lds
	s_mov_b32 m0, s69
	s_nop 0
	buffer_load_dwordx4 v201, s[4:7], s41 offen lds
	s_waitcnt vmcnt(8)
	s_waitcnt lgkmcnt(0)
	s_setprio 1
	s_barrier
	v_mfma_f32_16x16x32_bf16 v[126:129], v[132:135], v[164:167], v[126:129]
	v_mfma_f32_16x16x32_bf16 v[122:125], v[140:143], v[164:167], v[122:125]
	v_mfma_f32_16x16x32_bf16 v[110:113], v[132:135], v[172:175], v[110:113]
	v_mfma_f32_16x16x32_bf16 v[106:109], v[140:143], v[172:175], v[106:109]
	v_mfma_f32_16x16x32_bf16 v[94:97], v[132:135], v[180:183], v[94:97]
	v_mfma_f32_16x16x32_bf16 v[90:93], v[140:143], v[180:183], v[90:93]
	v_mfma_f32_16x16x32_bf16 v[78:81], v[132:135], v[188:191], v[78:81]
	v_mfma_f32_16x16x32_bf16 v[74:77], v[140:143], v[188:191], v[74:77]
	v_mfma_f32_16x16x32_bf16 v[126:129], v[136:139], v[168:171], v[126:129]
	v_mfma_f32_16x16x32_bf16 v[122:125], v[144:147], v[168:171], v[122:125]
	v_mfma_f32_16x16x32_bf16 v[110:113], v[136:139], v[176:179], v[110:113]
	v_mfma_f32_16x16x32_bf16 v[106:109], v[144:147], v[176:179], v[106:109]
	v_mfma_f32_16x16x32_bf16 v[94:97], v[136:139], v[184:187], v[94:97]
	v_mfma_f32_16x16x32_bf16 v[90:93], v[144:147], v[184:187], v[90:93]
	v_mfma_f32_16x16x32_bf16 v[78:81], v[136:139], v[208:211], v[78:81]
	v_mfma_f32_16x16x32_bf16 v[74:77], v[144:147], v[208:211], v[74:77]
	v_mfma_f32_16x16x32_bf16 v[118:121], v[148:151], v[164:167], v[118:121]
	v_mfma_f32_16x16x32_bf16 v[114:117], v[156:159], v[164:167], v[114:117]
	v_mfma_f32_16x16x32_bf16 v[102:105], v[148:151], v[172:175], v[102:105]
	v_mfma_f32_16x16x32_bf16 v[98:101], v[156:159], v[172:175], v[98:101]
	v_mfma_f32_16x16x32_bf16 v[86:89], v[148:151], v[180:183], v[86:89]
	v_mfma_f32_16x16x32_bf16 v[82:85], v[156:159], v[180:183], v[82:85]
	v_mfma_f32_16x16x32_bf16 v[70:73], v[148:151], v[188:191], v[70:73]
	v_mfma_f32_16x16x32_bf16 v[66:69], v[156:159], v[188:191], v[66:69]
	v_mfma_f32_16x16x32_bf16 v[118:121], v[152:155], v[168:171], v[118:121]
	v_mfma_f32_16x16x32_bf16 v[114:117], v[160:163], v[168:171], v[114:117]
	v_mfma_f32_16x16x32_bf16 v[102:105], v[152:155], v[176:179], v[102:105]
	v_mfma_f32_16x16x32_bf16 v[98:101], v[160:163], v[176:179], v[98:101]
	v_mfma_f32_16x16x32_bf16 v[86:89], v[152:155], v[184:187], v[86:89]
	v_mfma_f32_16x16x32_bf16 v[82:85], v[160:163], v[184:187], v[82:85]
	v_mfma_f32_16x16x32_bf16 v[70:73], v[152:155], v[208:211], v[70:73]
	v_mfma_f32_16x16x32_bf16 v[66:69], v[160:163], v[208:211], v[66:69]
	s_setprio 0
	s_barrier
	s_mov_b32 m0, s46
	s_cselect_b32 s41, s23, s66
	s_mov_b32 s66, s6
	s_mov_b32 s67, s7
	ds_read_b128 v[164:167], v205 offset:16384
	ds_read_b128 v[168:171], v205 offset:17408
	ds_read_b128 v[172:175], v205 offset:18432
	ds_read_b128 v[176:179], v205 offset:19456
	ds_read_b128 v[180:183], v205 offset:20480
	ds_read_b128 v[184:187], v205 offset:21504
	ds_read_b128 v[188:191], v205 offset:22528
	ds_read_b128 v[208:211], v205 offset:23552
	buffer_load_dwordx4 v200, s[64:67], s41 offen lds
	s_mov_b32 m0, s47
	s_cselect_b32 s73, s21, s73
	buffer_load_dwordx4 v201, s[64:67], s41 offen lds
	s_add_i32 s74, s41, 0x80000
	s_mov_b32 m0, s48
	s_nop 0
	buffer_load_dwordx4 v200, s[64:67], s74 offen lds
	s_mov_b32 m0, s49
	s_nop 0
	buffer_load_dwordx4 v201, s[64:67], s74 offen lds
	s_mov_b32 m0, s45
	s_nop 0
	buffer_load_dwordx4 v200, s[4:7], s73 offen lds
	s_mov_b32 m0, s50
	s_nop 0
	buffer_load_dwordx4 v201, s[4:7], s73 offen lds
	s_waitcnt vmcnt(8)
	s_waitcnt lgkmcnt(0)
	s_setprio 1
	s_barrier
	v_mfma_f32_16x16x32_bf16 v[62:65], v[132:135], v[164:167], v[62:65]
	v_mfma_f32_16x16x32_bf16 v[58:61], v[140:143], v[164:167], v[58:61]
	v_mfma_f32_16x16x32_bf16 v[46:49], v[132:135], v[172:175], v[46:49]
	v_mfma_f32_16x16x32_bf16 v[42:45], v[140:143], v[172:175], v[42:45]
	v_mfma_f32_16x16x32_bf16 v[30:33], v[132:135], v[180:183], v[30:33]
	v_mfma_f32_16x16x32_bf16 v[26:29], v[140:143], v[180:183], v[26:29]
	v_mfma_f32_16x16x32_bf16 v[14:17], v[132:135], v[188:191], v[14:17]
	v_mfma_f32_16x16x32_bf16 v[10:13], v[140:143], v[188:191], v[10:13]
	v_mfma_f32_16x16x32_bf16 v[62:65], v[136:139], v[168:171], v[62:65]
	v_mfma_f32_16x16x32_bf16 v[58:61], v[144:147], v[168:171], v[58:61]
	v_mfma_f32_16x16x32_bf16 v[46:49], v[136:139], v[176:179], v[46:49]
	v_mfma_f32_16x16x32_bf16 v[42:45], v[144:147], v[176:179], v[42:45]
	v_mfma_f32_16x16x32_bf16 v[30:33], v[136:139], v[184:187], v[30:33]
	v_mfma_f32_16x16x32_bf16 v[26:29], v[144:147], v[184:187], v[26:29]
	v_mfma_f32_16x16x32_bf16 v[14:17], v[136:139], v[208:211], v[14:17]
	v_mfma_f32_16x16x32_bf16 v[10:13], v[144:147], v[208:211], v[10:13]
	v_mfma_f32_16x16x32_bf16 v[54:57], v[148:151], v[164:167], v[54:57]
	v_mfma_f32_16x16x32_bf16 v[50:53], v[156:159], v[164:167], v[50:53]
	v_mfma_f32_16x16x32_bf16 v[38:41], v[148:151], v[172:175], v[38:41]
	v_mfma_f32_16x16x32_bf16 v[34:37], v[156:159], v[172:175], v[34:37]
	v_mfma_f32_16x16x32_bf16 v[22:25], v[148:151], v[180:183], v[22:25]
	v_mfma_f32_16x16x32_bf16 v[18:21], v[156:159], v[180:183], v[18:21]
	v_mfma_f32_16x16x32_bf16 v[6:9], v[148:151], v[188:191], v[6:9]
	v_mfma_f32_16x16x32_bf16 v[2:5], v[156:159], v[188:191], v[2:5]
	v_mfma_f32_16x16x32_bf16 v[54:57], v[152:155], v[168:171], v[54:57]
	v_mfma_f32_16x16x32_bf16 v[50:53], v[160:163], v[168:171], v[50:53]
	v_mfma_f32_16x16x32_bf16 v[38:41], v[152:155], v[176:179], v[38:41]
	v_mfma_f32_16x16x32_bf16 v[34:37], v[160:163], v[176:179], v[34:37]
	v_mfma_f32_16x16x32_bf16 v[22:25], v[152:155], v[184:187], v[22:25]
	v_mfma_f32_16x16x32_bf16 v[18:21], v[160:163], v[184:187], v[18:21]
	v_mfma_f32_16x16x32_bf16 v[6:9], v[152:155], v[208:211], v[6:9]
	v_mfma_f32_16x16x32_bf16 v[2:5], v[160:163], v[208:211], v[2:5]
	s_setprio 0
	s_barrier
; #define PG8_STAGEA(bufoff, goff, voff) PG8_STAGEX(rsA, bufoff, goff, voff)
; #define PG8_STAGEB(bufoff, goff, voff) PG8_STAGEX(rsB, bufoff, goff, voff)
; #define PG8_LDA(dst, b, h) do { _Pragma("unroll") for (int m = 0; m < 4; ++m) _Pragma("unroll") for (int k = 0; k < 2; ++k) dst[m][k] = *(const PG8_LAS bf16x8*)(lds + PG8_SA(b, h) + aoff + m * 2048 + k * 1024); } while (0)
; #define PG8_LDB(dst, b, h) do { _Pragma("unroll") for (int n = 0; n < 2; ++n) _Pragma("unroll") for (int k = 0; k < 2; ++k) dst[n][k] = *(const PG8_LAS bf16x8*)(lds + PG8_SB(b, h) + boff + n * 2048 + k * 1024); } while (0)
; #define PG8_MMA(ai, bj, At, Bt) do { __builtin_amdgcn_s_setprio(1); _Pragma("unroll") for (int m = 0; m < 4; ++m) _Pragma("unroll") for (int n = 0; n < 2; ++n) _Pragma("unroll") for (int k = 0; k < 2; ++k) \
;         acc[ai][bj][m][n] = __builtin_amdgcn_mfma_f32_16x16x32_bf16(Bt[n][k], At[m][k], acc[ai][bj][m][n], 0, 0, 0); __builtin_amdgcn_s_setprio(0); } while (0)
; #define PG8_WAIT_V(n) asm volatile("s_waitcnt vmcnt(" #n ")" ::: "memory")
; #define PG8_WAIT_L(n) asm volatile("s_waitcnt lgkmcnt(" #n ")" ::: "memory")
; #define PG8_BAR __builtin_amdgcn_s_barrier()
; #define PG8_SCHED __builtin_amdgcn_sched_barrier(0)
; template <class Epi, class Sched, bool ALIGN_EPI = false, bool SP2 = false>
; __device__ __forceinline__ void gemm_phase(PG8_LAS unsigned char* lds, const Gemm g, const Sched& S, const Epi& E) {
;     ...
;             PG8_LDB(B0, 1, 0); PG8_LDB(B1, 1, 1); PG8_SCHED; PG8_LDA(At, 1, 0); PG8_STAGEA(PG8_SA(0, 1), a2 + hstep, voffA);
;             PG8_WAIT_V(8); PG8_WAIT_L(0); PG8_BAR; PG8_MMA(0, 0, At, B0); PG8_MMA(0, 1, At, B1); PG8_BAR; PG8_SCHED;
;             PG8_LDA(At, 1, 1); PG8_STAGEB(PG8_SB(1, 0), b3, voffB); PG8_STAGEB(PG8_SB(1, 1), b3 + hstep, voffB); PG8_STAGEA(PG8_SA(1, 0), a3, voffA);
;             PG8_WAIT_V(8); PG8_WAIT_L(0); PG8_BAR; PG8_MMA(1, 0, At, B0); PG8_MMA(1, 1, At, B1); PG8_BAR; PG8_SCHED;
	ds_read_b128 v[132:135], v130
	ds_read_b128 v[136:139], v130 offset:1024
	ds_read_b128 v[140:143], v130 offset:2048
	ds_read_b128 v[144:147], v130 offset:3072
	ds_read_b128 v[148:151], v131
	ds_read_b128 v[152:155], v131 offset:1024
	ds_read_b128 v[156:159], v131 offset:2048
	ds_read_b128 v[160:163], v131 offset:3072
	s_add_i32 s74, s73, 0x80000
	s_mov_b32 m0, s51
	ds_read_b128 v[164:167], v205 offset:32768
	ds_read_b128 v[168:171], v205 offset:33792
	ds_read_b128 v[172:175], v205 offset:34816
	ds_read_b128 v[176:179], v205 offset:35840
	ds_read_b128 v[180:183], v205 offset:36864
	ds_read_b128 v[184:187], v205 offset:37888
	ds_read_b128 v[188:191], v205 offset:38912
	ds_read_b128 v[208:211], v205 offset:39936
	buffer_load_dwordx4 v200, s[4:7], s74 offen lds
	s_mov_b32 m0, s56
	s_nop 0
	buffer_load_dwordx4 v201, s[4:7], s74 offen lds
	s_waitcnt vmcnt(8)
	s_waitcnt lgkmcnt(0)
	s_setprio 1
	s_barrier
	v_mfma_f32_16x16x32_bf16 v[126:129], v[132:135], v[164:167], v[126:129]
	v_mfma_f32_16x16x32_bf16 v[122:125], v[140:143], v[164:167], v[122:125]
	v_mfma_f32_16x16x32_bf16 v[110:113], v[132:135], v[172:175], v[110:113]
	v_mfma_f32_16x16x32_bf16 v[106:109], v[140:143], v[172:175], v[106:109]
	v_mfma_f32_16x16x32_bf16 v[94:97], v[132:135], v[180:183], v[94:97]
	v_mfma_f32_16x16x32_bf16 v[90:93], v[140:143], v[180:183], v[90:93]
	v_mfma_f32_16x16x32_bf16 v[78:81], v[132:135], v[188:191], v[78:81]
	v_mfma_f32_16x16x32_bf16 v[74:77], v[140:143], v[188:191], v[74:77]
	v_mfma_f32_16x16x32_bf16 v[126:129], v[136:139], v[168:171], v[126:129]
	v_mfma_f32_16x16x32_bf16 v[122:125], v[144:147], v[168:171], v[122:125]
	v_mfma_f32_16x16x32_bf16 v[110:113], v[136:139], v[176:179], v[110:113]
	v_mfma_f32_16x16x32_bf16 v[106:109], v[144:147], v[176:179], v[106:109]
	v_mfma_f32_16x16x32_bf16 v[94:97], v[136:139], v[184:187], v[94:97]
	v_mfma_f32_16x16x32_bf16 v[90:93], v[144:147], v[184:187], v[90:93]
	v_mfma_f32_16x16x32_bf16 v[78:81], v[136:139], v[208:211], v[78:81]
	v_mfma_f32_16x16x32_bf16 v[74:77], v[144:147], v[208:211], v[74:77]
	v_mfma_f32_16x16x32_bf16 v[118:121], v[148:151], v[164:167], v[118:121]
	v_mfma_f32_16x16x32_bf16 v[114:117], v[156:159], v[164:167], v[114:117]
	v_mfma_f32_16x16x32_bf16 v[102:105], v[148:151], v[172:175], v[102:105]
	v_mfma_f32_16x16x32_bf16 v[98:101], v[156:159], v[172:175], v[98:101]
	v_mfma_f32_16x16x32_bf16 v[86:89], v[148:151], v[180:183], v[86:89]
	v_mfma_f32_16x16x32_bf16 v[82:85], v[156:159], v[180:183], v[82:85]
	v_mfma_f32_16x16x32_bf16 v[70:73], v[148:151], v[188:191], v[70:73]
	v_mfma_f32_16x16x32_bf16 v[66:69], v[156:159], v[188:191], v[66:69]
	v_mfma_f32_16x16x32_bf16 v[118:121], v[152:155], v[168:171], v[118:121]
	v_mfma_f32_16x16x32_bf16 v[114:117], v[160:163], v[168:171], v[114:117]
	v_mfma_f32_16x16x32_bf16 v[102:105], v[152:155], v[176:179], v[102:105]
	v_mfma_f32_16x16x32_bf16 v[98:101], v[160:163], v[176:179], v[98:101]
	v_mfma_f32_16x16x32_bf16 v[86:89], v[152:155], v[184:187], v[86:89]
	v_mfma_f32_16x16x32_bf16 v[82:85], v[160:163], v[184:187], v[82:85]
	v_mfma_f32_16x16x32_bf16 v[70:73], v[152:155], v[208:211], v[70:73]
	v_mfma_f32_16x16x32_bf16 v[66:69], v[160:163], v[208:211], v[66:69]
	s_setprio 0
	s_barrier
	s_mov_b32 m0, s57
	s_add_i32 s74, s41, 0x80
	ds_read_b128 v[164:167], v205 offset:49152
	ds_read_b128 v[168:171], v205 offset:50176
	ds_read_b128 v[172:175], v205 offset:51200
	ds_read_b128 v[176:179], v205 offset:52224
	ds_read_b128 v[180:183], v205 offset:53248
	ds_read_b128 v[184:187], v205 offset:54272
	ds_read_b128 v[188:191], v205 offset:55296
	ds_read_b128 v[208:211], v205 offset:56320
	buffer_load_dwordx4 v200, s[64:67], s74 offen lds
	s_mov_b32 m0, s58
	s_add_i32 s41, s41, 0x80080
	buffer_load_dwordx4 v201, s[64:67], s74 offen lds
	s_mov_b32 m0, s62
	s_addk_i32 s73, 0x80
	buffer_load_dwordx4 v200, s[64:67], s41 offen lds
	s_mov_b32 m0, s63
	s_nop 0
	buffer_load_dwordx4 v201, s[64:67], s41 offen lds
	s_mov_b32 m0, s59
	s_nop 0
	buffer_load_dwordx4 v200, s[4:7], s73 offen lds
	s_mov_b32 m0, s61
	s_nop 0
	buffer_load_dwordx4 v201, s[4:7], s73 offen lds
	s_waitcnt vmcnt(8)
	s_waitcnt lgkmcnt(0)
	s_setprio 1
	s_barrier
	v_mfma_f32_16x16x32_bf16 v[62:65], v[132:135], v[164:167], v[62:65]
	v_mfma_f32_16x16x32_bf16 v[58:61], v[140:143], v[164:167], v[58:61]
	v_mfma_f32_16x16x32_bf16 v[46:49], v[132:135], v[172:175], v[46:49]
	v_mfma_f32_16x16x32_bf16 v[42:45], v[140:143], v[172:175], v[42:45]
	v_mfma_f32_16x16x32_bf16 v[30:33], v[132:135], v[180:183], v[30:33]
	v_mfma_f32_16x16x32_bf16 v[26:29], v[140:143], v[180:183], v[26:29]
	v_mfma_f32_16x16x32_bf16 v[14:17], v[132:135], v[188:191], v[14:17]
	v_mfma_f32_16x16x32_bf16 v[10:13], v[140:143], v[188:191], v[10:13]
	v_mfma_f32_16x16x32_bf16 v[62:65], v[136:139], v[168:171], v[62:65]
	v_mfma_f32_16x16x32_bf16 v[58:61], v[144:147], v[168:171], v[58:61]
	v_mfma_f32_16x16x32_bf16 v[46:49], v[136:139], v[176:179], v[46:49]
	v_mfma_f32_16x16x32_bf16 v[42:45], v[144:147], v[176:179], v[42:45]
	v_mfma_f32_16x16x32_bf16 v[30:33], v[136:139], v[184:187], v[30:33]
	v_mfma_f32_16x16x32_bf16 v[26:29], v[144:147], v[184:187], v[26:29]
	v_mfma_f32_16x16x32_bf16 v[14:17], v[136:139], v[208:211], v[14:17]
	v_mfma_f32_16x16x32_bf16 v[10:13], v[144:147], v[208:211], v[10:13]
	v_mfma_f32_16x16x32_bf16 v[54:57], v[148:151], v[164:167], v[54:57]
	v_mfma_f32_16x16x32_bf16 v[50:53], v[156:159], v[164:167], v[50:53]
	v_mfma_f32_16x16x32_bf16 v[38:41], v[148:151], v[172:175], v[38:41]
	v_mfma_f32_16x16x32_bf16 v[34:37], v[156:159], v[172:175], v[34:37]
	v_mfma_f32_16x16x32_bf16 v[22:25], v[148:151], v[180:183], v[22:25]
	v_mfma_f32_16x16x32_bf16 v[18:21], v[156:159], v[180:183], v[18:21]
	v_mfma_f32_16x16x32_bf16 v[6:9], v[148:151], v[188:191], v[6:9]
	v_mfma_f32_16x16x32_bf16 v[2:5], v[156:159], v[188:191], v[2:5]
	v_mfma_f32_16x16x32_bf16 v[54:57], v[152:155], v[168:171], v[54:57]
	v_mfma_f32_16x16x32_bf16 v[50:53], v[160:163], v[168:171], v[50:53]
	v_mfma_f32_16x16x32_bf16 v[38:41], v[152:155], v[176:179], v[38:41]
	v_mfma_f32_16x16x32_bf16 v[34:37], v[160:163], v[176:179], v[34:37]
	v_mfma_f32_16x16x32_bf16 v[22:25], v[152:155], v[184:187], v[22:25]
	v_mfma_f32_16x16x32_bf16 v[18:21], v[160:163], v[184:187], v[18:21]
	v_mfma_f32_16x16x32_bf16 v[6:9], v[152:155], v[208:211], v[6:9]
	v_mfma_f32_16x16x32_bf16 v[2:5], v[160:163], v[208:211], v[2:5]
	s_setprio 0
	s_barrier
	s_add_i32 s72, s72, 2
	s_add_u32 s42, s42, 0x100
	s_addc_u32 s43, s43, 0
	s_cmp_gt_u32 s72, 29
	s_cbranch_scc1 .LBB0_634

; #define PG8_STAGEA(bufoff, goff, voff) PG8_STAGEX(rsA, bufoff, goff, voff)
; #define PG8_STAGEB(bufoff, goff, voff) PG8_STAGEX(rsB, bufoff, goff, voff)
; #define PG8_LDA(dst, b, h) do { _Pragma("unroll") for (int m = 0; m < 4; ++m) _Pragma("unroll") for (int k = 0; k < 2; ++k) dst[m][k] = *(const PG8_LAS bf16x8*)(lds + PG8_SA(b, h) + aoff + m * 2048 + k * 1024); } while (0)
; #define PG8_MMA(ai, bj, At, Bt) do { __builtin_amdgcn_s_setprio(1); _Pragma("unroll") for (int m = 0; m < 4; ++m) _Pragma("unroll") for (int n = 0; n < 2; ++n) _Pragma("unroll") for (int k = 0; k < 2; ++k) \
;         acc[ai][bj][m][n] = __builtin_amdgcn_mfma_f32_16x16x32_bf16(Bt[n][k], At[m][k], acc[ai][bj][m][n], 0, 0, 0); __builtin_amdgcn_s_setprio(0); } while (0)
; #define PG8_WAIT_V(n) asm volatile("s_waitcnt vmcnt(" #n ")" ::: "memory")
; #define PG8_WAIT_L(n) asm volatile("s_waitcnt lgkmcnt(" #n ")" ::: "memory")
; #define PG8_BAR __builtin_amdgcn_s_barrier()
; #define PG8_SCHED __builtin_amdgcn_sched_barrier(0)
; template <class Epi, class Sched, bool ALIGN_EPI = false, bool SP2 = false>
; __device__ __forceinline__ void gemm_phase(PG8_LAS unsigned char* lds, const Gemm g, const Sched& S, const Epi& E) {
;     ...
;             PG8_WAIT_V(8); PG8_WAIT_L(0); PG8_BAR; PG8_MMA(0, 0, At, B0); PG8_MMA(0, 1, At, B1); PG8_BAR; PG8_SCHED;
;             PG8_LDA(At, 0, 1); PG8_STAGEB(PG8_SB(0, 0), b2, voffB); PG8_STAGEB(PG8_SB(0, 1), b2 + hstep, voffB); PG8_STAGEA(PG8_SA(0, 0), a2, voffA);
;             PG8_WAIT_V(8); PG8_WAIT_L(0); PG8_BAR; PG8_MMA(1, 0, At, B0); PG8_MMA(1, 1, At, B1); PG8_BAR; PG8_SCHED;
.LBB0_892:
	s_waitcnt vmcnt(8)
	s_waitcnt lgkmcnt(0)
	s_setprio 1
	s_barrier
	v_mfma_f32_16x16x32_bf16 v[126:129], v[146:149], v[186:189], v[126:129]
	v_mfma_f32_16x16x32_bf16 v[122:125], v[154:157], v[186:189], v[122:125]
	v_mfma_f32_16x16x32_bf16 v[110:113], v[146:149], v[178:181], v[110:113]
	v_mfma_f32_16x16x32_bf16 v[106:109], v[154:157], v[178:181], v[106:109]
	v_mfma_f32_16x16x32_bf16 v[94:97], v[146:149], v[170:173], v[94:97]
	v_mfma_f32_16x16x32_bf16 v[90:93], v[154:157], v[170:173], v[90:93]
	v_mfma_f32_16x16x32_bf16 v[78:81], v[146:149], v[162:165], v[78:81]
	v_mfma_f32_16x16x32_bf16 v[74:77], v[154:157], v[162:165], v[74:77]
	v_mfma_f32_16x16x32_bf16 v[126:129], v[150:153], v[190:193], v[126:129]
	v_mfma_f32_16x16x32_bf16 v[122:125], v[158:161], v[190:193], v[122:125]
	v_mfma_f32_16x16x32_bf16 v[110:113], v[150:153], v[182:185], v[110:113]
	v_mfma_f32_16x16x32_bf16 v[106:109], v[158:161], v[182:185], v[106:109]
	v_mfma_f32_16x16x32_bf16 v[94:97], v[150:153], v[174:177], v[94:97]
	v_mfma_f32_16x16x32_bf16 v[90:93], v[158:161], v[174:177], v[90:93]
	v_mfma_f32_16x16x32_bf16 v[78:81], v[150:153], v[166:169], v[78:81]
	v_mfma_f32_16x16x32_bf16 v[74:77], v[158:161], v[166:169], v[74:77]
	v_mfma_f32_16x16x32_bf16 v[118:121], v[130:133], v[186:189], v[118:121]
	v_mfma_f32_16x16x32_bf16 v[114:117], v[138:141], v[186:189], v[114:117]
	v_mfma_f32_16x16x32_bf16 v[102:105], v[130:133], v[178:181], v[102:105]
	v_mfma_f32_16x16x32_bf16 v[98:101], v[138:141], v[178:181], v[98:101]
	v_mfma_f32_16x16x32_bf16 v[86:89], v[130:133], v[170:173], v[86:89]
	v_mfma_f32_16x16x32_bf16 v[82:85], v[138:141], v[170:173], v[82:85]
	v_mfma_f32_16x16x32_bf16 v[70:73], v[130:133], v[162:165], v[70:73]
	v_mfma_f32_16x16x32_bf16 v[66:69], v[138:141], v[162:165], v[66:69]
	v_mfma_f32_16x16x32_bf16 v[118:121], v[134:137], v[190:193], v[118:121]
	v_mfma_f32_16x16x32_bf16 v[114:117], v[142:145], v[190:193], v[114:117]
	v_mfma_f32_16x16x32_bf16 v[102:105], v[134:137], v[182:185], v[102:105]
	v_mfma_f32_16x16x32_bf16 v[98:101], v[142:145], v[182:185], v[98:101]
	v_mfma_f32_16x16x32_bf16 v[86:89], v[134:137], v[174:177], v[86:89]
	v_mfma_f32_16x16x32_bf16 v[82:85], v[142:145], v[174:177], v[82:85]
	v_mfma_f32_16x16x32_bf16 v[70:73], v[134:137], v[166:169], v[70:73]
	v_mfma_f32_16x16x32_bf16 v[66:69], v[142:145], v[166:169], v[66:69]
	s_setprio 0
	s_barrier
	s_mov_b32 m0, s38
	s_add_i32 s24, s18, 0x100
	s_mov_b32 s14, s30
	s_mov_b32 s15, s31
	ds_read_b128 v[162:165], v203 offset:16384
	ds_read_b128 v[166:169], v203 offset:17408
	ds_read_b128 v[170:173], v203 offset:18432
	ds_read_b128 v[174:177], v203 offset:19456
	ds_read_b128 v[178:181], v203 offset:20480
	ds_read_b128 v[182:185], v203 offset:21504
	ds_read_b128 v[186:189], v203 offset:22528
	ds_read_b128 v[190:193], v203 offset:23552
	buffer_load_dwordx4 v195, s[12:15], s24 offen lds
	s_mov_b32 m0, s39
	s_nop 0
	buffer_load_dwordx4 v200, s[12:15], s24 offen lds
	s_add_i32 s24, s18, 0x160100
	s_mov_b32 m0, s40
	s_nop 0
	buffer_load_dwordx4 v195, s[12:15], s24 offen lds
	s_mov_b32 m0, s41
	s_nop 0
	buffer_load_dwordx4 v200, s[12:15], s24 offen lds
	s_add_i32 s24, s20, 0x100
	s_mov_b32 m0, s37
	s_nop 0
	buffer_load_dwordx4 v195, s[28:31], s24 offen lds
	s_mov_b32 m0, s42
	s_nop 0
	buffer_load_dwordx4 v200, s[28:31], s24 offen lds
	s_waitcnt vmcnt(8)
	s_waitcnt lgkmcnt(0)
	s_setprio 1
	s_barrier
	v_mfma_f32_16x16x32_bf16 v[62:65], v[146:149], v[162:165], v[62:65]
	v_mfma_f32_16x16x32_bf16 v[58:61], v[154:157], v[162:165], v[58:61]
	v_mfma_f32_16x16x32_bf16 v[46:49], v[146:149], v[170:173], v[46:49]
	v_mfma_f32_16x16x32_bf16 v[42:45], v[154:157], v[170:173], v[42:45]
	v_mfma_f32_16x16x32_bf16 v[30:33], v[146:149], v[178:181], v[30:33]
	v_mfma_f32_16x16x32_bf16 v[26:29], v[154:157], v[178:181], v[26:29]
	v_mfma_f32_16x16x32_bf16 v[14:17], v[146:149], v[186:189], v[14:17]
	v_mfma_f32_16x16x32_bf16 v[10:13], v[154:157], v[186:189], v[10:13]
	v_mfma_f32_16x16x32_bf16 v[62:65], v[150:153], v[166:169], v[62:65]
	v_mfma_f32_16x16x32_bf16 v[58:61], v[158:161], v[166:169], v[58:61]
	v_mfma_f32_16x16x32_bf16 v[46:49], v[150:153], v[174:177], v[46:49]
	v_mfma_f32_16x16x32_bf16 v[42:45], v[158:161], v[174:177], v[42:45]
	v_mfma_f32_16x16x32_bf16 v[30:33], v[150:153], v[182:185], v[30:33]
	v_mfma_f32_16x16x32_bf16 v[26:29], v[158:161], v[182:185], v[26:29]
	v_mfma_f32_16x16x32_bf16 v[14:17], v[150:153], v[190:193], v[14:17]
	v_mfma_f32_16x16x32_bf16 v[10:13], v[158:161], v[190:193], v[10:13]
	v_mfma_f32_16x16x32_bf16 v[54:57], v[130:133], v[162:165], v[54:57]
	v_mfma_f32_16x16x32_bf16 v[50:53], v[138:141], v[162:165], v[50:53]
	v_mfma_f32_16x16x32_bf16 v[38:41], v[130:133], v[170:173], v[38:41]
	v_mfma_f32_16x16x32_bf16 v[34:37], v[138:141], v[170:173], v[34:37]
	v_mfma_f32_16x16x32_bf16 v[22:25], v[130:133], v[178:181], v[22:25]
	v_mfma_f32_16x16x32_bf16 v[18:21], v[138:141], v[178:181], v[18:21]
	v_mfma_f32_16x16x32_bf16 v[6:9], v[130:133], v[186:189], v[6:9]
	v_mfma_f32_16x16x32_bf16 v[2:5], v[138:141], v[186:189], v[2:5]
	v_mfma_f32_16x16x32_bf16 v[54:57], v[134:137], v[166:169], v[54:57]
	v_mfma_f32_16x16x32_bf16 v[50:53], v[142:145], v[166:169], v[50:53]
	v_mfma_f32_16x16x32_bf16 v[38:41], v[134:137], v[174:177], v[38:41]
	v_mfma_f32_16x16x32_bf16 v[34:37], v[142:145], v[174:177], v[34:37]
	v_mfma_f32_16x16x32_bf16 v[22:25], v[134:137], v[182:185], v[22:25]
	v_mfma_f32_16x16x32_bf16 v[18:21], v[142:145], v[182:185], v[18:21]
	v_mfma_f32_16x16x32_bf16 v[6:9], v[134:137], v[190:193], v[6:9]
	v_mfma_f32_16x16x32_bf16 v[2:5], v[142:145], v[190:193], v[2:5]
	s_setprio 0
	s_barrier
; #define PG8_STAGEA(bufoff, goff, voff) PG8_STAGEX(rsA, bufoff, goff, voff)
; #define PG8_STAGEB(bufoff, goff, voff) PG8_STAGEX(rsB, bufoff, goff, voff)
; #define PG8_LDA(dst, b, h) do { _Pragma("unroll") for (int m = 0; m < 4; ++m) _Pragma("unroll") for (int k = 0; k < 2; ++k) dst[m][k] = *(const PG8_LAS bf16x8*)(lds + PG8_SA(b, h) + aoff + m * 2048 + k * 1024); } while (0)
; #define PG8_LDB(dst, b, h) do { _Pragma("unroll") for (int n = 0; n < 2; ++n) _Pragma("unroll") for (int k = 0; k < 2; ++k) dst[n][k] = *(const PG8_LAS bf16x8*)(lds + PG8_SB(b, h) + boff + n * 2048 + k * 1024); } while (0)
; #define PG8_MMA(ai, bj, At, Bt) do { __builtin_amdgcn_s_setprio(1); _Pragma("unroll") for (int m = 0; m < 4; ++m) _Pragma("unroll") for (int n = 0; n < 2; ++n) _Pragma("unroll") for (int k = 0; k < 2; ++k) \
;         acc[ai][bj][m][n] = __builtin_amdgcn_mfma_f32_16x16x32_bf16(Bt[n][k], At[m][k], acc[ai][bj][m][n], 0, 0, 0); __builtin_amdgcn_s_setprio(0); } while (0)
; #define PG8_WAIT_V(n) asm volatile("s_waitcnt vmcnt(" #n ")" ::: "memory")
; #define PG8_WAIT_L(n) asm volatile("s_waitcnt lgkmcnt(" #n ")" ::: "memory")
; #define PG8_BAR __builtin_amdgcn_s_barrier()
; #define PG8_SCHED __builtin_amdgcn_sched_barrier(0)
; template <class Epi, class Sched, bool ALIGN_EPI = false, bool SP2 = false>
; __device__ __forceinline__ void gemm_phase(PG8_LAS unsigned char* lds, const Gemm g, const Sched& S, const Epi& E) {
;     ...
;             PG8_LDB(B0, 1, 0); PG8_LDB(B1, 1, 1); PG8_SCHED; PG8_LDA(At, 1, 0); PG8_STAGEA(PG8_SA(0, 1), a2 + hstep, voffA);
;             PG8_WAIT_V(8); PG8_WAIT_L(0); PG8_BAR; PG8_MMA(0, 0, At, B0); PG8_MMA(0, 1, At, B1); PG8_BAR; PG8_SCHED;
;             PG8_LDA(At, 1, 1); PG8_STAGEB(PG8_SB(1, 0), b3, voffB); PG8_STAGEB(PG8_SB(1, 1), b3 + hstep, voffB); PG8_STAGEA(PG8_SA(1, 0), a3, voffA);
;             PG8_WAIT_V(8); PG8_WAIT_L(0); PG8_BAR; PG8_MMA(1, 0, At, B0); PG8_MMA(1, 1, At, B1); PG8_BAR; PG8_SCHED;
	v_add_u32_e32 v130, 0x18000, v202
	v_add_u32_e32 v131, 0x1c000, v202
	ds_read_b128 v[132:135], v130
	ds_read_b128 v[136:139], v130 offset:1024
	ds_read_b128 v[140:143], v130 offset:2048
	ds_read_b128 v[144:147], v130 offset:3072
	ds_read_b128 v[148:151], v131
	ds_read_b128 v[152:155], v131 offset:1024
	ds_read_b128 v[156:159], v131 offset:2048
	ds_read_b128 v[160:163], v131 offset:3072
	s_add_i32 s24, s20, 0x160100
	s_mov_b32 m0, s43
	ds_read_b128 v[164:167], v203 offset:32768
	ds_read_b128 v[168:171], v203 offset:33792
	ds_read_b128 v[172:175], v203 offset:34816
	ds_read_b128 v[176:179], v203 offset:35840
	ds_read_b128 v[180:183], v203 offset:36864
	ds_read_b128 v[184:187], v203 offset:37888
	ds_read_b128 v[188:191], v203 offset:38912
	ds_read_b128 v[206:209], v203 offset:39936
	buffer_load_dwordx4 v195, s[28:31], s24 offen lds
	s_mov_b32 m0, s44
	s_nop 0
	buffer_load_dwordx4 v200, s[28:31], s24 offen lds
	s_waitcnt vmcnt(8)
	s_waitcnt lgkmcnt(0)
	s_setprio 1
	s_barrier
	v_mfma_f32_16x16x32_bf16 v[126:129], v[132:135], v[164:167], v[126:129]
	v_mfma_f32_16x16x32_bf16 v[122:125], v[140:143], v[164:167], v[122:125]
	v_mfma_f32_16x16x32_bf16 v[110:113], v[132:135], v[172:175], v[110:113]
	v_mfma_f32_16x16x32_bf16 v[106:109], v[140:143], v[172:175], v[106:109]
	v_mfma_f32_16x16x32_bf16 v[94:97], v[132:135], v[180:183], v[94:97]
	v_mfma_f32_16x16x32_bf16 v[90:93], v[140:143], v[180:183], v[90:93]
	v_mfma_f32_16x16x32_bf16 v[78:81], v[132:135], v[188:191], v[78:81]
	v_mfma_f32_16x16x32_bf16 v[74:77], v[140:143], v[188:191], v[74:77]
	v_mfma_f32_16x16x32_bf16 v[126:129], v[136:139], v[168:171], v[126:129]
	v_mfma_f32_16x16x32_bf16 v[122:125], v[144:147], v[168:171], v[122:125]
	v_mfma_f32_16x16x32_bf16 v[110:113], v[136:139], v[176:179], v[110:113]
	v_mfma_f32_16x16x32_bf16 v[106:109], v[144:147], v[176:179], v[106:109]
	v_mfma_f32_16x16x32_bf16 v[94:97], v[136:139], v[184:187], v[94:97]
	v_mfma_f32_16x16x32_bf16 v[90:93], v[144:147], v[184:187], v[90:93]
	v_mfma_f32_16x16x32_bf16 v[78:81], v[136:139], v[206:209], v[78:81]
	v_mfma_f32_16x16x32_bf16 v[74:77], v[144:147], v[206:209], v[74:77]
	v_mfma_f32_16x16x32_bf16 v[118:121], v[148:151], v[164:167], v[118:121]
	v_mfma_f32_16x16x32_bf16 v[114:117], v[156:159], v[164:167], v[114:117]
	v_mfma_f32_16x16x32_bf16 v[102:105], v[148:151], v[172:175], v[102:105]
	v_mfma_f32_16x16x32_bf16 v[98:101], v[156:159], v[172:175], v[98:101]
	v_mfma_f32_16x16x32_bf16 v[86:89], v[148:151], v[180:183], v[86:89]
	v_mfma_f32_16x16x32_bf16 v[82:85], v[156:159], v[180:183], v[82:85]
	v_mfma_f32_16x16x32_bf16 v[70:73], v[148:151], v[188:191], v[70:73]
	v_mfma_f32_16x16x32_bf16 v[66:69], v[156:159], v[188:191], v[66:69]
	v_mfma_f32_16x16x32_bf16 v[118:121], v[152:155], v[168:171], v[118:121]
	v_mfma_f32_16x16x32_bf16 v[114:117], v[160:163], v[168:171], v[114:117]
	v_mfma_f32_16x16x32_bf16 v[102:105], v[152:155], v[176:179], v[102:105]
	v_mfma_f32_16x16x32_bf16 v[98:101], v[160:163], v[176:179], v[98:101]
	v_mfma_f32_16x16x32_bf16 v[86:89], v[152:155], v[184:187], v[86:89]
	v_mfma_f32_16x16x32_bf16 v[82:85], v[160:163], v[184:187], v[82:85]
	v_mfma_f32_16x16x32_bf16 v[70:73], v[152:155], v[206:209], v[70:73]
	v_mfma_f32_16x16x32_bf16 v[66:69], v[160:163], v[206:209], v[66:69]
	s_setprio 0
	s_barrier
	s_mov_b32 m0, s46
	s_add_i32 s24, s18, 0x180
	ds_read_b128 v[164:167], v203 offset:49152
	ds_read_b128 v[168:171], v203 offset:50176
	ds_read_b128 v[172:175], v203 offset:51200
	ds_read_b128 v[176:179], v203 offset:52224
	ds_read_b128 v[180:183], v203 offset:53248
	ds_read_b128 v[184:187], v203 offset:54272
	ds_read_b128 v[188:191], v203 offset:55296
	ds_read_b128 v[206:209], v203 offset:56320
	buffer_load_dwordx4 v195, s[12:15], s24 offen lds
	s_mov_b32 m0, s47
	s_nop 0
	buffer_load_dwordx4 v200, s[12:15], s24 offen lds
	s_add_i32 s24, s18, 0x160180
	s_mov_b32 m0, s50
	s_nop 0
	buffer_load_dwordx4 v195, s[12:15], s24 offen lds
	s_mov_b32 m0, s51
	s_nop 0
	buffer_load_dwordx4 v200, s[12:15], s24 offen lds
	s_add_i32 s24, s20, 0x180
	s_mov_b32 m0, s48
	s_nop 0
	buffer_load_dwordx4 v195, s[28:31], s24 offen lds
	s_mov_b32 m0, s49
	s_nop 0
	buffer_load_dwordx4 v200, s[28:31], s24 offen lds
	s_waitcnt vmcnt(8)
	s_waitcnt lgkmcnt(0)
	s_setprio 1
	s_barrier
	v_mfma_f32_16x16x32_bf16 v[62:65], v[132:135], v[164:167], v[62:65]
	v_mfma_f32_16x16x32_bf16 v[58:61], v[140:143], v[164:167], v[58:61]
	v_mfma_f32_16x16x32_bf16 v[46:49], v[132:135], v[172:175], v[46:49]
	v_mfma_f32_16x16x32_bf16 v[42:45], v[140:143], v[172:175], v[42:45]
	v_mfma_f32_16x16x32_bf16 v[30:33], v[132:135], v[180:183], v[30:33]
	v_mfma_f32_16x16x32_bf16 v[26:29], v[140:143], v[180:183], v[26:29]
	v_mfma_f32_16x16x32_bf16 v[14:17], v[132:135], v[188:191], v[14:17]
	v_mfma_f32_16x16x32_bf16 v[10:13], v[140:143], v[188:191], v[10:13]
	v_mfma_f32_16x16x32_bf16 v[62:65], v[136:139], v[168:171], v[62:65]
	v_mfma_f32_16x16x32_bf16 v[58:61], v[144:147], v[168:171], v[58:61]
	v_mfma_f32_16x16x32_bf16 v[46:49], v[136:139], v[176:179], v[46:49]
	v_mfma_f32_16x16x32_bf16 v[42:45], v[144:147], v[176:179], v[42:45]
	v_mfma_f32_16x16x32_bf16 v[30:33], v[136:139], v[184:187], v[30:33]
	v_mfma_f32_16x16x32_bf16 v[26:29], v[144:147], v[184:187], v[26:29]
	v_mfma_f32_16x16x32_bf16 v[14:17], v[136:139], v[206:209], v[14:17]
	v_mfma_f32_16x16x32_bf16 v[10:13], v[144:147], v[206:209], v[10:13]
	v_mfma_f32_16x16x32_bf16 v[54:57], v[148:151], v[164:167], v[54:57]
	v_mfma_f32_16x16x32_bf16 v[50:53], v[156:159], v[164:167], v[50:53]
	v_mfma_f32_16x16x32_bf16 v[38:41], v[148:151], v[172:175], v[38:41]
	v_mfma_f32_16x16x32_bf16 v[34:37], v[156:159], v[172:175], v[34:37]
	v_mfma_f32_16x16x32_bf16 v[22:25], v[148:151], v[180:183], v[22:25]
	v_mfma_f32_16x16x32_bf16 v[18:21], v[156:159], v[180:183], v[18:21]
	v_mfma_f32_16x16x32_bf16 v[6:9], v[148:151], v[188:191], v[6:9]
	v_mfma_f32_16x16x32_bf16 v[2:5], v[156:159], v[188:191], v[2:5]
	v_mfma_f32_16x16x32_bf16 v[54:57], v[152:155], v[168:171], v[54:57]
	v_mfma_f32_16x16x32_bf16 v[50:53], v[160:163], v[168:171], v[50:53]
	v_mfma_f32_16x16x32_bf16 v[38:41], v[152:155], v[176:179], v[38:41]
	v_mfma_f32_16x16x32_bf16 v[34:37], v[160:163], v[176:179], v[34:37]
	v_mfma_f32_16x16x32_bf16 v[22:25], v[152:155], v[184:187], v[22:25]
	v_mfma_f32_16x16x32_bf16 v[18:21], v[160:163], v[184:187], v[18:21]
	v_mfma_f32_16x16x32_bf16 v[6:9], v[152:155], v[206:209], v[6:9]
	v_mfma_f32_16x16x32_bf16 v[2:5], v[160:163], v[206:209], v[2:5]
	s_setprio 0
	s_barrier
	s_mov_b32 s61, 0
	s_mov_b64 s[24:25], 0x160180
; #define PG8_STAGEA(bufoff, goff, voff) PG8_STAGEX(rsA, bufoff, goff, voff)
; #define PG8_STAGEB(bufoff, goff, voff) PG8_STAGEX(rsB, bufoff, goff, voff)
; #define PG8_LDA(dst, b, h) do { _Pragma("unroll") for (int m = 0; m < 4; ++m) _Pragma("unroll") for (int k = 0; k < 2; ++k) dst[m][k] = *(const PG8_LAS bf16x8*)(lds + PG8_SA(b, h) + aoff + m * 2048 + k * 1024); } while (0)
; #define PG8_LDB(dst, b, h) do { _Pragma("unroll") for (int n = 0; n < 2; ++n) _Pragma("unroll") for (int k = 0; k < 2; ++k) dst[n][k] = *(const PG8_LAS bf16x8*)(lds + PG8_SB(b, h) + boff + n * 2048 + k * 1024); } while (0)
; #define PG8_MMA(ai, bj, At, Bt) do { __builtin_amdgcn_s_setprio(1); _Pragma("unroll") for (int m = 0; m < 4; ++m) _Pragma("unroll") for (int n = 0; n < 2; ++n) _Pragma("unroll") for (int k = 0; k < 2; ++k) \
;         acc[ai][bj][m][n] = __builtin_amdgcn_mfma_f32_16x16x32_bf16(Bt[n][k], At[m][k], acc[ai][bj][m][n], 0, 0, 0); __builtin_amdgcn_s_setprio(0); } while (0)
; #define PG8_WAIT_V(n) asm volatile("s_waitcnt vmcnt(" #n ")" ::: "memory")
; #define PG8_WAIT_L(n) asm volatile("s_waitcnt lgkmcnt(" #n ")" ::: "memory")
; #define PG8_BAR __builtin_amdgcn_s_barrier()
; #define PG8_SCHED __builtin_amdgcn_sched_barrier(0)
; template <class Epi, class Sched, bool ALIGN_EPI = false, bool SP2 = false>
; __device__ __forceinline__ void gemm_phase(PG8_LAS unsigned char* lds, const Gemm g, const Sched& S, const Epi& E) {
;     ...
;             PG8_LDB(B0, 0, 0); PG8_LDB(B1, 0, 1); PG8_SCHED; PG8_LDA(At, 0, 0); PG8_STAGEA(PG8_SA(1, 1), a1 + hstep, voffA);
;             if (t == 0 && ui > 0) {
; #pragma unroll
;                 for (int a = 0; a < 2; ++a)
; #pragma unroll
;                     for (int b = 0; b < 2; ++b)
; #pragma unroll
;                         for (int m = 0; m < 4; ++m)
; #pragma unroll
;                             for (int n = 0; n < 2; ++n) acc[a][b][m][n] = (f32x4){0.f, 0.f, 0.f, 0.f}; }
;             PG8_WAIT_V(8); PG8_WAIT_L(0); PG8_BAR; PG8_MMA(0, 0, At, B0); PG8_MMA(0, 1, At, B1); PG8_BAR; PG8_SCHED;
;             PG8_LDA(At, 0, 1); PG8_STAGEB(PG8_SB(0, 0), b2, voffB); PG8_STAGEB(PG8_SB(0, 1), b2 + hstep, voffB); PG8_STAGEA(PG8_SA(0, 0), a2, voffA);
;             PG8_WAIT_V(8); PG8_WAIT_L(0); PG8_BAR; PG8_MMA(1, 0, At, B0); PG8_MMA(1, 1, At, B1); PG8_BAR; PG8_SCHED;
.LBB0_893:
	ds_read_b128 v[132:135], v204
	ds_read_b128 v[136:139], v204 offset:1024
	ds_read_b128 v[140:143], v204 offset:2048
	ds_read_b128 v[144:147], v204 offset:3072
	ds_read_b128 v[148:151], v205
	ds_read_b128 v[152:155], v205 offset:1024
	ds_read_b128 v[156:159], v205 offset:2048
	ds_read_b128 v[160:163], v205 offset:3072
	s_mov_b32 m0, s56
	s_add_i32 s62, s20, s24
	ds_read_b128 v[164:167], v203
	ds_read_b128 v[168:171], v203 offset:1024
	ds_read_b128 v[172:175], v203 offset:2048
	ds_read_b128 v[176:179], v203 offset:3072
	ds_read_b128 v[180:183], v203 offset:4096
	ds_read_b128 v[184:187], v203 offset:5120
	ds_read_b128 v[188:191], v203 offset:6144
	ds_read_b128 v[206:209], v203 offset:7168
	buffer_load_dwordx4 v195, s[28:31], s62 offen lds
	s_mov_b32 m0, s57
	s_add_i32 s63, s18, s24
	buffer_load_dwordx4 v200, s[28:31], s62 offen lds
	s_waitcnt vmcnt(8)
	s_waitcnt lgkmcnt(0)
	s_add_i32 s63, s63, 0xffea0080
	s_add_i32 s62, s62, 0xffea0080
	s_cmpk_eq_i32 s61, 0x54
	s_setprio 1
	s_barrier
	v_mfma_f32_16x16x32_bf16 v[126:129], v[132:135], v[164:167], v[126:129]
	v_mfma_f32_16x16x32_bf16 v[122:125], v[140:143], v[164:167], v[122:125]
	v_mfma_f32_16x16x32_bf16 v[110:113], v[132:135], v[172:175], v[110:113]
	v_mfma_f32_16x16x32_bf16 v[106:109], v[140:143], v[172:175], v[106:109]
	v_mfma_f32_16x16x32_bf16 v[94:97], v[132:135], v[180:183], v[94:97]
	v_mfma_f32_16x16x32_bf16 v[90:93], v[140:143], v[180:183], v[90:93]
	v_mfma_f32_16x16x32_bf16 v[78:81], v[132:135], v[188:191], v[78:81]
	v_mfma_f32_16x16x32_bf16 v[74:77], v[140:143], v[188:191], v[74:77]
	v_mfma_f32_16x16x32_bf16 v[126:129], v[136:139], v[168:171], v[126:129]
	v_mfma_f32_16x16x32_bf16 v[122:125], v[144:147], v[168:171], v[122:125]
	v_mfma_f32_16x16x32_bf16 v[110:113], v[136:139], v[176:179], v[110:113]
	v_mfma_f32_16x16x32_bf16 v[106:109], v[144:147], v[176:179], v[106:109]
	v_mfma_f32_16x16x32_bf16 v[94:97], v[136:139], v[184:187], v[94:97]
	v_mfma_f32_16x16x32_bf16 v[90:93], v[144:147], v[184:187], v[90:93]
	v_mfma_f32_16x16x32_bf16 v[78:81], v[136:139], v[206:209], v[78:81]
	v_mfma_f32_16x16x32_bf16 v[74:77], v[144:147], v[206:209], v[74:77]
	v_mfma_f32_16x16x32_bf16 v[118:121], v[148:151], v[164:167], v[118:121]
	v_mfma_f32_16x16x32_bf16 v[114:117], v[156:159], v[164:167], v[114:117]
	v_mfma_f32_16x16x32_bf16 v[102:105], v[148:151], v[172:175], v[102:105]
	v_mfma_f32_16x16x32_bf16 v[98:101], v[156:159], v[172:175], v[98:101]
	v_mfma_f32_16x16x32_bf16 v[86:89], v[148:151], v[180:183], v[86:89]
	v_mfma_f32_16x16x32_bf16 v[82:85], v[156:159], v[180:183], v[82:85]
	v_mfma_f32_16x16x32_bf16 v[70:73], v[148:151], v[188:191], v[70:73]
	v_mfma_f32_16x16x32_bf16 v[66:69], v[156:159], v[188:191], v[66:69]
	v_mfma_f32_16x16x32_bf16 v[118:121], v[152:155], v[168:171], v[118:121]
	v_mfma_f32_16x16x32_bf16 v[114:117], v[160:163], v[168:171], v[114:117]
	v_mfma_f32_16x16x32_bf16 v[102:105], v[152:155], v[176:179], v[102:105]
	v_mfma_f32_16x16x32_bf16 v[98:101], v[160:163], v[176:179], v[98:101]
	v_mfma_f32_16x16x32_bf16 v[86:89], v[152:155], v[184:187], v[86:89]
	v_mfma_f32_16x16x32_bf16 v[82:85], v[160:163], v[184:187], v[82:85]
	v_mfma_f32_16x16x32_bf16 v[70:73], v[152:155], v[206:209], v[70:73]
	v_mfma_f32_16x16x32_bf16 v[66:69], v[160:163], v[206:209], v[66:69]
	s_setprio 0
	s_barrier
	s_mov_b32 m0, s38
	s_cselect_b32 s63, s4, s63
	ds_read_b128 v[164:167], v203 offset:16384
	ds_read_b128 v[168:171], v203 offset:17408
	ds_read_b128 v[172:175], v203 offset:18432
	ds_read_b128 v[176:179], v203 offset:19456
	ds_read_b128 v[180:183], v203 offset:20480
	ds_read_b128 v[184:187], v203 offset:21504
	ds_read_b128 v[188:191], v203 offset:22528
	ds_read_b128 v[206:209], v203 offset:23552
	buffer_load_dwordx4 v195, s[12:15], s63 offen lds
	s_mov_b32 m0, s39
	s_cselect_b32 s62, s22, s62
	buffer_load_dwordx4 v200, s[12:15], s63 offen lds
	s_add_i32 s64, s63, 0x160000
	s_mov_b32 m0, s40
	s_nop 0
	buffer_load_dwordx4 v195, s[12:15], s64 offen lds
	s_mov_b32 m0, s41
	s_nop 0
	buffer_load_dwordx4 v200, s[12:15], s64 offen lds
	s_mov_b32 m0, s37
	s_nop 0
	buffer_load_dwordx4 v195, s[28:31], s62 offen lds
	s_mov_b32 m0, s42
	s_nop 0
	buffer_load_dwordx4 v200, s[28:31], s62 offen lds
	s_waitcnt vmcnt(8)
	s_waitcnt lgkmcnt(0)
	s_setprio 1
	s_barrier
	v_mfma_f32_16x16x32_bf16 v[62:65], v[132:135], v[164:167], v[62:65]
	v_mfma_f32_16x16x32_bf16 v[58:61], v[140:143], v[164:167], v[58:61]
	v_mfma_f32_16x16x32_bf16 v[46:49], v[132:135], v[172:175], v[46:49]
	v_mfma_f32_16x16x32_bf16 v[42:45], v[140:143], v[172:175], v[42:45]
	v_mfma_f32_16x16x32_bf16 v[30:33], v[132:135], v[180:183], v[30:33]
	v_mfma_f32_16x16x32_bf16 v[26:29], v[140:143], v[180:183], v[26:29]
	v_mfma_f32_16x16x32_bf16 v[14:17], v[132:135], v[188:191], v[14:17]
	v_mfma_f32_16x16x32_bf16 v[10:13], v[140:143], v[188:191], v[10:13]
	v_mfma_f32_16x16x32_bf16 v[62:65], v[136:139], v[168:171], v[62:65]
	v_mfma_f32_16x16x32_bf16 v[58:61], v[144:147], v[168:171], v[58:61]
	v_mfma_f32_16x16x32_bf16 v[46:49], v[136:139], v[176:179], v[46:49]
	v_mfma_f32_16x16x32_bf16 v[42:45], v[144:147], v[176:179], v[42:45]
	v_mfma_f32_16x16x32_bf16 v[30:33], v[136:139], v[184:187], v[30:33]
	v_mfma_f32_16x16x32_bf16 v[26:29], v[144:147], v[184:187], v[26:29]
	v_mfma_f32_16x16x32_bf16 v[14:17], v[136:139], v[206:209], v[14:17]
	v_mfma_f32_16x16x32_bf16 v[10:13], v[144:147], v[206:209], v[10:13]
	v_mfma_f32_16x16x32_bf16 v[54:57], v[148:151], v[164:167], v[54:57]
	v_mfma_f32_16x16x32_bf16 v[50:53], v[156:159], v[164:167], v[50:53]
	v_mfma_f32_16x16x32_bf16 v[38:41], v[148:151], v[172:175], v[38:41]
	v_mfma_f32_16x16x32_bf16 v[34:37], v[156:159], v[172:175], v[34:37]
	v_mfma_f32_16x16x32_bf16 v[22:25], v[148:151], v[180:183], v[22:25]
	v_mfma_f32_16x16x32_bf16 v[18:21], v[156:159], v[180:183], v[18:21]
	v_mfma_f32_16x16x32_bf16 v[6:9], v[148:151], v[188:191], v[6:9]
	v_mfma_f32_16x16x32_bf16 v[2:5], v[156:159], v[188:191], v[2:5]
	v_mfma_f32_16x16x32_bf16 v[54:57], v[152:155], v[168:171], v[54:57]
	v_mfma_f32_16x16x32_bf16 v[50:53], v[160:163], v[168:171], v[50:53]
	v_mfma_f32_16x16x32_bf16 v[38:41], v[152:155], v[176:179], v[38:41]
	v_mfma_f32_16x16x32_bf16 v[34:37], v[160:163], v[176:179], v[34:37]
	v_mfma_f32_16x16x32_bf16 v[22:25], v[152:155], v[184:187], v[22:25]
	v_mfma_f32_16x16x32_bf16 v[18:21], v[160:163], v[184:187], v[18:21]
	v_mfma_f32_16x16x32_bf16 v[6:9], v[152:155], v[206:209], v[6:9]
	v_mfma_f32_16x16x32_bf16 v[2:5], v[160:163], v[206:209], v[2:5]
	s_setprio 0
	s_barrier
; #define PG8_STAGEA(bufoff, goff, voff) PG8_STAGEX(rsA, bufoff, goff, voff)
; #define PG8_STAGEB(bufoff, goff, voff) PG8_STAGEX(rsB, bufoff, goff, voff)
; #define PG8_LDA(dst, b, h) do { _Pragma("unroll") for (int m = 0; m < 4; ++m) _Pragma("unroll") for (int k = 0; k < 2; ++k) dst[m][k] = *(const PG8_LAS bf16x8*)(lds + PG8_SA(b, h) + aoff + m * 2048 + k * 1024); } while (0)
; #define PG8_LDB(dst, b, h) do { _Pragma("unroll") for (int n = 0; n < 2; ++n) _Pragma("unroll") for (int k = 0; k < 2; ++k) dst[n][k] = *(const PG8_LAS bf16x8*)(lds + PG8_SB(b, h) + boff + n * 2048 + k * 1024); } while (0)
; #define PG8_MMA(ai, bj, At, Bt) do { __builtin_amdgcn_s_setprio(1); _Pragma("unroll") for (int m = 0; m < 4; ++m) _Pragma("unroll") for (int n = 0; n < 2; ++n) _Pragma("unroll") for (int k = 0; k < 2; ++k) \
;         acc[ai][bj][m][n] = __builtin_amdgcn_mfma_f32_16x16x32_bf16(Bt[n][k], At[m][k], acc[ai][bj][m][n], 0, 0, 0); __builtin_amdgcn_s_setprio(0); } while (0)
; #define PG8_WAIT_V(n) asm volatile("s_waitcnt vmcnt(" #n ")" ::: "memory")
; #define PG8_WAIT_L(n) asm volatile("s_waitcnt lgkmcnt(" #n ")" ::: "memory")
; #define PG8_BAR __builtin_amdgcn_s_barrier()
; #define PG8_SCHED __builtin_amdgcn_sched_barrier(0)
; template <class Epi, class Sched, bool ALIGN_EPI = false, bool SP2 = false>
; __device__ __forceinline__ void gemm_phase(PG8_LAS unsigned char* lds, const Gemm g, const Sched& S, const Epi& E) {
;     ...
;             PG8_LDB(B0, 1, 0); PG8_LDB(B1, 1, 1); PG8_SCHED; PG8_LDA(At, 1, 0); PG8_STAGEA(PG8_SA(0, 1), a2 + hstep, voffA);
;             PG8_WAIT_V(8); PG8_WAIT_L(0); PG8_BAR; PG8_MMA(0, 0, At, B0); PG8_MMA(0, 1, At, B1); PG8_BAR; PG8_SCHED;
;             PG8_LDA(At, 1, 1); PG8_STAGEB(PG8_SB(1, 0), b3, voffB); PG8_STAGEB(PG8_SB(1, 1), b3 + hstep, voffB); PG8_STAGEA(PG8_SA(1, 0), a3, voffA);
;             PG8_WAIT_V(8); PG8_WAIT_L(0); PG8_BAR; PG8_MMA(1, 0, At, B0); PG8_MMA(1, 1, At, B1); PG8_BAR; PG8_SCHED;
;     ...
;         if (!has_next) break;
;         cur = nxt; cA = nA; cB = nB; ++ui;
	ds_read_b128 v[132:135], v130
	ds_read_b128 v[136:139], v130 offset:1024
	ds_read_b128 v[140:143], v130 offset:2048
	ds_read_b128 v[144:147], v130 offset:3072
	ds_read_b128 v[148:151], v131
	ds_read_b128 v[152:155], v131 offset:1024
	ds_read_b128 v[156:159], v131 offset:2048
	ds_read_b128 v[160:163], v131 offset:3072
	s_add_i32 s64, s62, 0x160000
	s_mov_b32 m0, s43
	ds_read_b128 v[164:167], v203 offset:32768
	ds_read_b128 v[168:171], v203 offset:33792
	ds_read_b128 v[172:175], v203 offset:34816
	ds_read_b128 v[176:179], v203 offset:35840
	ds_read_b128 v[180:183], v203 offset:36864
	ds_read_b128 v[184:187], v203 offset:37888
	ds_read_b128 v[188:191], v203 offset:38912
	ds_read_b128 v[206:209], v203 offset:39936
	buffer_load_dwordx4 v195, s[28:31], s64 offen lds
	s_mov_b32 m0, s44
	s_nop 0
	buffer_load_dwordx4 v200, s[28:31], s64 offen lds
	s_waitcnt vmcnt(8)
	s_waitcnt lgkmcnt(0)
	s_setprio 1
	s_barrier
	v_mfma_f32_16x16x32_bf16 v[126:129], v[132:135], v[164:167], v[126:129]
	v_mfma_f32_16x16x32_bf16 v[122:125], v[140:143], v[164:167], v[122:125]
	v_mfma_f32_16x16x32_bf16 v[110:113], v[132:135], v[172:175], v[110:113]
	v_mfma_f32_16x16x32_bf16 v[106:109], v[140:143], v[172:175], v[106:109]
	v_mfma_f32_16x16x32_bf16 v[94:97], v[132:135], v[180:183], v[94:97]
	v_mfma_f32_16x16x32_bf16 v[90:93], v[140:143], v[180:183], v[90:93]
	v_mfma_f32_16x16x32_bf16 v[78:81], v[132:135], v[188:191], v[78:81]
	v_mfma_f32_16x16x32_bf16 v[74:77], v[140:143], v[188:191], v[74:77]
	v_mfma_f32_16x16x32_bf16 v[126:129], v[136:139], v[168:171], v[126:129]
	v_mfma_f32_16x16x32_bf16 v[122:125], v[144:147], v[168:171], v[122:125]
	v_mfma_f32_16x16x32_bf16 v[110:113], v[136:139], v[176:179], v[110:113]
	v_mfma_f32_16x16x32_bf16 v[106:109], v[144:147], v[176:179], v[106:109]
	v_mfma_f32_16x16x32_bf16 v[94:97], v[136:139], v[184:187], v[94:97]
	v_mfma_f32_16x16x32_bf16 v[90:93], v[144:147], v[184:187], v[90:93]
	v_mfma_f32_16x16x32_bf16 v[78:81], v[136:139], v[206:209], v[78:81]
	v_mfma_f32_16x16x32_bf16 v[74:77], v[144:147], v[206:209], v[74:77]
	v_mfma_f32_16x16x32_bf16 v[118:121], v[148:151], v[164:167], v[118:121]
	v_mfma_f32_16x16x32_bf16 v[114:117], v[156:159], v[164:167], v[114:117]
	v_mfma_f32_16x16x32_bf16 v[102:105], v[148:151], v[172:175], v[102:105]
	v_mfma_f32_16x16x32_bf16 v[98:101], v[156:159], v[172:175], v[98:101]
	v_mfma_f32_16x16x32_bf16 v[86:89], v[148:151], v[180:183], v[86:89]
	v_mfma_f32_16x16x32_bf16 v[82:85], v[156:159], v[180:183], v[82:85]
	v_mfma_f32_16x16x32_bf16 v[70:73], v[148:151], v[188:191], v[70:73]
	v_mfma_f32_16x16x32_bf16 v[66:69], v[156:159], v[188:191], v[66:69]
	v_mfma_f32_16x16x32_bf16 v[118:121], v[152:155], v[168:171], v[118:121]
	v_mfma_f32_16x16x32_bf16 v[114:117], v[160:163], v[168:171], v[114:117]
	v_mfma_f32_16x16x32_bf16 v[102:105], v[152:155], v[176:179], v[102:105]
	v_mfma_f32_16x16x32_bf16 v[98:101], v[160:163], v[176:179], v[98:101]
	v_mfma_f32_16x16x32_bf16 v[86:89], v[152:155], v[184:187], v[86:89]
	v_mfma_f32_16x16x32_bf16 v[82:85], v[160:163], v[184:187], v[82:85]
	v_mfma_f32_16x16x32_bf16 v[70:73], v[152:155], v[206:209], v[70:73]
	v_mfma_f32_16x16x32_bf16 v[66:69], v[160:163], v[206:209], v[66:69]
	s_setprio 0
	s_barrier
	s_mov_b32 m0, s46
	s_add_i32 s64, s63, 0x80
	ds_read_b128 v[164:167], v203 offset:49152
	ds_read_b128 v[168:171], v203 offset:50176
	ds_read_b128 v[172:175], v203 offset:51200
	ds_read_b128 v[176:179], v203 offset:52224
	ds_read_b128 v[180:183], v203 offset:53248
	ds_read_b128 v[184:187], v203 offset:54272
	ds_read_b128 v[188:191], v203 offset:55296
	ds_read_b128 v[206:209], v203 offset:56320
	buffer_load_dwordx4 v195, s[12:15], s64 offen lds
	s_mov_b32 m0, s47
	s_add_i32 s63, s63, 0x160080
	buffer_load_dwordx4 v200, s[12:15], s64 offen lds
	s_mov_b32 m0, s50
	s_addk_i32 s62, 0x80
	buffer_load_dwordx4 v195, s[12:15], s63 offen lds
	s_mov_b32 m0, s51
	s_nop 0
	buffer_load_dwordx4 v200, s[12:15], s63 offen lds
	s_mov_b32 m0, s48
	s_nop 0
	buffer_load_dwordx4 v195, s[28:31], s62 offen lds
	s_mov_b32 m0, s49
	s_nop 0
	buffer_load_dwordx4 v200, s[28:31], s62 offen lds
	s_waitcnt vmcnt(8)
	s_waitcnt lgkmcnt(0)
	s_setprio 1
	s_barrier
	v_mfma_f32_16x16x32_bf16 v[62:65], v[132:135], v[164:167], v[62:65]
	v_mfma_f32_16x16x32_bf16 v[58:61], v[140:143], v[164:167], v[58:61]
	v_mfma_f32_16x16x32_bf16 v[46:49], v[132:135], v[172:175], v[46:49]
	v_mfma_f32_16x16x32_bf16 v[42:45], v[140:143], v[172:175], v[42:45]
	v_mfma_f32_16x16x32_bf16 v[30:33], v[132:135], v[180:183], v[30:33]
	v_mfma_f32_16x16x32_bf16 v[26:29], v[140:143], v[180:183], v[26:29]
	v_mfma_f32_16x16x32_bf16 v[14:17], v[132:135], v[188:191], v[14:17]
	v_mfma_f32_16x16x32_bf16 v[10:13], v[140:143], v[188:191], v[10:13]
	v_mfma_f32_16x16x32_bf16 v[62:65], v[136:139], v[168:171], v[62:65]
	v_mfma_f32_16x16x32_bf16 v[58:61], v[144:147], v[168:171], v[58:61]
	v_mfma_f32_16x16x32_bf16 v[46:49], v[136:139], v[176:179], v[46:49]
	v_mfma_f32_16x16x32_bf16 v[42:45], v[144:147], v[176:179], v[42:45]
	v_mfma_f32_16x16x32_bf16 v[30:33], v[136:139], v[184:187], v[30:33]
	v_mfma_f32_16x16x32_bf16 v[26:29], v[144:147], v[184:187], v[26:29]
	v_mfma_f32_16x16x32_bf16 v[14:17], v[136:139], v[206:209], v[14:17]
	v_mfma_f32_16x16x32_bf16 v[10:13], v[144:147], v[206:209], v[10:13]
	v_mfma_f32_16x16x32_bf16 v[54:57], v[148:151], v[164:167], v[54:57]
	v_mfma_f32_16x16x32_bf16 v[50:53], v[156:159], v[164:167], v[50:53]
	v_mfma_f32_16x16x32_bf16 v[38:41], v[148:151], v[172:175], v[38:41]
	v_mfma_f32_16x16x32_bf16 v[34:37], v[156:159], v[172:175], v[34:37]
	v_mfma_f32_16x16x32_bf16 v[22:25], v[148:151], v[180:183], v[22:25]
	v_mfma_f32_16x16x32_bf16 v[18:21], v[156:159], v[180:183], v[18:21]
	v_mfma_f32_16x16x32_bf16 v[6:9], v[148:151], v[188:191], v[6:9]
	v_mfma_f32_16x16x32_bf16 v[2:5], v[156:159], v[188:191], v[2:5]
	v_mfma_f32_16x16x32_bf16 v[54:57], v[152:155], v[168:171], v[54:57]
	v_mfma_f32_16x16x32_bf16 v[50:53], v[160:163], v[168:171], v[50:53]
	v_mfma_f32_16x16x32_bf16 v[38:41], v[152:155], v[176:179], v[38:41]
	v_mfma_f32_16x16x32_bf16 v[34:37], v[160:163], v[176:179], v[34:37]
	v_mfma_f32_16x16x32_bf16 v[22:25], v[152:155], v[184:187], v[22:25]
	v_mfma_f32_16x16x32_bf16 v[18:21], v[160:163], v[184:187], v[18:21]
	v_mfma_f32_16x16x32_bf16 v[6:9], v[152:155], v[206:209], v[6:9]
	v_mfma_f32_16x16x32_bf16 v[2:5], v[160:163], v[206:209], v[2:5]
	s_setprio 0
	s_barrier
	s_add_i32 s61, s61, 2
	s_add_u32 s24, s24, 0x100
	s_addc_u32 s25, s25, 0
	s_cmpk_gt_u32 s61, 0x55
	s_cbranch_scc0 .LBB0_893
	s_and_b64 vcc, exec, s[2:3]
	s_cbranch_vccz .LBB0_879
	s_mov_b32 s16, s58
	s_mov_b32 s36, s59
	s_mov_b64 s[18:19], s[4:5]
	s_mov_b64 s[20:21], s[22:23]
	s_mov_b32 s45, s60
	s_branch .LBB0_879
